# removed store-drain waits at GEMM tile-loop headers and mid-prologue wait in input projection
# baseline (speedup 1.0000x reference)
; #define MFMA(a, b, c) __builtin_amdgcn_mfma_f32_32x32x16_bf16((a), (b), (c), 0, 0, 0)
; #define TIDX opaque_tid()
; template <int AI, int BI>
; DI void gemm_tile(const u16* __restrict__ A, int lda, const u16* __restrict__ B, int ldb, int nk, bool swap,
;                   f32x16 (&acc)[AI][BI], char* lds) {
;   const int tid = TIDX, lane = tid & 63, wid = tid >> 6;
;   gemm_stage<AI, BI>(A, lda, B, ldb, lds, tid);
;   asm volatile("s_waitcnt vmcnt(0)" ::: "memory");
;   __syncthreads();
;   const int wa = wid >> 1, wb = wid & 1, r = lane & 31, h = lane >> 5, sw = (r >> 1) & 7;
;   const int offA = (swap ? 16384 : 0) + (wa * 32 * AI + r) * 128;
;   const int offB = (swap ? 0 : 16384) + (wb * 32 * BI + r) * 128;
;   for (int kt = 0; kt < nk; ++kt) {
;     const char* cur = lds + (kt & 1) * 32768;
;     if (kt + 1 < nk) gemm_stage<AI, BI>(A + (kt + 1) * 64, lda, B + (kt + 1) * 64, ldb, lds + ((kt + 1) & 1) * 32768, tid);
; #pragma unroll
;     for (int ks = 0; ks < 4; ++ks) {
;       const int co = ((ks * 2 + h) ^ sw) << 4;
;       s16x8 fa[AI], fb[BI];
; #pragma unroll
;       for (int i = 0; i < AI; ++i) fa[i] = *(const s16x8*)(cur + offA + i * 4096 + co);
; #pragma unroll
;       for (int i = 0; i < BI; ++i) fb[i] = *(const s16x8*)(cur + offB + i * 4096 + co);
; #pragma unroll
;       for (int i = 0; i < AI; ++i)
; #pragma unroll
;         for (int j = 0; j < BI; ++j) acc[i][j] = MFMA(fa[i], fb[j], acc[i][j]);
; DI bool next_tile(int rnd, int MT, int NT, int& mt, int& nt) {
;   const int G8 = gridDim.x >> 3, x = blockIdx.x & 7, slot = blockIdx.x >> 3;
;   const int T = (rnd * 8 + x) * G8 + slot;
;   if (T >= MT * NT) return false;
;   const int band = T / (NT * 8), rem = T - band * NT * 8;
;   nt = rem >> 3; mt = band * 8 + (rem & 7);
;   return true;
.LBB0_419:
	s_and_b32 s16, s14, 0xffff
	s_mul_hi_u32 s17, s16, 0xba2e8c
	s_mul_i32 s16, s16, 0xba2f
	s_mulk_i32 s17, 0x160
	s_lshr_b32 s16, s16, 24
	s_sub_i32 s17, s14, s17
	s_lshl_b32 s16, s16, 10
	s_and_b32 s18, s15, 0x380
	s_ashr_i32 s17, s17, 3
	s_or_b32 s16, s16, s18
	s_lshl_b32 s28, s17, 7
	v_mov_b32_e32 v82, v178
	v_mov_b32_e32 v83, v178
	s_lshl_b32 s18, s16, 11
	v_mov_b32_e32 v12, v178
	s_add_u32 s34, s10, s18
	s_addc_u32 s35, s11, 0
	v_lshrrev_b32_e32 v0, 4, v12
	s_ashr_i32 s29, s28, 31
	v_xor_b32_e32 v0, v0, v12
	v_add_u32_e32 v8, 0x100, v12
	v_add_u32_e32 v10, 0x200, v12
	v_add_u32_e32 v13, 0x300, v12
	s_lshl_b64 s[28:29], s[28:29], 11
	v_lshlrev_b32_e32 v0, 4, v0
	v_ashrrev_i32_e32 v4, 3, v12
	v_ashrrev_i32_e32 v6, 3, v8
	v_lshlrev_b32_e32 v99, 4, v8
	v_ashrrev_i32_e32 v8, 3, v10
	v_lshlrev_b32_e32 v100, 4, v10
	v_ashrrev_i32_e32 v10, 3, v13
	s_add_u32 s28, s12, s28
	v_and_b32_e32 v0, 0x70, v0
	v_ashrrev_i32_e32 v5, 31, v4
	v_ashrrev_i32_e32 v7, 31, v6
	v_ashrrev_i32_e32 v9, 31, v8
	v_ashrrev_i32_e32 v11, 31, v10
	s_addc_u32 s29, s13, s29
	v_lshl_add_u64 v[2:3], s[34:35], 0, v[0:1]
	v_lshlrev_b64 v[4:5], 11, v[4:5]
	v_lshlrev_b32_e32 v95, 4, v12
	v_lshlrev_b64 v[6:7], 11, v[6:7]
	v_lshlrev_b64 v[8:9], 11, v[8:9]
	v_lshlrev_b64 v[10:11], 11, v[10:11]
	v_lshl_add_u64 v[66:67], v[2:3], 0, v[4:5]
	v_lshl_add_u64 v[68:69], v[2:3], 0, v[6:7]
	v_lshl_add_u64 v[70:71], v[2:3], 0, v[8:9]
	v_lshl_add_u64 v[72:73], v[2:3], 0, v[10:11]
	v_lshl_add_u64 v[2:3], s[28:29], 0, v[0:1]
	v_add_u32_e32 v0, 0x4000, v95
	v_readfirstlane_b32 s37, v95
	v_readfirstlane_b32 s28, v0
	v_add_u32_e32 v0, 0x4000, v99
	s_mov_b32 m0, s37
	v_readfirstlane_b32 s48, v99
	v_lshlrev_b32_e32 v101, 4, v13
	v_readfirstlane_b32 s29, v0
	v_add_u32_e32 v0, 0x4000, v100
	global_load_lds_dwordx4 v[66:67], off
	s_mov_b32 m0, s48
	v_readfirstlane_b32 s51, v100
	v_readfirstlane_b32 s34, v0
	v_add_u32_e32 v0, 0x4000, v101
	global_load_lds_dwordx4 v[68:69], off
	s_mov_b32 m0, s51
	v_readfirstlane_b32 s52, v101
	v_lshl_add_u64 v[74:75], v[2:3], 0, v[4:5]
	v_readfirstlane_b32 s35, v0
	v_and_b32_e32 v0, 31, v12
	v_lshrrev_b32_e32 v4, 1, v12
	global_load_lds_dwordx4 v[70:71], off
	s_mov_b32 m0, s52
	v_and_or_b32 v0, v4, s54, v0
	global_load_lds_dwordx4 v[72:73], off
	s_mov_b32 m0, s28
	v_lshl_add_u64 v[76:77], v[2:3], 0, v[6:7]
	v_lshl_add_u64 v[78:79], v[2:3], 0, v[8:9]
	v_lshl_add_u64 v[80:81], v[2:3], 0, v[10:11]
	v_lshrrev_b32_e32 v2, 5, v12
	v_bfe_u32 v5, v12, 1, 3
	v_lshlrev_b32_e32 v85, 7, v0
	v_lshlrev_b32_e32 v0, 7, v12
	global_load_lds_dwordx4 v[74:75], off
	s_mov_b32 m0, s29
	v_bfe_u32 v3, v12, 5, 1
	v_and_b32_e32 v87, 0x2f80, v0
	v_bitop3_b32 v0, v2, v5, 1 bitop3:0x6c
	global_load_lds_dwordx4 v[76:77], off
	s_mov_b32 m0, s34
	v_lshlrev_b32_e32 v6, 4, v0
	v_bitop3_b32 v0, v3, v5, 2 bitop3:0x36
	v_add_u32_e32 v91, 0x8000, v95
	global_load_lds_dwordx4 v[78:79], off
	s_mov_b32 m0, s35
	v_lshlrev_b32_e32 v84, 4, v0
	v_bitop3_b32 v0, v3, v5, 4 bitop3:0x36
	v_readfirstlane_b32 s36, v91
	v_add_u32_e32 v92, 0x8000, v99
	global_load_lds_dwordx4 v[80:81], off
	v_lshlrev_b32_e32 v118, 4, v0
	v_bitop3_b32 v0, v3, v5, 6 bitop3:0x36
	v_lshl_add_u64 v[2:3], v[66:67], 0, s[64:65]
	s_mov_b32 m0, s36
	v_readfirstlane_b32 s40, v92
	v_add_u32_e32 v93, 0x8000, v100
	s_waitcnt vmcnt(0)
	s_waitcnt vmcnt(0) lgkmcnt(0)
	s_barrier
	global_load_lds_dwordx4 v[2:3], off
	v_lshl_add_u64 v[2:3], v[68:69], 0, s[64:65]
	s_mov_b32 m0, s40
	v_readfirstlane_b32 s41, v93
	v_add_u32_e32 v94, 0x8000, v101
	global_load_lds_dwordx4 v[2:3], off
	v_lshl_add_u64 v[2:3], v[70:71], 0, s[64:65]
	s_mov_b32 m0, s41
	v_readfirstlane_b32 s46, v94
	v_add_u32_e32 v96, 0xc000, v95
	global_load_lds_dwordx4 v[2:3], off
	v_lshl_add_u64 v[2:3], v[72:73], 0, s[64:65]
	s_mov_b32 m0, s46
	v_readfirstlane_b32 s47, v96
	v_add_u32_e32 v97, 0xc000, v99
	global_load_lds_dwordx4 v[2:3], off
	v_lshl_add_u64 v[2:3], v[74:75], 0, s[64:65]
	s_mov_b32 m0, s47
	v_readfirstlane_b32 s49, v97
	v_add_u32_e32 v98, 0xc000, v100
	v_lshlrev_b32_e32 v119, 4, v0
	global_load_lds_dwordx4 v[2:3], off
	v_lshl_add_u64 v[2:3], v[76:77], 0, s[64:65]
	s_mov_b32 m0, s49
	v_readfirstlane_b32 s50, v98
	v_add_u32_e32 v0, 0xc000, v101
	global_load_lds_dwordx4 v[2:3], off
	v_lshl_add_u64 v[2:3], v[78:79], 0, s[64:65]
	s_mov_b32 m0, s50
	v_readfirstlane_b32 s18, v0
	global_load_lds_dwordx4 v[2:3], off
	v_lshl_add_u64 v[2:3], v[80:81], 0, s[64:65]
	s_mov_b32 m0, s18
	v_or_b32_e32 v0, v85, v6
	global_load_lds_dwordx4 v[2:3], off
	v_or_b32_e32 v86, v87, v6
	ds_read_b128 v[2:5], v0
	ds_read_b128 v[18:21], v0 offset:4096
	ds_read_b128 v[6:9], v86 offset:16384
	ds_read_b128 v[22:25], v86 offset:20480
	s_waitcnt lgkmcnt(0)
	v_mfma_f32_32x32x16_bf16 v[34:49], v[2:5], v[6:9], 0
	v_or_b32_e32 v88, v85, v84
	v_or_b32_e32 v89, v87, v84
	ds_read_b128 v[102:105], v88
	ds_read_b128 v[106:109], v88 offset:4096
	ds_read_b128 v[110:113], v89 offset:16384
	ds_read_b128 v[114:117], v89 offset:20480
	v_or_b32_e32 v90, v85, v118
	v_or_b32_e32 v84, v87, v118
	v_or_b32_e32 v85, v85, v119
	v_mfma_f32_32x32x16_bf16 v[50:65], v[2:5], v[22:25], 0
	v_or_b32_e32 v87, v87, v119
	s_mov_b32 m0, s37
	s_lshl_b32 s17, s17, 6
	v_mfma_f32_32x32x16_bf16 v[2:17], v[18:21], v[6:9], 0
	v_mfma_f32_32x32x16_bf16 v[18:33], v[18:21], v[22:25], 0
	s_waitcnt lgkmcnt(1)
	v_mfma_f32_32x32x16_bf16 v[34:49], v[102:105], v[110:113], v[34:49]
	s_waitcnt lgkmcnt(0)
	v_mfma_f32_32x32x16_bf16 v[50:65], v[102:105], v[114:117], v[50:65]
	v_mfma_f32_32x32x16_bf16 v[2:17], v[106:109], v[110:113], v[2:17]
	v_mfma_f32_32x32x16_bf16 v[18:33], v[106:109], v[114:117], v[18:33]
	ds_read_b128 v[102:105], v90
	ds_read_b128 v[106:109], v90 offset:4096
	ds_read_b128 v[110:113], v84 offset:16384
	ds_read_b128 v[114:117], v84 offset:20480
	s_waitcnt lgkmcnt(1)
	v_mfma_f32_32x32x16_bf16 v[34:49], v[102:105], v[110:113], v[34:49]
	s_waitcnt lgkmcnt(0)
	v_mfma_f32_32x32x16_bf16 v[50:65], v[102:105], v[114:117], v[50:65]
	v_mfma_f32_32x32x16_bf16 v[2:17], v[106:109], v[110:113], v[2:17]
	v_mfma_f32_32x32x16_bf16 v[18:33], v[106:109], v[114:117], v[18:33]
	ds_read_b128 v[102:105], v85
	ds_read_b128 v[106:109], v85 offset:4096
	ds_read_b128 v[110:113], v87 offset:16384
	ds_read_b128 v[114:117], v87 offset:20480
	s_waitcnt vmcnt(0)
	s_waitcnt lgkmcnt(0)
	s_barrier
; #define MFMA(a, b, c) __builtin_amdgcn_mfma_f32_32x32x16_bf16((a), (b), (c), 0, 0, 0)
; template <int AI, int BI>
; DI void gemm_tile(const u16* __restrict__ A, int lda, const u16* __restrict__ B, int ldb, int nk, bool swap,
;                   f32x16 (&acc)[AI][BI], char* lds) {
;     ...
;   for (int kt = 0; kt < nk; ++kt) {
;     const char* cur = lds + (kt & 1) * 32768;
;     if (kt + 1 < nk) gemm_stage<AI, BI>(A + (kt + 1) * 64, lda, B + (kt + 1) * 64, ldb, lds + ((kt + 1) & 1) * 32768, tid);
; #pragma unroll
;     for (int ks = 0; ks < 4; ++ks) {
;       const int co = ((ks * 2 + h) ^ sw) << 4;
;       s16x8 fa[AI], fb[BI];
; #pragma unroll
;       for (int i = 0; i < AI; ++i) fa[i] = *(const s16x8*)(cur + offA + i * 4096 + co);
; #pragma unroll
;       for (int i = 0; i < BI; ++i) fb[i] = *(const s16x8*)(cur + offB + i * 4096 + co);
; #pragma unroll
;       for (int i = 0; i < AI; ++i)
; #pragma unroll
;         for (int j = 0; j < BI; ++j) acc[i][j] = MFMA(fa[i], fb[j], acc[i][j]);
;     }
;     asm volatile("s_waitcnt vmcnt(0)" ::: "memory");
;     __syncthreads();
;   }
	v_mfma_f32_32x32x16_bf16 v[34:49], v[102:105], v[110:113], v[34:49]
	v_mfma_f32_32x32x16_bf16 v[50:65], v[102:105], v[114:117], v[50:65]
	v_lshl_add_u64 v[102:103], v[66:67], 0, s[4:5]
	global_load_lds_dwordx4 v[102:103], off
	v_lshl_add_u64 v[102:103], v[68:69], 0, s[4:5]
	s_mov_b32 m0, s48
	s_nop 0
	global_load_lds_dwordx4 v[102:103], off
	v_lshl_add_u64 v[102:103], v[70:71], 0, s[4:5]
	s_mov_b32 m0, s51
	v_mfma_f32_32x32x16_bf16 v[2:17], v[106:109], v[110:113], v[2:17]
	global_load_lds_dwordx4 v[102:103], off
	v_lshl_add_u64 v[102:103], v[72:73], 0, s[4:5]
	s_mov_b32 m0, s52
	s_nop 0
	global_load_lds_dwordx4 v[102:103], off
	v_lshl_add_u64 v[102:103], v[74:75], 0, s[4:5]
	s_mov_b32 m0, s28
	v_mfma_f32_32x32x16_bf16 v[18:33], v[106:109], v[114:117], v[18:33]
	global_load_lds_dwordx4 v[102:103], off
	v_lshl_add_u64 v[102:103], v[76:77], 0, s[4:5]
	s_mov_b32 m0, s29
	s_nop 0
	global_load_lds_dwordx4 v[102:103], off
	v_lshl_add_u64 v[102:103], v[78:79], 0, s[4:5]
	s_mov_b32 m0, s34
	s_nop 0
	global_load_lds_dwordx4 v[102:103], off
	v_lshl_add_u64 v[102:103], v[80:81], 0, s[4:5]
	s_mov_b32 m0, s35
	s_nop 0
	global_load_lds_dwordx4 v[102:103], off
	ds_read_b128 v[102:105], v0 offset:32768
	ds_read_b128 v[106:109], v0 offset:36864
	ds_read_b128 v[110:113], v86 offset:49152
	ds_read_b128 v[114:117], v86 offset:53248
	s_waitcnt lgkmcnt(0)
	v_mfma_f32_32x32x16_bf16 v[34:49], v[102:105], v[110:113], v[34:49]
	s_mov_b32 m0, s36
	v_mfma_f32_32x32x16_bf16 v[50:65], v[102:105], v[114:117], v[50:65]
	v_mfma_f32_32x32x16_bf16 v[2:17], v[106:109], v[110:113], v[2:17]
	v_mfma_f32_32x32x16_bf16 v[18:33], v[106:109], v[114:117], v[18:33]
	ds_read_b128 v[102:105], v88 offset:32768
	ds_read_b128 v[106:109], v88 offset:36864
	ds_read_b128 v[110:113], v89 offset:49152
	ds_read_b128 v[114:117], v89 offset:53248
	s_waitcnt lgkmcnt(1)
	v_mfma_f32_32x32x16_bf16 v[34:49], v[102:105], v[110:113], v[34:49]
	s_waitcnt lgkmcnt(0)
	v_mfma_f32_32x32x16_bf16 v[50:65], v[102:105], v[114:117], v[50:65]
	v_mfma_f32_32x32x16_bf16 v[2:17], v[106:109], v[110:113], v[2:17]
	v_mfma_f32_32x32x16_bf16 v[18:33], v[106:109], v[114:117], v[18:33]
	ds_read_b128 v[102:105], v90 offset:32768
	ds_read_b128 v[106:109], v90 offset:36864
	ds_read_b128 v[110:113], v84 offset:49152
	ds_read_b128 v[114:117], v84 offset:53248
	s_waitcnt lgkmcnt(1)
	v_mfma_f32_32x32x16_bf16 v[34:49], v[102:105], v[110:113], v[34:49]
	s_waitcnt lgkmcnt(0)
	v_mfma_f32_32x32x16_bf16 v[50:65], v[102:105], v[114:117], v[50:65]
	v_mfma_f32_32x32x16_bf16 v[2:17], v[106:109], v[110:113], v[2:17]
	v_mfma_f32_32x32x16_bf16 v[18:33], v[106:109], v[114:117], v[18:33]
	ds_read_b128 v[102:105], v85 offset:32768
	ds_read_b128 v[106:109], v85 offset:36864
	ds_read_b128 v[110:113], v87 offset:49152
	ds_read_b128 v[114:117], v87 offset:53248
	s_waitcnt vmcnt(0)
	s_waitcnt lgkmcnt(0)
	s_barrier
	v_mfma_f32_32x32x16_bf16 v[34:49], v[102:105], v[110:113], v[34:49]
	v_mfma_f32_32x32x16_bf16 v[50:65], v[102:105], v[114:117], v[50:65]
	v_lshl_add_u64 v[102:103], v[66:67], 0, s[66:67]
	global_load_lds_dwordx4 v[102:103], off
	v_lshl_add_u64 v[102:103], v[68:69], 0, s[66:67]
	s_mov_b32 m0, s40
	s_nop 0
	global_load_lds_dwordx4 v[102:103], off
	v_lshl_add_u64 v[102:103], v[70:71], 0, s[66:67]
	s_mov_b32 m0, s41
	v_mfma_f32_32x32x16_bf16 v[2:17], v[106:109], v[110:113], v[2:17]
	global_load_lds_dwordx4 v[102:103], off
	v_lshl_add_u64 v[102:103], v[72:73], 0, s[66:67]
	s_mov_b32 m0, s46
	s_nop 0
	global_load_lds_dwordx4 v[102:103], off
	v_lshl_add_u64 v[102:103], v[74:75], 0, s[66:67]
	s_mov_b32 m0, s47
	v_mfma_f32_32x32x16_bf16 v[18:33], v[106:109], v[114:117], v[18:33]
	global_load_lds_dwordx4 v[102:103], off
	v_lshl_add_u64 v[102:103], v[76:77], 0, s[66:67]
	s_mov_b32 m0, s49
	s_nop 0
	global_load_lds_dwordx4 v[102:103], off
	v_lshl_add_u64 v[102:103], v[78:79], 0, s[66:67]
	s_mov_b32 m0, s50
	s_nop 0
	global_load_lds_dwordx4 v[102:103], off
	v_lshl_add_u64 v[102:103], v[80:81], 0, s[66:67]
	s_mov_b32 m0, s18
	s_nop 0
	global_load_lds_dwordx4 v[102:103], off
	ds_read_b128 v[102:105], v0
	ds_read_b128 v[106:109], v0 offset:4096
	ds_read_b128 v[110:113], v86 offset:16384
	ds_read_b128 v[114:117], v86 offset:20480
	s_waitcnt lgkmcnt(0)
	v_mfma_f32_32x32x16_bf16 v[34:49], v[102:105], v[110:113], v[34:49]
	s_mov_b32 m0, s37
	v_mfma_f32_32x32x16_bf16 v[50:65], v[102:105], v[114:117], v[50:65]
	v_mfma_f32_32x32x16_bf16 v[2:17], v[106:109], v[110:113], v[2:17]
	v_mfma_f32_32x32x16_bf16 v[18:33], v[106:109], v[114:117], v[18:33]
	ds_read_b128 v[102:105], v88
	ds_read_b128 v[106:109], v88 offset:4096
	ds_read_b128 v[110:113], v89 offset:16384
	ds_read_b128 v[114:117], v89 offset:20480
	s_waitcnt lgkmcnt(1)
	v_mfma_f32_32x32x16_bf16 v[34:49], v[102:105], v[110:113], v[34:49]
	s_waitcnt lgkmcnt(0)
	v_mfma_f32_32x32x16_bf16 v[50:65], v[102:105], v[114:117], v[50:65]
	v_mfma_f32_32x32x16_bf16 v[2:17], v[106:109], v[110:113], v[2:17]
	v_mfma_f32_32x32x16_bf16 v[18:33], v[106:109], v[114:117], v[18:33]
	ds_read_b128 v[102:105], v90
	ds_read_b128 v[106:109], v90 offset:4096
	ds_read_b128 v[110:113], v84 offset:16384
	ds_read_b128 v[114:117], v84 offset:20480
	s_waitcnt lgkmcnt(1)
	v_mfma_f32_32x32x16_bf16 v[34:49], v[102:105], v[110:113], v[34:49]
	s_waitcnt lgkmcnt(0)
	v_mfma_f32_32x32x16_bf16 v[50:65], v[102:105], v[114:117], v[50:65]
	v_mfma_f32_32x32x16_bf16 v[2:17], v[106:109], v[110:113], v[2:17]
	v_mfma_f32_32x32x16_bf16 v[18:33], v[106:109], v[114:117], v[18:33]
	ds_read_b128 v[102:105], v85
	ds_read_b128 v[106:109], v85 offset:4096
	ds_read_b128 v[110:113], v87 offset:16384
	ds_read_b128 v[114:117], v87 offset:20480
	s_waitcnt vmcnt(0)
	s_waitcnt lgkmcnt(0)
	s_barrier
; #define MFMA(a, b, c) __builtin_amdgcn_mfma_f32_32x32x16_bf16((a), (b), (c), 0, 0, 0)
; template <int AI, int BI>
; DI void gemm_tile(const u16* __restrict__ A, int lda, const u16* __restrict__ B, int ldb, int nk, bool swap,
;                   f32x16 (&acc)[AI][BI], char* lds) {
;     ...
;   for (int kt = 0; kt < nk; ++kt) {
;     const char* cur = lds + (kt & 1) * 32768;
;     if (kt + 1 < nk) gemm_stage<AI, BI>(A + (kt + 1) * 64, lda, B + (kt + 1) * 64, ldb, lds + ((kt + 1) & 1) * 32768, tid);
; #pragma unroll
;     for (int ks = 0; ks < 4; ++ks) {
;       const int co = ((ks * 2 + h) ^ sw) << 4;
;       s16x8 fa[AI], fb[BI];
; #pragma unroll
;       for (int i = 0; i < AI; ++i) fa[i] = *(const s16x8*)(cur + offA + i * 4096 + co);
; #pragma unroll
;       for (int i = 0; i < BI; ++i) fb[i] = *(const s16x8*)(cur + offB + i * 4096 + co);
; #pragma unroll
;       for (int i = 0; i < AI; ++i)
; #pragma unroll
;         for (int j = 0; j < BI; ++j) acc[i][j] = MFMA(fa[i], fb[j], acc[i][j]);
;     }
;     asm volatile("s_waitcnt vmcnt(0)" ::: "memory");
;     __syncthreads();
;   }
	v_mfma_f32_32x32x16_bf16 v[34:49], v[102:105], v[110:113], v[34:49]
	v_mfma_f32_32x32x16_bf16 v[50:65], v[102:105], v[114:117], v[50:65]
	v_lshl_add_u64 v[102:103], v[66:67], 0, s[56:57]
	global_load_lds_dwordx4 v[102:103], off
	v_lshl_add_u64 v[102:103], v[68:69], 0, s[56:57]
	s_mov_b32 m0, s48
	s_nop 0
	global_load_lds_dwordx4 v[102:103], off
	v_lshl_add_u64 v[102:103], v[70:71], 0, s[56:57]
	s_mov_b32 m0, s51
	v_mfma_f32_32x32x16_bf16 v[2:17], v[106:109], v[110:113], v[2:17]
	global_load_lds_dwordx4 v[102:103], off
	v_lshl_add_u64 v[102:103], v[72:73], 0, s[56:57]
	s_mov_b32 m0, s52
	s_nop 0
	global_load_lds_dwordx4 v[102:103], off
	v_lshl_add_u64 v[102:103], v[74:75], 0, s[56:57]
	s_mov_b32 m0, s28
	v_mfma_f32_32x32x16_bf16 v[18:33], v[106:109], v[114:117], v[18:33]
	global_load_lds_dwordx4 v[102:103], off
	v_lshl_add_u64 v[102:103], v[76:77], 0, s[56:57]
	s_mov_b32 m0, s29
	s_nop 0
	global_load_lds_dwordx4 v[102:103], off
	v_lshl_add_u64 v[102:103], v[78:79], 0, s[56:57]
	s_mov_b32 m0, s34
	s_nop 0
	global_load_lds_dwordx4 v[102:103], off
	v_lshl_add_u64 v[102:103], v[80:81], 0, s[56:57]
	s_mov_b32 m0, s35
	s_nop 0
	global_load_lds_dwordx4 v[102:103], off
	ds_read_b128 v[102:105], v0 offset:32768
	ds_read_b128 v[106:109], v0 offset:36864
	ds_read_b128 v[110:113], v86 offset:49152
	ds_read_b128 v[114:117], v86 offset:53248
	s_waitcnt lgkmcnt(0)
	v_mfma_f32_32x32x16_bf16 v[34:49], v[102:105], v[110:113], v[34:49]
	s_mov_b32 m0, s36
	v_mfma_f32_32x32x16_bf16 v[50:65], v[102:105], v[114:117], v[50:65]
	v_mfma_f32_32x32x16_bf16 v[2:17], v[106:109], v[110:113], v[2:17]
	v_mfma_f32_32x32x16_bf16 v[18:33], v[106:109], v[114:117], v[18:33]
	ds_read_b128 v[102:105], v88 offset:32768
	ds_read_b128 v[106:109], v88 offset:36864
	ds_read_b128 v[110:113], v89 offset:49152
	ds_read_b128 v[114:117], v89 offset:53248
	s_waitcnt lgkmcnt(1)
	v_mfma_f32_32x32x16_bf16 v[34:49], v[102:105], v[110:113], v[34:49]
	s_waitcnt lgkmcnt(0)
	v_mfma_f32_32x32x16_bf16 v[50:65], v[102:105], v[114:117], v[50:65]
	v_mfma_f32_32x32x16_bf16 v[2:17], v[106:109], v[110:113], v[2:17]
	v_mfma_f32_32x32x16_bf16 v[18:33], v[106:109], v[114:117], v[18:33]
	ds_read_b128 v[102:105], v90 offset:32768
	ds_read_b128 v[106:109], v90 offset:36864
	ds_read_b128 v[110:113], v84 offset:49152
	ds_read_b128 v[114:117], v84 offset:53248
	s_waitcnt lgkmcnt(1)
	v_mfma_f32_32x32x16_bf16 v[34:49], v[102:105], v[110:113], v[34:49]
	s_waitcnt lgkmcnt(0)
	v_mfma_f32_32x32x16_bf16 v[50:65], v[102:105], v[114:117], v[50:65]
	v_mfma_f32_32x32x16_bf16 v[2:17], v[106:109], v[110:113], v[2:17]
	v_mfma_f32_32x32x16_bf16 v[18:33], v[106:109], v[114:117], v[18:33]
	ds_read_b128 v[102:105], v85 offset:32768
	ds_read_b128 v[106:109], v85 offset:36864
	ds_read_b128 v[110:113], v87 offset:49152
	ds_read_b128 v[114:117], v87 offset:53248
	s_waitcnt vmcnt(0)
	s_waitcnt lgkmcnt(0)
	s_barrier
	v_mfma_f32_32x32x16_bf16 v[34:49], v[102:105], v[110:113], v[34:49]
	v_mfma_f32_32x32x16_bf16 v[50:65], v[102:105], v[114:117], v[50:65]
	v_lshl_add_u64 v[102:103], v[66:67], 0, s[68:69]
	global_load_lds_dwordx4 v[102:103], off
	v_lshl_add_u64 v[102:103], v[68:69], 0, s[68:69]
	s_mov_b32 m0, s40
	s_nop 0
	global_load_lds_dwordx4 v[102:103], off
	v_lshl_add_u64 v[102:103], v[70:71], 0, s[68:69]
	s_mov_b32 m0, s41
	v_mfma_f32_32x32x16_bf16 v[2:17], v[106:109], v[110:113], v[2:17]
	global_load_lds_dwordx4 v[102:103], off
	v_lshl_add_u64 v[102:103], v[72:73], 0, s[68:69]
	s_mov_b32 m0, s46
	s_nop 0
	global_load_lds_dwordx4 v[102:103], off
	v_lshl_add_u64 v[102:103], v[74:75], 0, s[68:69]
	s_mov_b32 m0, s47
	v_mfma_f32_32x32x16_bf16 v[18:33], v[106:109], v[114:117], v[18:33]
	global_load_lds_dwordx4 v[102:103], off
	v_lshl_add_u64 v[102:103], v[76:77], 0, s[68:69]
	s_mov_b32 m0, s49
	s_nop 0
	global_load_lds_dwordx4 v[102:103], off
	v_lshl_add_u64 v[102:103], v[78:79], 0, s[68:69]
	s_mov_b32 m0, s50
	s_nop 0
	global_load_lds_dwordx4 v[102:103], off
	v_lshl_add_u64 v[102:103], v[80:81], 0, s[68:69]
	s_mov_b32 m0, s18
	s_nop 0
	global_load_lds_dwordx4 v[102:103], off
	ds_read_b128 v[102:105], v0
	ds_read_b128 v[106:109], v0 offset:4096
	ds_read_b128 v[110:113], v86 offset:16384
	ds_read_b128 v[114:117], v86 offset:20480
	s_waitcnt lgkmcnt(0)
	v_mfma_f32_32x32x16_bf16 v[34:49], v[102:105], v[110:113], v[34:49]
	s_mov_b32 m0, s37
	v_readfirstlane_b32 s37, v99
	v_mfma_f32_32x32x16_bf16 v[50:65], v[102:105], v[114:117], v[50:65]
	v_mfma_f32_32x32x16_bf16 v[2:17], v[106:109], v[110:113], v[2:17]
	v_mfma_f32_32x32x16_bf16 v[18:33], v[106:109], v[114:117], v[18:33]
	ds_read_b128 v[102:105], v88
	ds_read_b128 v[106:109], v88 offset:4096
	ds_read_b128 v[110:113], v89 offset:16384
	ds_read_b128 v[114:117], v89 offset:20480
	s_waitcnt lgkmcnt(1)
	v_mfma_f32_32x32x16_bf16 v[34:49], v[102:105], v[110:113], v[34:49]
	s_waitcnt lgkmcnt(0)
	v_mfma_f32_32x32x16_bf16 v[50:65], v[102:105], v[114:117], v[50:65]
	v_mfma_f32_32x32x16_bf16 v[2:17], v[106:109], v[110:113], v[2:17]
	v_mfma_f32_32x32x16_bf16 v[18:33], v[106:109], v[114:117], v[18:33]
	ds_read_b128 v[102:105], v90
	ds_read_b128 v[106:109], v90 offset:4096
	ds_read_b128 v[110:113], v84 offset:16384
	ds_read_b128 v[114:117], v84 offset:20480
	s_waitcnt lgkmcnt(1)
	v_mfma_f32_32x32x16_bf16 v[34:49], v[102:105], v[110:113], v[34:49]
	s_waitcnt lgkmcnt(0)
	v_mfma_f32_32x32x16_bf16 v[50:65], v[102:105], v[114:117], v[50:65]
	v_mfma_f32_32x32x16_bf16 v[2:17], v[106:109], v[110:113], v[2:17]
	v_mfma_f32_32x32x16_bf16 v[18:33], v[106:109], v[114:117], v[18:33]
	ds_read_b128 v[102:105], v85
	ds_read_b128 v[106:109], v85 offset:4096
	ds_read_b128 v[110:113], v87 offset:16384
	ds_read_b128 v[114:117], v87 offset:20480
	s_waitcnt vmcnt(0)
	s_waitcnt lgkmcnt(0)
	s_barrier
; #define MFMA(a, b, c) __builtin_amdgcn_mfma_f32_32x32x16_bf16((a), (b), (c), 0, 0, 0)
; template <int AI, int BI>
; DI void gemm_tile(const u16* __restrict__ A, int lda, const u16* __restrict__ B, int ldb, int nk, bool swap,
;                   f32x16 (&acc)[AI][BI], char* lds) {
;     ...
;   for (int kt = 0; kt < nk; ++kt) {
;     const char* cur = lds + (kt & 1) * 32768;
;     if (kt + 1 < nk) gemm_stage<AI, BI>(A + (kt + 1) * 64, lda, B + (kt + 1) * 64, ldb, lds + ((kt + 1) & 1) * 32768, tid);
; #pragma unroll
;     for (int ks = 0; ks < 4; ++ks) {
;       const int co = ((ks * 2 + h) ^ sw) << 4;
;       s16x8 fa[AI], fb[BI];
; #pragma unroll
;       for (int i = 0; i < AI; ++i) fa[i] = *(const s16x8*)(cur + offA + i * 4096 + co);
; #pragma unroll
;       for (int i = 0; i < BI; ++i) fb[i] = *(const s16x8*)(cur + offB + i * 4096 + co);
; #pragma unroll
;       for (int i = 0; i < AI; ++i)
; #pragma unroll
;         for (int j = 0; j < BI; ++j) acc[i][j] = MFMA(fa[i], fb[j], acc[i][j]);
;     }
;     asm volatile("s_waitcnt vmcnt(0)" ::: "memory");
;     __syncthreads();
;   }
	v_mfma_f32_32x32x16_bf16 v[34:49], v[102:105], v[110:113], v[34:49]
	v_mfma_f32_32x32x16_bf16 v[50:65], v[102:105], v[114:117], v[50:65]
	v_lshl_add_u64 v[102:103], v[66:67], 0, s[70:71]
	global_load_lds_dwordx4 v[102:103], off
	v_lshl_add_u64 v[102:103], v[68:69], 0, s[70:71]
	s_mov_b32 m0, s48
	v_readfirstlane_b32 s48, v93
	global_load_lds_dwordx4 v[102:103], off
	v_lshl_add_u64 v[102:103], v[70:71], 0, s[70:71]
	s_mov_b32 m0, s51
	v_mfma_f32_32x32x16_bf16 v[2:17], v[106:109], v[110:113], v[2:17]
	global_load_lds_dwordx4 v[102:103], off
	v_lshl_add_u64 v[102:103], v[72:73], 0, s[70:71]
	s_mov_b32 m0, s52
	v_readfirstlane_b32 s51, v97
	global_load_lds_dwordx4 v[102:103], off
	v_lshl_add_u64 v[102:103], v[74:75], 0, s[70:71]
	s_mov_b32 m0, s28
	v_mfma_f32_32x32x16_bf16 v[18:33], v[106:109], v[114:117], v[18:33]
	global_load_lds_dwordx4 v[102:103], off
	v_lshl_add_u64 v[102:103], v[76:77], 0, s[70:71]
	s_mov_b32 m0, s29
	v_readfirstlane_b32 s52, v98
	global_load_lds_dwordx4 v[102:103], off
	v_lshl_add_u64 v[102:103], v[78:79], 0, s[70:71]
	s_mov_b32 m0, s34
	s_nop 0
	global_load_lds_dwordx4 v[102:103], off
	v_lshl_add_u64 v[102:103], v[80:81], 0, s[70:71]
	s_mov_b32 m0, s35
	s_nop 0
	global_load_lds_dwordx4 v[102:103], off
	ds_read_b128 v[102:105], v0 offset:32768
	ds_read_b128 v[106:109], v0 offset:36864
	ds_read_b128 v[110:113], v86 offset:49152
	ds_read_b128 v[114:117], v86 offset:53248
	s_waitcnt lgkmcnt(0)
	v_mfma_f32_32x32x16_bf16 v[34:49], v[102:105], v[110:113], v[34:49]
	s_mov_b32 m0, s36
	v_readfirstlane_b32 s36, v95
	v_mfma_f32_32x32x16_bf16 v[50:65], v[102:105], v[114:117], v[50:65]
	v_mfma_f32_32x32x16_bf16 v[2:17], v[106:109], v[110:113], v[2:17]
	v_mfma_f32_32x32x16_bf16 v[18:33], v[106:109], v[114:117], v[18:33]
	ds_read_b128 v[102:105], v88 offset:32768
	ds_read_b128 v[106:109], v88 offset:36864
	ds_read_b128 v[110:113], v89 offset:49152
	ds_read_b128 v[114:117], v89 offset:53248
	s_waitcnt lgkmcnt(1)
	v_mfma_f32_32x32x16_bf16 v[34:49], v[102:105], v[110:113], v[34:49]
	s_waitcnt lgkmcnt(0)
	v_mfma_f32_32x32x16_bf16 v[50:65], v[102:105], v[114:117], v[50:65]
	v_mfma_f32_32x32x16_bf16 v[2:17], v[106:109], v[110:113], v[2:17]
	v_mfma_f32_32x32x16_bf16 v[18:33], v[106:109], v[114:117], v[18:33]
	ds_read_b128 v[102:105], v90 offset:32768
	ds_read_b128 v[106:109], v90 offset:36864
	ds_read_b128 v[110:113], v84 offset:49152
	ds_read_b128 v[114:117], v84 offset:53248
	s_waitcnt lgkmcnt(1)
	v_mfma_f32_32x32x16_bf16 v[34:49], v[102:105], v[110:113], v[34:49]
	s_waitcnt lgkmcnt(0)
	v_mfma_f32_32x32x16_bf16 v[50:65], v[102:105], v[114:117], v[50:65]
	v_mfma_f32_32x32x16_bf16 v[2:17], v[106:109], v[110:113], v[2:17]
	v_mfma_f32_32x32x16_bf16 v[18:33], v[106:109], v[114:117], v[18:33]
	ds_read_b128 v[102:105], v85 offset:32768
	ds_read_b128 v[106:109], v85 offset:36864
	ds_read_b128 v[110:113], v87 offset:49152
	ds_read_b128 v[114:117], v87 offset:53248
	s_waitcnt vmcnt(0)
	s_waitcnt lgkmcnt(0)
	s_barrier
	v_mfma_f32_32x32x16_bf16 v[34:49], v[102:105], v[110:113], v[34:49]
	v_mfma_f32_32x32x16_bf16 v[50:65], v[102:105], v[114:117], v[50:65]
	v_lshl_add_u64 v[102:103], v[66:67], 0, s[72:73]
	global_load_lds_dwordx4 v[102:103], off
	v_lshl_add_u64 v[102:103], v[68:69], 0, s[72:73]
	s_mov_b32 m0, s40
	v_readfirstlane_b32 s40, v100
	global_load_lds_dwordx4 v[102:103], off
	v_lshl_add_u64 v[102:103], v[70:71], 0, s[72:73]
	s_mov_b32 m0, s41
	v_mfma_f32_32x32x16_bf16 v[2:17], v[106:109], v[110:113], v[2:17]
	global_load_lds_dwordx4 v[102:103], off
	v_lshl_add_u64 v[102:103], v[72:73], 0, s[72:73]
	s_mov_b32 m0, s46
	v_readfirstlane_b32 s41, v101
	global_load_lds_dwordx4 v[102:103], off
	v_lshl_add_u64 v[102:103], v[74:75], 0, s[72:73]
	s_mov_b32 m0, s47
	v_mfma_f32_32x32x16_bf16 v[18:33], v[106:109], v[114:117], v[18:33]
	global_load_lds_dwordx4 v[102:103], off
	v_lshl_add_u64 v[102:103], v[76:77], 0, s[72:73]
	s_mov_b32 m0, s49
	v_lshl_add_u64 v[100:101], v[74:75], 0, s[74:75]
	global_load_lds_dwordx4 v[102:103], off
	v_lshl_add_u64 v[102:103], v[78:79], 0, s[72:73]
	s_mov_b32 m0, s50
	v_readfirstlane_b32 s46, v91
	global_load_lds_dwordx4 v[102:103], off
	v_lshl_add_u64 v[102:103], v[80:81], 0, s[72:73]
	s_mov_b32 m0, s18
	v_readfirstlane_b32 s47, v92
	global_load_lds_dwordx4 v[102:103], off
	ds_read_b128 v[102:105], v0
	ds_read_b128 v[106:109], v0 offset:4096
	ds_read_b128 v[110:113], v86 offset:16384
	ds_read_b128 v[114:117], v86 offset:20480
	s_waitcnt lgkmcnt(0)
	v_mfma_f32_32x32x16_bf16 v[34:49], v[102:105], v[110:113], v[34:49]
	s_mov_b32 m0, s36
	v_readfirstlane_b32 s49, v94
	v_lshl_add_u64 v[92:93], v[72:73], 0, s[76:77]
	v_readfirstlane_b32 s50, v96
	v_and_b32_e32 v91, 31, v82
	v_mfma_f32_32x32x16_bf16 v[50:65], v[102:105], v[114:117], v[50:65]
	v_mfma_f32_32x32x16_bf16 v[2:17], v[106:109], v[110:113], v[2:17]
	v_mfma_f32_32x32x16_bf16 v[18:33], v[106:109], v[114:117], v[18:33]
	ds_read_b128 v[102:105], v88
	ds_read_b128 v[106:109], v88 offset:4096
	ds_read_b128 v[110:113], v89 offset:16384
	ds_read_b128 v[114:117], v89 offset:20480
	s_waitcnt lgkmcnt(1)
	v_mfma_f32_32x32x16_bf16 v[34:49], v[102:105], v[110:113], v[34:49]
	s_waitcnt lgkmcnt(0)
	v_mfma_f32_32x32x16_bf16 v[50:65], v[102:105], v[114:117], v[50:65]
	v_mfma_f32_32x32x16_bf16 v[2:17], v[106:109], v[110:113], v[2:17]
	v_mfma_f32_32x32x16_bf16 v[18:33], v[106:109], v[114:117], v[18:33]
	ds_read_b128 v[102:105], v90
	ds_read_b128 v[106:109], v90 offset:4096
	ds_read_b128 v[110:113], v84 offset:16384
	ds_read_b128 v[114:117], v84 offset:20480
	s_waitcnt lgkmcnt(1)
	v_mfma_f32_32x32x16_bf16 v[34:49], v[102:105], v[110:113], v[34:49]
	s_waitcnt lgkmcnt(0)
	v_mfma_f32_32x32x16_bf16 v[50:65], v[102:105], v[114:117], v[50:65]
	v_mfma_f32_32x32x16_bf16 v[2:17], v[106:109], v[110:113], v[2:17]
	v_mfma_f32_32x32x16_bf16 v[18:33], v[106:109], v[114:117], v[18:33]
	ds_read_b128 v[102:105], v85
	ds_read_b128 v[106:109], v85 offset:4096
	ds_read_b128 v[110:113], v87 offset:16384
	ds_read_b128 v[114:117], v87 offset:20480
	s_waitcnt vmcnt(0)
	s_waitcnt lgkmcnt(0)
	s_barrier
; #define MFMA(a, b, c) __builtin_amdgcn_mfma_f32_32x32x16_bf16((a), (b), (c), 0, 0, 0)
; template <int AI, int BI>
; DI void gemm_tile(const u16* __restrict__ A, int lda, const u16* __restrict__ B, int ldb, int nk, bool swap,
;                   f32x16 (&acc)[AI][BI], char* lds) {
;     ...
;   for (int kt = 0; kt < nk; ++kt) {
;     const char* cur = lds + (kt & 1) * 32768;
;     if (kt + 1 < nk) gemm_stage<AI, BI>(A + (kt + 1) * 64, lda, B + (kt + 1) * 64, ldb, lds + ((kt + 1) & 1) * 32768, tid);
; #pragma unroll
;     for (int ks = 0; ks < 4; ++ks) {
;       const int co = ((ks * 2 + h) ^ sw) << 4;
;       s16x8 fa[AI], fb[BI];
; #pragma unroll
;       for (int i = 0; i < AI; ++i) fa[i] = *(const s16x8*)(cur + offA + i * 4096 + co);
; #pragma unroll
;       for (int i = 0; i < BI; ++i) fb[i] = *(const s16x8*)(cur + offB + i * 4096 + co);
; #pragma unroll
;       for (int i = 0; i < AI; ++i)
; #pragma unroll
;         for (int j = 0; j < BI; ++j) acc[i][j] = MFMA(fa[i], fb[j], acc[i][j]);
;     }
;     asm volatile("s_waitcnt vmcnt(0)" ::: "memory");
;     __syncthreads();
;   }
	v_mfma_f32_32x32x16_bf16 v[34:49], v[102:105], v[110:113], v[34:49]
	v_mfma_f32_32x32x16_bf16 v[50:65], v[102:105], v[114:117], v[50:65]
	v_lshl_add_u64 v[102:103], v[66:67], 0, s[74:75]
	global_load_lds_dwordx4 v[102:103], off
	v_lshl_add_u64 v[102:103], v[68:69], 0, s[74:75]
	s_mov_b32 m0, s37
	s_nop 0
	global_load_lds_dwordx4 v[102:103], off
	v_lshl_add_u64 v[102:103], v[70:71], 0, s[74:75]
	s_mov_b32 m0, s40
	v_mfma_f32_32x32x16_bf16 v[2:17], v[106:109], v[110:113], v[2:17]
	global_load_lds_dwordx4 v[102:103], off
	v_lshl_add_u64 v[102:103], v[72:73], 0, s[74:75]
	s_mov_b32 m0, s41
	s_nop 0
	global_load_lds_dwordx4 v[102:103], off
	s_mov_b32 m0, s28
	v_mfma_f32_32x32x16_bf16 v[18:33], v[106:109], v[114:117], v[18:33]
	global_load_lds_dwordx4 v[100:101], off
	v_lshl_add_u64 v[100:101], v[76:77], 0, s[74:75]
	s_mov_b32 m0, s29
	s_nop 0
	global_load_lds_dwordx4 v[100:101], off
	v_lshl_add_u64 v[100:101], v[78:79], 0, s[74:75]
	s_mov_b32 m0, s34
	s_nop 0
	global_load_lds_dwordx4 v[100:101], off
	v_lshl_add_u64 v[100:101], v[80:81], 0, s[74:75]
	s_mov_b32 m0, s35
	s_nop 0
	global_load_lds_dwordx4 v[100:101], off
	ds_read_b128 v[100:103], v0 offset:32768
	ds_read_b128 v[104:107], v0 offset:36864
	ds_read_b128 v[108:111], v86 offset:49152
	ds_read_b128 v[112:115], v86 offset:53248
	s_waitcnt lgkmcnt(0)
	v_mfma_f32_32x32x16_bf16 v[34:49], v[100:103], v[108:111], v[34:49]
	s_mov_b32 m0, s46
	v_mfma_f32_32x32x16_bf16 v[50:65], v[100:103], v[112:115], v[50:65]
	v_mfma_f32_32x32x16_bf16 v[2:17], v[104:107], v[108:111], v[2:17]
	v_mfma_f32_32x32x16_bf16 v[18:33], v[104:107], v[112:115], v[18:33]
	ds_read_b128 v[100:103], v88 offset:32768
	ds_read_b128 v[104:107], v88 offset:36864
	ds_read_b128 v[108:111], v89 offset:49152
	ds_read_b128 v[112:115], v89 offset:53248
	s_waitcnt lgkmcnt(1)
	v_mfma_f32_32x32x16_bf16 v[34:49], v[100:103], v[108:111], v[34:49]
	s_waitcnt lgkmcnt(0)
	v_mfma_f32_32x32x16_bf16 v[50:65], v[100:103], v[112:115], v[50:65]
	v_mfma_f32_32x32x16_bf16 v[2:17], v[104:107], v[108:111], v[2:17]
	v_mfma_f32_32x32x16_bf16 v[18:33], v[104:107], v[112:115], v[18:33]
	ds_read_b128 v[100:103], v90 offset:32768
	ds_read_b128 v[104:107], v90 offset:36864
	ds_read_b128 v[108:111], v84 offset:49152
	ds_read_b128 v[112:115], v84 offset:53248
	s_waitcnt lgkmcnt(1)
	v_mfma_f32_32x32x16_bf16 v[34:49], v[100:103], v[108:111], v[34:49]
	s_waitcnt lgkmcnt(0)
	v_mfma_f32_32x32x16_bf16 v[50:65], v[100:103], v[112:115], v[50:65]
	v_mfma_f32_32x32x16_bf16 v[2:17], v[104:107], v[108:111], v[2:17]
	v_mfma_f32_32x32x16_bf16 v[18:33], v[104:107], v[112:115], v[18:33]
	ds_read_b128 v[100:103], v85 offset:32768
	ds_read_b128 v[104:107], v85 offset:36864
	ds_read_b128 v[108:111], v87 offset:49152
	ds_read_b128 v[112:115], v87 offset:53248
	s_waitcnt vmcnt(0)
	s_waitcnt lgkmcnt(0)
	s_barrier
	v_mfma_f32_32x32x16_bf16 v[34:49], v[100:103], v[108:111], v[34:49]
	v_mfma_f32_32x32x16_bf16 v[50:65], v[100:103], v[112:115], v[50:65]
	v_lshl_add_u64 v[100:101], v[66:67], 0, s[76:77]
	global_load_lds_dwordx4 v[100:101], off
	v_lshl_add_u64 v[100:101], v[68:69], 0, s[76:77]
	s_mov_b32 m0, s47
	s_nop 0
	global_load_lds_dwordx4 v[100:101], off
	v_lshl_add_u64 v[100:101], v[70:71], 0, s[76:77]
	s_mov_b32 m0, s48
	v_mfma_f32_32x32x16_bf16 v[2:17], v[104:107], v[108:111], v[2:17]
	global_load_lds_dwordx4 v[100:101], off
	s_mov_b32 m0, s49
	s_nop 0
	global_load_lds_dwordx4 v[92:93], off
	v_lshl_add_u64 v[92:93], v[74:75], 0, s[76:77]
	s_mov_b32 m0, s50
	v_mfma_f32_32x32x16_bf16 v[18:33], v[104:107], v[112:115], v[18:33]
	global_load_lds_dwordx4 v[92:93], off
	v_lshl_add_u64 v[92:93], v[76:77], 0, s[76:77]
	s_mov_b32 m0, s51
	s_nop 0
	global_load_lds_dwordx4 v[92:93], off
	v_lshl_add_u64 v[92:93], v[78:79], 0, s[76:77]
	s_mov_b32 m0, s52
	s_nop 0
	global_load_lds_dwordx4 v[92:93], off
	v_lshl_add_u64 v[92:93], v[80:81], 0, s[76:77]
	s_mov_b32 m0, s18
	s_nop 0
	global_load_lds_dwordx4 v[92:93], off
	ds_read_b128 v[92:95], v0
	ds_read_b128 v[96:99], v0 offset:4096
	ds_read_b128 v[100:103], v86 offset:16384
	ds_read_b128 v[104:107], v86 offset:20480
	s_waitcnt lgkmcnt(0)
	v_mfma_f32_32x32x16_bf16 v[34:49], v[92:95], v[100:103], v[34:49]
	s_mov_b32 m0, s36
	v_mfma_f32_32x32x16_bf16 v[50:65], v[92:95], v[104:107], v[50:65]
	v_mfma_f32_32x32x16_bf16 v[2:17], v[96:99], v[100:103], v[2:17]
	v_mfma_f32_32x32x16_bf16 v[18:33], v[96:99], v[104:107], v[18:33]
	ds_read_b128 v[92:95], v88
	ds_read_b128 v[96:99], v88 offset:4096
	ds_read_b128 v[100:103], v89 offset:16384
	ds_read_b128 v[104:107], v89 offset:20480
	s_waitcnt lgkmcnt(1)
	v_mfma_f32_32x32x16_bf16 v[34:49], v[92:95], v[100:103], v[34:49]
	s_waitcnt lgkmcnt(0)
	v_mfma_f32_32x32x16_bf16 v[50:65], v[92:95], v[104:107], v[50:65]
	v_mfma_f32_32x32x16_bf16 v[2:17], v[96:99], v[100:103], v[2:17]
	v_mfma_f32_32x32x16_bf16 v[18:33], v[96:99], v[104:107], v[18:33]
	ds_read_b128 v[92:95], v90
	ds_read_b128 v[96:99], v90 offset:4096
	ds_read_b128 v[100:103], v84 offset:16384
	ds_read_b128 v[104:107], v84 offset:20480
	s_waitcnt lgkmcnt(1)
	v_mfma_f32_32x32x16_bf16 v[34:49], v[92:95], v[100:103], v[34:49]
	s_waitcnt lgkmcnt(0)
	v_mfma_f32_32x32x16_bf16 v[50:65], v[92:95], v[104:107], v[50:65]
	v_mfma_f32_32x32x16_bf16 v[2:17], v[96:99], v[100:103], v[2:17]
	v_mfma_f32_32x32x16_bf16 v[18:33], v[96:99], v[104:107], v[18:33]
	ds_read_b128 v[92:95], v85
	ds_read_b128 v[96:99], v85 offset:4096
	ds_read_b128 v[100:103], v87 offset:16384
	ds_read_b128 v[104:107], v87 offset:20480
	s_waitcnt vmcnt(0)
	s_waitcnt lgkmcnt(0)
	s_barrier
; #define MFMA(a, b, c) __builtin_amdgcn_mfma_f32_32x32x16_bf16((a), (b), (c), 0, 0, 0)
; template <int AI, int BI>
; DI void gemm_tile(const u16* __restrict__ A, int lda, const u16* __restrict__ B, int ldb, int nk, bool swap,
;                   f32x16 (&acc)[AI][BI], char* lds) {
;     ...
;   for (int kt = 0; kt < nk; ++kt) {
;     const char* cur = lds + (kt & 1) * 32768;
;     if (kt + 1 < nk) gemm_stage<AI, BI>(A + (kt + 1) * 64, lda, B + (kt + 1) * 64, ldb, lds + ((kt + 1) & 1) * 32768, tid);
; #pragma unroll
;     for (int ks = 0; ks < 4; ++ks) {
;       const int co = ((ks * 2 + h) ^ sw) << 4;
;       s16x8 fa[AI], fb[BI];
; #pragma unroll
;       for (int i = 0; i < AI; ++i) fa[i] = *(const s16x8*)(cur + offA + i * 4096 + co);
; #pragma unroll
;       for (int i = 0; i < BI; ++i) fb[i] = *(const s16x8*)(cur + offB + i * 4096 + co);
; #pragma unroll
;       for (int i = 0; i < AI; ++i)
; #pragma unroll
;         for (int j = 0; j < BI; ++j) acc[i][j] = MFMA(fa[i], fb[j], acc[i][j]);
;     }
;     asm volatile("s_waitcnt vmcnt(0)" ::: "memory");
;     __syncthreads();
;   }
	v_mfma_f32_32x32x16_bf16 v[34:49], v[92:95], v[100:103], v[34:49]
	v_mfma_f32_32x32x16_bf16 v[50:65], v[92:95], v[104:107], v[50:65]
	v_lshl_add_u64 v[92:93], v[66:67], 0, s[80:81]
	global_load_lds_dwordx4 v[92:93], off
	v_lshl_add_u64 v[92:93], v[68:69], 0, s[80:81]
	s_mov_b32 m0, s37
	s_nop 0
	global_load_lds_dwordx4 v[92:93], off
	v_lshl_add_u64 v[92:93], v[70:71], 0, s[80:81]
	s_mov_b32 m0, s40
	v_mfma_f32_32x32x16_bf16 v[2:17], v[96:99], v[100:103], v[2:17]
	global_load_lds_dwordx4 v[92:93], off
	v_lshl_add_u64 v[92:93], v[72:73], 0, s[80:81]
	s_mov_b32 m0, s41
	s_nop 0
	global_load_lds_dwordx4 v[92:93], off
	v_lshl_add_u64 v[92:93], v[74:75], 0, s[80:81]
	s_mov_b32 m0, s28
	v_mfma_f32_32x32x16_bf16 v[18:33], v[96:99], v[104:107], v[18:33]
	global_load_lds_dwordx4 v[92:93], off
	v_lshl_add_u64 v[92:93], v[76:77], 0, s[80:81]
	s_mov_b32 m0, s29
	s_nop 0
	global_load_lds_dwordx4 v[92:93], off
	v_lshl_add_u64 v[92:93], v[78:79], 0, s[80:81]
	s_mov_b32 m0, s34
	s_nop 0
	global_load_lds_dwordx4 v[92:93], off
	v_lshl_add_u64 v[92:93], v[80:81], 0, s[80:81]
	s_mov_b32 m0, s35
	s_nop 0
	global_load_lds_dwordx4 v[92:93], off
	ds_read_b128 v[92:95], v0 offset:32768
	ds_read_b128 v[96:99], v0 offset:36864
	ds_read_b128 v[100:103], v86 offset:49152
	ds_read_b128 v[104:107], v86 offset:53248
	s_waitcnt lgkmcnt(0)
	v_mfma_f32_32x32x16_bf16 v[34:49], v[92:95], v[100:103], v[34:49]
	s_mov_b32 m0, s46
	v_mfma_f32_32x32x16_bf16 v[50:65], v[92:95], v[104:107], v[50:65]
	v_mfma_f32_32x32x16_bf16 v[2:17], v[96:99], v[100:103], v[2:17]
	v_mfma_f32_32x32x16_bf16 v[18:33], v[96:99], v[104:107], v[18:33]
	ds_read_b128 v[92:95], v88 offset:32768
	ds_read_b128 v[96:99], v88 offset:36864
	ds_read_b128 v[100:103], v89 offset:49152
	ds_read_b128 v[104:107], v89 offset:53248
	s_waitcnt lgkmcnt(1)
	v_mfma_f32_32x32x16_bf16 v[34:49], v[92:95], v[100:103], v[34:49]
	s_waitcnt lgkmcnt(0)
	v_mfma_f32_32x32x16_bf16 v[50:65], v[92:95], v[104:107], v[50:65]
	v_mfma_f32_32x32x16_bf16 v[2:17], v[96:99], v[100:103], v[2:17]
	v_mfma_f32_32x32x16_bf16 v[18:33], v[96:99], v[104:107], v[18:33]
	ds_read_b128 v[92:95], v90 offset:32768
	ds_read_b128 v[96:99], v90 offset:36864
	ds_read_b128 v[100:103], v84 offset:49152
	ds_read_b128 v[104:107], v84 offset:53248
	s_waitcnt lgkmcnt(1)
	v_mfma_f32_32x32x16_bf16 v[34:49], v[92:95], v[100:103], v[34:49]
	s_waitcnt lgkmcnt(0)
	v_mfma_f32_32x32x16_bf16 v[50:65], v[92:95], v[104:107], v[50:65]
	v_mfma_f32_32x32x16_bf16 v[2:17], v[96:99], v[100:103], v[2:17]
	v_mfma_f32_32x32x16_bf16 v[18:33], v[96:99], v[104:107], v[18:33]
	ds_read_b128 v[92:95], v85 offset:32768
	ds_read_b128 v[96:99], v85 offset:36864
	ds_read_b128 v[100:103], v87 offset:49152
	ds_read_b128 v[104:107], v87 offset:53248
	s_waitcnt vmcnt(0)
	s_waitcnt lgkmcnt(0)
	s_barrier
	v_mfma_f32_32x32x16_bf16 v[34:49], v[92:95], v[100:103], v[34:49]
	v_mfma_f32_32x32x16_bf16 v[50:65], v[92:95], v[104:107], v[50:65]
	v_lshl_add_u64 v[92:93], v[66:67], 0, s[82:83]
	global_load_lds_dwordx4 v[92:93], off
	v_lshl_add_u64 v[92:93], v[68:69], 0, s[82:83]
	s_mov_b32 m0, s47
	s_nop 0
	global_load_lds_dwordx4 v[92:93], off
	v_lshl_add_u64 v[92:93], v[70:71], 0, s[82:83]
	s_mov_b32 m0, s48
	v_mfma_f32_32x32x16_bf16 v[2:17], v[96:99], v[100:103], v[2:17]
	global_load_lds_dwordx4 v[92:93], off
	v_lshl_add_u64 v[92:93], v[72:73], 0, s[82:83]
	s_mov_b32 m0, s49
	s_nop 0
	global_load_lds_dwordx4 v[92:93], off
	v_lshl_add_u64 v[92:93], v[74:75], 0, s[82:83]
	s_mov_b32 m0, s50
	v_mfma_f32_32x32x16_bf16 v[18:33], v[96:99], v[104:107], v[18:33]
	global_load_lds_dwordx4 v[92:93], off
	v_lshl_add_u64 v[92:93], v[76:77], 0, s[82:83]
	s_mov_b32 m0, s51
	s_nop 0
	global_load_lds_dwordx4 v[92:93], off
	v_lshl_add_u64 v[92:93], v[78:79], 0, s[82:83]
	s_mov_b32 m0, s52
	s_nop 0
	global_load_lds_dwordx4 v[92:93], off
	v_lshl_add_u64 v[92:93], v[80:81], 0, s[82:83]
	s_mov_b32 m0, s18
	s_nop 0
	global_load_lds_dwordx4 v[92:93], off
	ds_read_b128 v[92:95], v0
	ds_read_b128 v[96:99], v0 offset:4096
	ds_read_b128 v[100:103], v86 offset:16384
	ds_read_b128 v[104:107], v86 offset:20480
	s_waitcnt lgkmcnt(0)
	v_mfma_f32_32x32x16_bf16 v[34:49], v[92:95], v[100:103], v[34:49]
	s_mov_b32 m0, s36
	v_mfma_f32_32x32x16_bf16 v[50:65], v[92:95], v[104:107], v[50:65]
	v_mfma_f32_32x32x16_bf16 v[2:17], v[96:99], v[100:103], v[2:17]
	v_mfma_f32_32x32x16_bf16 v[18:33], v[96:99], v[104:107], v[18:33]
	ds_read_b128 v[92:95], v88
	ds_read_b128 v[96:99], v88 offset:4096
	ds_read_b128 v[100:103], v89 offset:16384
	ds_read_b128 v[104:107], v89 offset:20480
	s_waitcnt lgkmcnt(1)
	v_mfma_f32_32x32x16_bf16 v[34:49], v[92:95], v[100:103], v[34:49]
	s_waitcnt lgkmcnt(0)
	v_mfma_f32_32x32x16_bf16 v[50:65], v[92:95], v[104:107], v[50:65]
	v_mfma_f32_32x32x16_bf16 v[2:17], v[96:99], v[100:103], v[2:17]
	v_mfma_f32_32x32x16_bf16 v[18:33], v[96:99], v[104:107], v[18:33]
	ds_read_b128 v[92:95], v90
	ds_read_b128 v[96:99], v90 offset:4096
	ds_read_b128 v[100:103], v84 offset:16384
	ds_read_b128 v[104:107], v84 offset:20480
	s_waitcnt lgkmcnt(1)
	v_mfma_f32_32x32x16_bf16 v[34:49], v[92:95], v[100:103], v[34:49]
	s_waitcnt lgkmcnt(0)
	v_mfma_f32_32x32x16_bf16 v[50:65], v[92:95], v[104:107], v[50:65]
	v_mfma_f32_32x32x16_bf16 v[2:17], v[96:99], v[100:103], v[2:17]
	v_mfma_f32_32x32x16_bf16 v[18:33], v[96:99], v[104:107], v[18:33]
	ds_read_b128 v[92:95], v85
	ds_read_b128 v[96:99], v85 offset:4096
	ds_read_b128 v[100:103], v87 offset:16384
	ds_read_b128 v[104:107], v87 offset:20480
	s_waitcnt vmcnt(0)
	s_waitcnt lgkmcnt(0)
	s_barrier
; #define MFMA(a, b, c) __builtin_amdgcn_mfma_f32_32x32x16_bf16((a), (b), (c), 0, 0, 0)
; template <int AI, int BI>
; DI void gemm_tile(const u16* __restrict__ A, int lda, const u16* __restrict__ B, int ldb, int nk, bool swap,
;                   f32x16 (&acc)[AI][BI], char* lds) {
;     ...
;   for (int kt = 0; kt < nk; ++kt) {
;     const char* cur = lds + (kt & 1) * 32768;
;     if (kt + 1 < nk) gemm_stage<AI, BI>(A + (kt + 1) * 64, lda, B + (kt + 1) * 64, ldb, lds + ((kt + 1) & 1) * 32768, tid);
; #pragma unroll
;     for (int ks = 0; ks < 4; ++ks) {
;       const int co = ((ks * 2 + h) ^ sw) << 4;
;       s16x8 fa[AI], fb[BI];
; #pragma unroll
;       for (int i = 0; i < AI; ++i) fa[i] = *(const s16x8*)(cur + offA + i * 4096 + co);
; #pragma unroll
;       for (int i = 0; i < BI; ++i) fb[i] = *(const s16x8*)(cur + offB + i * 4096 + co);
; #pragma unroll
;       for (int i = 0; i < AI; ++i)
; #pragma unroll
;         for (int j = 0; j < BI; ++j) acc[i][j] = MFMA(fa[i], fb[j], acc[i][j]);
;     }
;     asm volatile("s_waitcnt vmcnt(0)" ::: "memory");
;     __syncthreads();
;   }
	v_mfma_f32_32x32x16_bf16 v[34:49], v[92:95], v[100:103], v[34:49]
	v_mfma_f32_32x32x16_bf16 v[50:65], v[92:95], v[104:107], v[50:65]
	v_lshl_add_u64 v[92:93], v[66:67], 0, s[84:85]
	global_load_lds_dwordx4 v[92:93], off
	v_lshl_add_u64 v[92:93], v[68:69], 0, s[84:85]
	s_mov_b32 m0, s37
	s_nop 0
	global_load_lds_dwordx4 v[92:93], off
	v_lshl_add_u64 v[92:93], v[70:71], 0, s[84:85]
	s_mov_b32 m0, s40
	v_mfma_f32_32x32x16_bf16 v[2:17], v[96:99], v[100:103], v[2:17]
	global_load_lds_dwordx4 v[92:93], off
	v_lshl_add_u64 v[92:93], v[72:73], 0, s[84:85]
	s_mov_b32 m0, s41
	s_nop 0
	global_load_lds_dwordx4 v[92:93], off
	v_lshl_add_u64 v[92:93], v[74:75], 0, s[84:85]
	s_mov_b32 m0, s28
	v_mfma_f32_32x32x16_bf16 v[18:33], v[96:99], v[104:107], v[18:33]
	global_load_lds_dwordx4 v[92:93], off
	v_lshl_add_u64 v[92:93], v[76:77], 0, s[84:85]
	s_mov_b32 m0, s29
	s_nop 0
	global_load_lds_dwordx4 v[92:93], off
	v_lshl_add_u64 v[92:93], v[78:79], 0, s[84:85]
	s_mov_b32 m0, s34
	s_nop 0
	global_load_lds_dwordx4 v[92:93], off
	v_lshl_add_u64 v[92:93], v[80:81], 0, s[84:85]
	s_mov_b32 m0, s35
	s_nop 0
	global_load_lds_dwordx4 v[92:93], off
	ds_read_b128 v[92:95], v0 offset:32768
	ds_read_b128 v[96:99], v0 offset:36864
	ds_read_b128 v[100:103], v86 offset:49152
	ds_read_b128 v[104:107], v86 offset:53248
	s_waitcnt lgkmcnt(0)
	v_mfma_f32_32x32x16_bf16 v[34:49], v[92:95], v[100:103], v[34:49]
	s_mov_b32 m0, s46
	v_mfma_f32_32x32x16_bf16 v[50:65], v[92:95], v[104:107], v[50:65]
	v_mfma_f32_32x32x16_bf16 v[2:17], v[96:99], v[100:103], v[2:17]
	v_mfma_f32_32x32x16_bf16 v[18:33], v[96:99], v[104:107], v[18:33]
	ds_read_b128 v[92:95], v88 offset:32768
	ds_read_b128 v[96:99], v88 offset:36864
	ds_read_b128 v[100:103], v89 offset:49152
	ds_read_b128 v[104:107], v89 offset:53248
	s_waitcnt lgkmcnt(1)
	v_mfma_f32_32x32x16_bf16 v[34:49], v[92:95], v[100:103], v[34:49]
	s_waitcnt lgkmcnt(0)
	v_mfma_f32_32x32x16_bf16 v[50:65], v[92:95], v[104:107], v[50:65]
	v_mfma_f32_32x32x16_bf16 v[2:17], v[96:99], v[100:103], v[2:17]
	v_mfma_f32_32x32x16_bf16 v[18:33], v[96:99], v[104:107], v[18:33]
	ds_read_b128 v[92:95], v90 offset:32768
	ds_read_b128 v[96:99], v90 offset:36864
	ds_read_b128 v[100:103], v84 offset:49152
	ds_read_b128 v[104:107], v84 offset:53248
	s_waitcnt lgkmcnt(1)
	v_mfma_f32_32x32x16_bf16 v[34:49], v[92:95], v[100:103], v[34:49]
	s_waitcnt lgkmcnt(0)
	v_mfma_f32_32x32x16_bf16 v[50:65], v[92:95], v[104:107], v[50:65]
	v_mfma_f32_32x32x16_bf16 v[2:17], v[96:99], v[100:103], v[2:17]
	v_mfma_f32_32x32x16_bf16 v[18:33], v[96:99], v[104:107], v[18:33]
	ds_read_b128 v[92:95], v85 offset:32768
	ds_read_b128 v[96:99], v85 offset:36864
	ds_read_b128 v[100:103], v87 offset:49152
	ds_read_b128 v[104:107], v87 offset:53248
	s_waitcnt vmcnt(0)
	s_waitcnt lgkmcnt(0)
	s_barrier
	v_mfma_f32_32x32x16_bf16 v[34:49], v[92:95], v[100:103], v[34:49]
	v_mfma_f32_32x32x16_bf16 v[50:65], v[92:95], v[104:107], v[50:65]
	v_lshl_add_u64 v[92:93], v[66:67], 0, s[78:79]
	global_load_lds_dwordx4 v[92:93], off
	v_lshl_add_u64 v[92:93], v[68:69], 0, s[78:79]
	s_mov_b32 m0, s47
	s_nop 0
	global_load_lds_dwordx4 v[92:93], off
	v_lshl_add_u64 v[92:93], v[70:71], 0, s[78:79]
	s_mov_b32 m0, s48
	v_mfma_f32_32x32x16_bf16 v[2:17], v[96:99], v[100:103], v[2:17]
	global_load_lds_dwordx4 v[92:93], off
	v_lshl_add_u64 v[92:93], v[72:73], 0, s[78:79]
	s_mov_b32 m0, s49
	s_nop 0
	global_load_lds_dwordx4 v[92:93], off
	v_lshl_add_u64 v[92:93], v[74:75], 0, s[78:79]
	s_mov_b32 m0, s50
	v_mfma_f32_32x32x16_bf16 v[18:33], v[96:99], v[104:107], v[18:33]
	global_load_lds_dwordx4 v[92:93], off
	v_lshl_add_u64 v[92:93], v[76:77], 0, s[78:79]
	s_mov_b32 m0, s51
	s_nop 0
	global_load_lds_dwordx4 v[92:93], off
	v_lshl_add_u64 v[92:93], v[78:79], 0, s[78:79]
	s_mov_b32 m0, s52
	s_nop 0
	global_load_lds_dwordx4 v[92:93], off
	v_lshl_add_u64 v[92:93], v[80:81], 0, s[78:79]
	s_mov_b32 m0, s18
	s_nop 0
	global_load_lds_dwordx4 v[92:93], off
	ds_read_b128 v[92:95], v0
	ds_read_b128 v[96:99], v0 offset:4096
	ds_read_b128 v[100:103], v86 offset:16384
	ds_read_b128 v[104:107], v86 offset:20480
	s_waitcnt lgkmcnt(0)
	v_mfma_f32_32x32x16_bf16 v[34:49], v[92:95], v[100:103], v[34:49]
	s_mov_b32 m0, s36
	v_mfma_f32_32x32x16_bf16 v[50:65], v[92:95], v[104:107], v[50:65]
	v_mfma_f32_32x32x16_bf16 v[2:17], v[96:99], v[100:103], v[2:17]
	v_mfma_f32_32x32x16_bf16 v[18:33], v[96:99], v[104:107], v[18:33]
	ds_read_b128 v[92:95], v88
	ds_read_b128 v[96:99], v88 offset:4096
	ds_read_b128 v[100:103], v89 offset:16384
	ds_read_b128 v[104:107], v89 offset:20480
	s_waitcnt lgkmcnt(1)
	v_mfma_f32_32x32x16_bf16 v[34:49], v[92:95], v[100:103], v[34:49]
	s_waitcnt lgkmcnt(0)
	v_mfma_f32_32x32x16_bf16 v[50:65], v[92:95], v[104:107], v[50:65]
	v_mfma_f32_32x32x16_bf16 v[2:17], v[96:99], v[100:103], v[2:17]
	v_mfma_f32_32x32x16_bf16 v[18:33], v[96:99], v[104:107], v[18:33]
	ds_read_b128 v[92:95], v90
	ds_read_b128 v[96:99], v90 offset:4096
	ds_read_b128 v[100:103], v84 offset:16384
	ds_read_b128 v[104:107], v84 offset:20480
	s_waitcnt lgkmcnt(1)
	v_mfma_f32_32x32x16_bf16 v[34:49], v[92:95], v[100:103], v[34:49]
	s_waitcnt lgkmcnt(0)
	v_mfma_f32_32x32x16_bf16 v[50:65], v[92:95], v[104:107], v[50:65]
	v_mfma_f32_32x32x16_bf16 v[2:17], v[96:99], v[100:103], v[2:17]
	v_mfma_f32_32x32x16_bf16 v[18:33], v[96:99], v[104:107], v[18:33]
	ds_read_b128 v[92:95], v85
	ds_read_b128 v[96:99], v85 offset:4096
	ds_read_b128 v[100:103], v87 offset:16384
	ds_read_b128 v[104:107], v87 offset:20480
	s_waitcnt vmcnt(0)
	s_waitcnt lgkmcnt(0)
	s_barrier
; #define MFMA(a, b, c) __builtin_amdgcn_mfma_f32_32x32x16_bf16((a), (b), (c), 0, 0, 0)
; template <int AI, int BI>
; DI void gemm_tile(const u16* __restrict__ A, int lda, const u16* __restrict__ B, int ldb, int nk, bool swap,
;                   f32x16 (&acc)[AI][BI], char* lds) {
;     ...
;   for (int kt = 0; kt < nk; ++kt) {
;     const char* cur = lds + (kt & 1) * 32768;
;     if (kt + 1 < nk) gemm_stage<AI, BI>(A + (kt + 1) * 64, lda, B + (kt + 1) * 64, ldb, lds + ((kt + 1) & 1) * 32768, tid);
; #pragma unroll
;     for (int ks = 0; ks < 4; ++ks) {
;       const int co = ((ks * 2 + h) ^ sw) << 4;
;       s16x8 fa[AI], fb[BI];
; #pragma unroll
;       for (int i = 0; i < AI; ++i) fa[i] = *(const s16x8*)(cur + offA + i * 4096 + co);
; #pragma unroll
;       for (int i = 0; i < BI; ++i) fb[i] = *(const s16x8*)(cur + offB + i * 4096 + co);
; #pragma unroll
;       for (int i = 0; i < AI; ++i)
; #pragma unroll
;         for (int j = 0; j < BI; ++j) acc[i][j] = MFMA(fa[i], fb[j], acc[i][j]);
;     }
;     asm volatile("s_waitcnt vmcnt(0)" ::: "memory");
;     __syncthreads();
;   }
	v_mfma_f32_32x32x16_bf16 v[34:49], v[92:95], v[100:103], v[34:49]
	v_mfma_f32_32x32x16_bf16 v[50:65], v[92:95], v[104:107], v[50:65]
	v_lshl_add_u64 v[92:93], v[66:67], 0, s[2:3]
	global_load_lds_dwordx4 v[92:93], off
	v_lshl_add_u64 v[92:93], v[68:69], 0, s[2:3]
	s_mov_b32 m0, s37
	v_lshl_add_u64 v[66:67], v[66:67], 0, s[30:31]
	global_load_lds_dwordx4 v[92:93], off
	v_lshl_add_u64 v[92:93], v[70:71], 0, s[2:3]
	s_mov_b32 m0, s40
	v_mfma_f32_32x32x16_bf16 v[2:17], v[96:99], v[100:103], v[2:17]
	global_load_lds_dwordx4 v[92:93], off
	v_lshl_add_u64 v[92:93], v[72:73], 0, s[2:3]
	s_mov_b32 m0, s41
	s_nop 0
	global_load_lds_dwordx4 v[92:93], off
	v_lshl_add_u64 v[92:93], v[74:75], 0, s[2:3]
	s_mov_b32 m0, s28
	v_mfma_f32_32x32x16_bf16 v[18:33], v[96:99], v[104:107], v[18:33]
	global_load_lds_dwordx4 v[92:93], off
	v_lshl_add_u64 v[92:93], v[76:77], 0, s[2:3]
	s_mov_b32 m0, s29
	s_movk_i32 s28, 0xb00
	global_load_lds_dwordx4 v[92:93], off
	v_lshl_add_u64 v[92:93], v[78:79], 0, s[2:3]
	s_mov_b32 m0, s34
	s_nop 0
	global_load_lds_dwordx4 v[92:93], off
	v_lshl_add_u64 v[92:93], v[80:81], 0, s[2:3]
	s_mov_b32 m0, s35
	s_nop 0
	global_load_lds_dwordx4 v[92:93], off
	ds_read_b128 v[92:95], v0 offset:32768
	ds_read_b128 v[96:99], v0 offset:36864
	ds_read_b128 v[100:103], v86 offset:49152
	ds_read_b128 v[104:107], v86 offset:53248
	s_waitcnt lgkmcnt(0)
	v_mfma_f32_32x32x16_bf16 v[34:49], v[92:95], v[100:103], v[34:49]
	s_mov_b32 m0, s46
	v_mfma_f32_32x32x16_bf16 v[50:65], v[92:95], v[104:107], v[50:65]
	v_mfma_f32_32x32x16_bf16 v[2:17], v[96:99], v[100:103], v[2:17]
	v_mfma_f32_32x32x16_bf16 v[18:33], v[96:99], v[104:107], v[18:33]
	ds_read_b128 v[92:95], v88 offset:32768
	ds_read_b128 v[96:99], v88 offset:36864
	ds_read_b128 v[100:103], v89 offset:49152
	ds_read_b128 v[104:107], v89 offset:53248
	s_waitcnt lgkmcnt(1)
	v_mfma_f32_32x32x16_bf16 v[34:49], v[92:95], v[100:103], v[34:49]
	s_waitcnt lgkmcnt(0)
	v_mfma_f32_32x32x16_bf16 v[50:65], v[92:95], v[104:107], v[50:65]
	v_mfma_f32_32x32x16_bf16 v[2:17], v[96:99], v[100:103], v[2:17]
	v_mfma_f32_32x32x16_bf16 v[18:33], v[96:99], v[104:107], v[18:33]
	ds_read_b128 v[92:95], v90 offset:32768
	ds_read_b128 v[96:99], v90 offset:36864
	ds_read_b128 v[100:103], v84 offset:49152
	ds_read_b128 v[104:107], v84 offset:53248
	s_waitcnt lgkmcnt(1)
	v_mfma_f32_32x32x16_bf16 v[34:49], v[92:95], v[100:103], v[34:49]
	s_waitcnt lgkmcnt(0)
	v_mfma_f32_32x32x16_bf16 v[50:65], v[92:95], v[104:107], v[50:65]
	v_mfma_f32_32x32x16_bf16 v[2:17], v[96:99], v[100:103], v[2:17]
	v_mfma_f32_32x32x16_bf16 v[18:33], v[96:99], v[104:107], v[18:33]
	ds_read_b128 v[92:95], v85 offset:32768
	ds_read_b128 v[96:99], v85 offset:36864
	ds_read_b128 v[100:103], v87 offset:49152
	ds_read_b128 v[104:107], v87 offset:53248
	s_waitcnt vmcnt(0)
	s_waitcnt lgkmcnt(0)
	s_barrier
	global_load_lds_dwordx4 v[66:67], off
	v_lshl_add_u64 v[66:67], v[68:69], 0, s[30:31]
	s_mov_b32 m0, s47
	v_mfma_f32_32x32x16_bf16 v[34:49], v[92:95], v[100:103], v[34:49]
	global_load_lds_dwordx4 v[66:67], off
	v_lshl_add_u64 v[66:67], v[70:71], 0, s[30:31]
	s_mov_b32 m0, s48
	s_nop 0
	global_load_lds_dwordx4 v[66:67], off
	v_lshl_add_u64 v[66:67], v[72:73], 0, s[30:31]
	s_mov_b32 m0, s49
	v_mfma_f32_32x32x16_bf16 v[50:65], v[92:95], v[104:107], v[50:65]
	global_load_lds_dwordx4 v[66:67], off
	v_lshl_add_u64 v[66:67], v[74:75], 0, s[30:31]
	s_mov_b32 m0, s50
	s_nop 0
	global_load_lds_dwordx4 v[66:67], off
	v_lshl_add_u64 v[66:67], v[76:77], 0, s[30:31]
	s_mov_b32 m0, s51
	v_mfma_f32_32x32x16_bf16 v[2:17], v[96:99], v[100:103], v[2:17]
	global_load_lds_dwordx4 v[66:67], off
	v_lshl_add_u64 v[66:67], v[78:79], 0, s[30:31]
	s_mov_b32 m0, s52
	s_nop 0
	global_load_lds_dwordx4 v[66:67], off
	v_lshl_add_u64 v[66:67], v[80:81], 0, s[30:31]
	s_mov_b32 m0, s18
	v_mfma_f32_32x32x16_bf16 v[18:33], v[96:99], v[104:107], v[18:33]
	global_load_lds_dwordx4 v[66:67], off
	ds_read_b128 v[66:69], v0
	ds_read_b128 v[70:73], v0 offset:4096
	ds_read_b128 v[74:77], v86 offset:16384
	ds_read_b128 v[78:81], v86 offset:20480
	s_waitcnt lgkmcnt(0)
	v_mfma_f32_32x32x16_bf16 v[34:49], v[66:69], v[74:77], v[34:49]
	v_mfma_f32_32x32x16_bf16 v[50:65], v[66:69], v[78:81], v[50:65]
	v_mfma_f32_32x32x16_bf16 v[2:17], v[70:73], v[74:77], v[2:17]
	v_mfma_f32_32x32x16_bf16 v[18:33], v[70:73], v[78:81], v[18:33]
	ds_read_b128 v[66:69], v88
	ds_read_b128 v[70:73], v88 offset:4096
	ds_read_b128 v[74:77], v89 offset:16384
	ds_read_b128 v[78:81], v89 offset:20480
	s_waitcnt lgkmcnt(1)
	v_mfma_f32_32x32x16_bf16 v[34:49], v[66:69], v[74:77], v[34:49]
	s_waitcnt lgkmcnt(0)
	v_mfma_f32_32x32x16_bf16 v[50:65], v[66:69], v[78:81], v[50:65]
	v_mfma_f32_32x32x16_bf16 v[2:17], v[70:73], v[74:77], v[2:17]
	v_mfma_f32_32x32x16_bf16 v[18:33], v[70:73], v[78:81], v[18:33]
	ds_read_b128 v[66:69], v90
	ds_read_b128 v[70:73], v90 offset:4096
	ds_read_b128 v[74:77], v84 offset:16384
	ds_read_b128 v[78:81], v84 offset:20480
	s_waitcnt lgkmcnt(1)
	v_mfma_f32_32x32x16_bf16 v[34:49], v[66:69], v[74:77], v[34:49]
	s_waitcnt lgkmcnt(0)
	v_mfma_f32_32x32x16_bf16 v[50:65], v[66:69], v[78:81], v[50:65]
	v_mfma_f32_32x32x16_bf16 v[2:17], v[70:73], v[74:77], v[2:17]
	v_mfma_f32_32x32x16_bf16 v[18:33], v[70:73], v[78:81], v[18:33]
	ds_read_b128 v[66:69], v85
	ds_read_b128 v[70:73], v85 offset:4096
	ds_read_b128 v[74:77], v87 offset:16384
	ds_read_b128 v[78:81], v87 offset:20480
	s_waitcnt vmcnt(0)
	s_waitcnt lgkmcnt(0)
	s_barrier
; #define MFMA(a, b, c) __builtin_amdgcn_mfma_f32_32x32x16_bf16((a), (b), (c), 0, 0, 0)
; #define GAS __attribute__((address_space(1)))
; DI int opaque0() { int z = 0; asm volatile("" : "+v"(z)); return z; }
; template <int AI, int BI>
; DI void gemm_tile(const u16* __restrict__ A, int lda, const u16* __restrict__ B, int ldb, int nk, bool swap,
;                   f32x16 (&acc)[AI][BI], char* lds) {
;     ...
; #pragma unroll
;     for (int ks = 0; ks < 4; ++ks) {
;       const int co = ((ks * 2 + h) ^ sw) << 4;
;       s16x8 fa[AI], fb[BI];
; #pragma unroll
;       for (int i = 0; i < AI; ++i) fa[i] = *(const s16x8*)(cur + offA + i * 4096 + co);
; #pragma unroll
;       for (int i = 0; i < BI; ++i) fb[i] = *(const s16x8*)(cur + offB + i * 4096 + co);
; #pragma unroll
;       for (int i = 0; i < AI; ++i)
; #pragma unroll
;         for (int j = 0; j < BI; ++j) acc[i][j] = MFMA(fa[i], fb[j], acc[i][j]);
; template <int AI>
; DI void gu_tile(char* wsb, int sub, int m0, int n0, char* lds) {
;     ...
;   const int m0e = m0 + opaque0();
;   const int hc = (n0 >> 1) + wb * 32 + r;
;   GAS u16* HIDu = uptr(HID);
;   const unsigned ib = (unsigned)((m0e + wa * 32 * AI + 4 * h) * 2816 + hc);
; #pragma unroll
;   for (int ai = 0; ai < AI; ++ai)
; #pragma unroll
;     for (int reg = 0; reg < 16; ++reg) {
;       float g = acc[ai][0][reg], u = acc[ai][1][reg];
;       float v = g * __builtin_amdgcn_rcpf(1.f + __expf(-g)) * u;
;       HIDu[ib + (unsigned)((ai * 32 + (reg & 3) + 8 * (reg >> 2)) * 2816)] = f2bf(v);
;       if ((reg & 7) == 7) __builtin_amdgcn_sched_barrier(0);
;     }
	v_mfma_f32_32x32x16_bf16 v[34:49], v[66:69], v[74:77], v[34:49]
	v_mfma_f32_32x32x16_bf16 v[50:65], v[66:69], v[78:81], v[50:65]
	v_mfma_f32_32x32x16_bf16 v[2:17], v[70:73], v[74:77], v[2:17]
	v_mfma_f32_32x32x16_bf16 v[18:33], v[70:73], v[78:81], v[18:33]
	ds_read_b128 v[66:69], v0 offset:32768
	ds_read_b128 v[70:73], v0 offset:36864
	ds_read_b128 v[74:77], v86 offset:49152
	ds_read_b128 v[78:81], v86 offset:53248
	v_mov_b32_e32 v0, v1
	s_waitcnt lgkmcnt(1)
	v_mfma_f32_32x32x16_bf16 v[34:49], v[66:69], v[74:77], v[34:49]
	s_waitcnt lgkmcnt(0)
	v_mfma_f32_32x32x16_bf16 v[50:65], v[66:69], v[78:81], v[50:65]
	v_mfma_f32_32x32x16_bf16 v[2:17], v[70:73], v[74:77], v[2:17]
	v_mfma_f32_32x32x16_bf16 v[18:33], v[70:73], v[78:81], v[18:33]
	ds_read_b128 v[66:69], v88 offset:32768
	ds_read_b128 v[70:73], v88 offset:36864
	ds_read_b128 v[74:77], v89 offset:49152
	ds_read_b128 v[78:81], v89 offset:53248
	s_waitcnt lgkmcnt(1)
	v_mfma_f32_32x32x16_bf16 v[34:49], v[66:69], v[74:77], v[34:49]
	s_waitcnt lgkmcnt(0)
	v_mfma_f32_32x32x16_bf16 v[50:65], v[66:69], v[78:81], v[50:65]
	v_mfma_f32_32x32x16_bf16 v[2:17], v[70:73], v[74:77], v[2:17]
	v_mfma_f32_32x32x16_bf16 v[18:33], v[70:73], v[78:81], v[18:33]
	ds_read_b128 v[66:69], v90 offset:32768
	ds_read_b128 v[70:73], v90 offset:36864
	ds_read_b128 v[74:77], v84 offset:49152
	ds_read_b128 v[78:81], v84 offset:53248
	s_waitcnt lgkmcnt(1)
	v_mfma_f32_32x32x16_bf16 v[34:49], v[66:69], v[74:77], v[34:49]
	s_waitcnt lgkmcnt(0)
	v_mfma_f32_32x32x16_bf16 v[50:65], v[66:69], v[78:81], v[50:65]
	v_mfma_f32_32x32x16_bf16 v[2:17], v[70:73], v[74:77], v[2:17]
	v_mfma_f32_32x32x16_bf16 v[18:33], v[70:73], v[78:81], v[18:33]
	ds_read_b128 v[66:69], v85 offset:32768
	ds_read_b128 v[70:73], v85 offset:36864
	ds_read_b128 v[74:77], v87 offset:49152
	ds_read_b128 v[78:81], v87 offset:53248
	s_waitcnt vmcnt(0)
	s_waitcnt lgkmcnt(0)
	s_barrier
	v_mfma_f32_32x32x16_bf16 v[34:49], v[66:69], v[74:77], v[34:49]
	v_mfma_f32_32x32x16_bf16 v[50:65], v[66:69], v[78:81], v[50:65]
	v_lshrrev_b32_e32 v66, 1, v83
	v_lshrrev_b32_e32 v68, 3, v82
	v_and_b32_e32 v67, 32, v66
	v_and_b32_e32 v66, 0xffffc0, v66
	v_and_or_b32 v68, v68, 4, s16
	v_add3_u32 v66, v68, v66, v0
	v_or3_b32 v0, s17, v91, v67
	s_nop 3
	v_mul_f32_e32 v67, 0xbfb8aa3b, v34
	v_exp_f32_e32 v67, v67
	v_mfma_f32_32x32x16_bf16 v[2:17], v[70:73], v[74:77], v[2:17]
	v_add_f32_e32 v67, 1.0, v67
	v_rcp_f32_e32 v67, v67
	s_nop 0
	v_mul_f32_e32 v34, v34, v67
	v_mad_u64_u32 v[66:67], s[16:17], v66, s28, v[0:1]
	v_mul_f32_e32 v0, 0xbfb8aa3b, v35
	v_exp_f32_e32 v0, v0
	v_mul_f32_e32 v34, v50, v34
	v_mov_b32_e32 v67, v1
	v_cvt_pk_bf16_f32 v34, v34, s0
	v_add_f32_e32 v0, 1.0, v0
	v_rcp_f32_e32 v0, v0
	v_lshl_add_u64 v[68:69], v[66:67], 1, s[6:7]
	global_store_short v[68:69], v34, off
	v_mfma_f32_32x32x16_bf16 v[18:33], v[70:73], v[78:81], v[18:33]
	v_mul_f32_e32 v0, v35, v0
	v_mul_f32_e32 v0, v51, v0
	v_cvt_pk_bf16_f32 v50, v0, s0
	v_add_u32_e32 v0, 0xb00, v66
	v_lshl_add_u64 v[34:35], v[0:1], 1, s[6:7]
	v_mul_f32_e32 v0, 0xbfb8aa3b, v36
	v_exp_f32_e32 v0, v0
	global_store_short v[34:35], v50, off
	v_add_f32_e32 v0, 1.0, v0
	v_rcp_f32_e32 v0, v0
	s_nop 0
	v_mul_f32_e32 v0, v36, v0
	v_mul_f32_e32 v0, v52, v0
	v_cvt_pk_bf16_f32 v36, v0, s0
	v_add_u32_e32 v0, 0x1600, v66
	v_lshl_add_u64 v[34:35], v[0:1], 1, s[6:7]
	v_mul_f32_e32 v0, 0xbfb8aa3b, v37
	v_exp_f32_e32 v0, v0
	global_store_short v[34:35], v36, off
	v_add_f32_e32 v0, 1.0, v0
	v_rcp_f32_e32 v0, v0
	s_nop 0
	v_mul_f32_e32 v0, v37, v0
	v_mul_f32_e32 v0, v53, v0
	v_cvt_pk_bf16_f32 v36, v0, s0
	v_add_u32_e32 v0, 0x2100, v66
	v_lshl_add_u64 v[34:35], v[0:1], 1, s[6:7]
	v_mul_f32_e32 v0, 0xbfb8aa3b, v38
	v_exp_f32_e32 v0, v0
	global_store_short v[34:35], v36, off
	v_add_f32_e32 v0, 1.0, v0
	v_rcp_f32_e32 v0, v0
	s_nop 0
	v_mul_f32_e32 v0, v38, v0
	v_mul_f32_e32 v0, v54, v0
	v_cvt_pk_bf16_f32 v36, v0, s0
	v_add_u32_e32 v0, 0x5800, v66
	v_lshl_add_u64 v[34:35], v[0:1], 1, s[6:7]
	v_mul_f32_e32 v0, 0xbfb8aa3b, v39
	v_exp_f32_e32 v0, v0
	global_store_short v[34:35], v36, off
	v_add_f32_e32 v0, 1.0, v0
	v_rcp_f32_e32 v0, v0
	s_nop 0
	v_mul_f32_e32 v0, v39, v0
	v_mul_f32_e32 v0, v55, v0
	v_cvt_pk_bf16_f32 v36, v0, s0
	v_add_u32_e32 v0, 0x6300, v66
	v_lshl_add_u64 v[34:35], v[0:1], 1, s[6:7]
	v_mul_f32_e32 v0, 0xbfb8aa3b, v40
	v_exp_f32_e32 v0, v0
	global_store_short v[34:35], v36, off
	v_add_f32_e32 v0, 1.0, v0
	v_rcp_f32_e32 v0, v0
	s_nop 0
	v_mul_f32_e32 v0, v40, v0
	v_mul_f32_e32 v0, v56, v0
	v_cvt_pk_bf16_f32 v36, v0, s0
	v_add_u32_e32 v0, 0x6e00, v66
	v_lshl_add_u64 v[34:35], v[0:1], 1, s[6:7]
	v_mul_f32_e32 v0, 0xbfb8aa3b, v41
	v_exp_f32_e32 v0, v0
	global_store_short v[34:35], v36, off
	v_add_f32_e32 v0, 1.0, v0
	v_rcp_f32_e32 v0, v0
	s_nop 0
	v_mul_f32_e32 v0, v41, v0
	v_mul_f32_e32 v0, v57, v0
	v_cvt_pk_bf16_f32 v36, v0, s0
	v_add_u32_e32 v0, 0x7900, v66
	v_lshl_add_u64 v[34:35], v[0:1], 1, s[6:7]
	global_store_short v[34:35], v36, off
	v_mul_f32_e32 v0, 0xbfb8aa3b, v42
	v_exp_f32_e32 v0, v0
	s_nop 0
	v_add_f32_e32 v0, 1.0, v0
	v_rcp_f32_e32 v0, v0
	s_nop 0
	v_mul_f32_e32 v0, v42, v0
	v_mul_f32_e32 v0, v58, v0
	v_cvt_pk_bf16_f32 v36, v0, s0
	v_add_u32_e32 v0, 0xb000, v66
	v_lshl_add_u64 v[34:35], v[0:1], 1, s[6:7]
	v_mul_f32_e32 v0, 0xbfb8aa3b, v43
	v_exp_f32_e32 v0, v0
	global_store_short v[34:35], v36, off
	v_add_f32_e32 v0, 1.0, v0
	v_rcp_f32_e32 v0, v0
	s_nop 0
	v_mul_f32_e32 v0, v43, v0
	v_mul_f32_e32 v0, v59, v0
	v_cvt_pk_bf16_f32 v36, v0, s0
	v_add_u32_e32 v0, 0xbb00, v66
	v_lshl_add_u64 v[34:35], v[0:1], 1, s[6:7]
	v_mul_f32_e32 v0, 0xbfb8aa3b, v44
	v_exp_f32_e32 v0, v0
	global_store_short v[34:35], v36, off
; template <int AI>
; DI void gu_tile(char* wsb, int sub, int m0, int n0, char* lds) {
;     ...
; #pragma unroll
;   for (int ai = 0; ai < AI; ++ai)
; #pragma unroll
;     for (int reg = 0; reg < 16; ++reg) {
;       float g = acc[ai][0][reg], u = acc[ai][1][reg];
;       float v = g * __builtin_amdgcn_rcpf(1.f + __expf(-g)) * u;
;       HIDu[ib + (unsigned)((ai * 32 + (reg & 3) + 8 * (reg >> 2)) * 2816)] = f2bf(v);
;       if ((reg & 7) == 7) __builtin_amdgcn_sched_barrier(0);
;     }
; DI void phase_gu(const Params& p, char* wsb, int sub, int mrows, char* lds) {
;     ...
;   for (int rnd = 0; next_tile(rnd, 128, 44, mt, nt); ++rnd) gu_tile<2>(wsb, sub, mt * 128, nt * 128, lds);
;   if (mrows > TL)
;     for (int rnd = 0; next_tile(rnd, 32, 44, mt, nt); ++rnd) gu_tile<1>(wsb, sub, TL + mt * 64, nt * 128, lds);
	v_add_f32_e32 v0, 1.0, v0
	v_rcp_f32_e32 v0, v0
	s_nop 0
	v_mul_f32_e32 v0, v44, v0
	v_mul_f32_e32 v0, v60, v0
	v_cvt_pk_bf16_f32 v36, v0, s0
	v_add_u32_e32 v0, 0xc600, v66
	v_lshl_add_u64 v[34:35], v[0:1], 1, s[6:7]
	v_mul_f32_e32 v0, 0xbfb8aa3b, v45
	v_exp_f32_e32 v0, v0
	global_store_short v[34:35], v36, off
	v_add_f32_e32 v0, 1.0, v0
	v_rcp_f32_e32 v0, v0
	s_nop 0
	v_mul_f32_e32 v0, v45, v0
	v_mul_f32_e32 v0, v61, v0
	v_cvt_pk_bf16_f32 v36, v0, s0
	v_add_u32_e32 v0, 0xd100, v66
	v_lshl_add_u64 v[34:35], v[0:1], 1, s[6:7]
	v_mul_f32_e32 v0, 0xbfb8aa3b, v46
	v_exp_f32_e32 v0, v0
	global_store_short v[34:35], v36, off
	v_add_f32_e32 v0, 1.0, v0
	v_rcp_f32_e32 v0, v0
	s_nop 0
	v_mul_f32_e32 v0, v46, v0
	v_mul_f32_e32 v0, v62, v0
	v_cvt_pk_bf16_f32 v36, v0, s0
	v_add_u32_e32 v0, 0x10800, v66
	v_lshl_add_u64 v[34:35], v[0:1], 1, s[6:7]
	v_mul_f32_e32 v0, 0xbfb8aa3b, v47
	v_exp_f32_e32 v0, v0
	global_store_short v[34:35], v36, off
	v_add_f32_e32 v0, 1.0, v0
	v_rcp_f32_e32 v0, v0
	s_nop 0
	v_mul_f32_e32 v0, v47, v0
	v_mul_f32_e32 v0, v63, v0
	v_cvt_pk_bf16_f32 v36, v0, s0
	v_add_u32_e32 v0, 0x11300, v66
	v_lshl_add_u64 v[34:35], v[0:1], 1, s[6:7]
	v_mul_f32_e32 v0, 0xbfb8aa3b, v48
	v_exp_f32_e32 v0, v0
	global_store_short v[34:35], v36, off
	v_add_f32_e32 v0, 1.0, v0
	v_rcp_f32_e32 v0, v0
	s_nop 0
	v_mul_f32_e32 v0, v48, v0
	v_mul_f32_e32 v0, v64, v0
	v_cvt_pk_bf16_f32 v36, v0, s0
	v_add_u32_e32 v0, 0x11e00, v66
	v_lshl_add_u64 v[34:35], v[0:1], 1, s[6:7]
	v_mul_f32_e32 v0, 0xbfb8aa3b, v49
	v_exp_f32_e32 v0, v0
	global_store_short v[34:35], v36, off
	v_add_f32_e32 v0, 1.0, v0
	v_rcp_f32_e32 v0, v0
	s_nop 0
	v_mul_f32_e32 v0, v49, v0
	v_mul_f32_e32 v0, v65, v0
	v_cvt_pk_bf16_f32 v36, v0, s0
	v_add_u32_e32 v0, 0x12900, v66
	v_lshl_add_u64 v[34:35], v[0:1], 1, s[6:7]
	global_store_short v[34:35], v36, off
	v_mul_f32_e32 v0, 0xbfb8aa3b, v2
	v_exp_f32_e32 v0, v0
	s_nop 0
	v_add_f32_e32 v0, 1.0, v0
	v_rcp_f32_e32 v0, v0
	s_nop 0
	v_mul_f32_e32 v0, v2, v0
	v_mul_f32_e32 v0, v18, v0
	v_cvt_pk_bf16_f32 v2, v0, s0
	v_add_u32_e32 v0, 0x16000, v66
	v_lshl_add_u64 v[34:35], v[0:1], 1, s[6:7]
	v_mul_f32_e32 v0, 0xbfb8aa3b, v3
	v_exp_f32_e32 v0, v0
	global_store_short v[34:35], v2, off
	v_add_f32_e32 v0, 1.0, v0
	v_rcp_f32_e32 v0, v0
	s_nop 0
	v_mul_f32_e32 v0, v3, v0
	v_mul_f32_e32 v0, v19, v0
	v_cvt_pk_bf16_f32 v18, v0, s0
	v_add_u32_e32 v0, 0x16b00, v66
	v_lshl_add_u64 v[2:3], v[0:1], 1, s[6:7]
	v_mul_f32_e32 v0, 0xbfb8aa3b, v4
	v_exp_f32_e32 v0, v0
	global_store_short v[2:3], v18, off
	v_add_f32_e32 v0, 1.0, v0
	v_rcp_f32_e32 v0, v0
	s_nop 0
	v_mul_f32_e32 v0, v4, v0
	v_mul_f32_e32 v0, v20, v0
	v_cvt_pk_bf16_f32 v4, v0, s0
	v_add_u32_e32 v0, 0x17600, v66
	v_lshl_add_u64 v[2:3], v[0:1], 1, s[6:7]
	v_mul_f32_e32 v0, 0xbfb8aa3b, v5
	v_exp_f32_e32 v0, v0
	global_store_short v[2:3], v4, off
	v_add_f32_e32 v0, 1.0, v0
	v_rcp_f32_e32 v0, v0
	s_nop 0
	v_mul_f32_e32 v0, v5, v0
	v_mul_f32_e32 v0, v21, v0
	v_cvt_pk_bf16_f32 v4, v0, s0
	v_add_u32_e32 v0, 0x18100, v66
	v_lshl_add_u64 v[2:3], v[0:1], 1, s[6:7]
	v_mul_f32_e32 v0, 0xbfb8aa3b, v6
	v_exp_f32_e32 v0, v0
	global_store_short v[2:3], v4, off
	v_add_f32_e32 v0, 1.0, v0
	v_rcp_f32_e32 v0, v0
	s_nop 0
	v_mul_f32_e32 v0, v6, v0
	v_mul_f32_e32 v0, v22, v0
	v_cvt_pk_bf16_f32 v4, v0, s0
	v_add_u32_e32 v0, 0x1b800, v66
	v_lshl_add_u64 v[2:3], v[0:1], 1, s[6:7]
	v_mul_f32_e32 v0, 0xbfb8aa3b, v7
	v_exp_f32_e32 v0, v0
	global_store_short v[2:3], v4, off
	v_add_f32_e32 v0, 1.0, v0
	v_rcp_f32_e32 v0, v0
	s_nop 0
	v_mul_f32_e32 v0, v7, v0
	v_mul_f32_e32 v0, v23, v0
	v_cvt_pk_bf16_f32 v4, v0, s0
	v_add_u32_e32 v0, 0x1c300, v66
	v_lshl_add_u64 v[2:3], v[0:1], 1, s[6:7]
	v_mul_f32_e32 v0, 0xbfb8aa3b, v8
	v_exp_f32_e32 v0, v0
	global_store_short v[2:3], v4, off
	v_add_f32_e32 v0, 1.0, v0
	v_rcp_f32_e32 v0, v0
	s_nop 0
	v_mul_f32_e32 v0, v8, v0
	v_mul_f32_e32 v0, v24, v0
	v_cvt_pk_bf16_f32 v4, v0, s0
	v_add_u32_e32 v0, 0x1ce00, v66
	v_lshl_add_u64 v[2:3], v[0:1], 1, s[6:7]
	v_mul_f32_e32 v0, 0xbfb8aa3b, v9
	v_exp_f32_e32 v0, v0
	global_store_short v[2:3], v4, off
	v_add_f32_e32 v0, 1.0, v0
	v_rcp_f32_e32 v0, v0
	s_nop 0
	v_mul_f32_e32 v0, v9, v0
	v_mul_f32_e32 v0, v25, v0
	v_cvt_pk_bf16_f32 v4, v0, s0
	v_add_u32_e32 v0, 0x1d900, v66
	v_lshl_add_u64 v[2:3], v[0:1], 1, s[6:7]
	global_store_short v[2:3], v4, off
	v_mul_f32_e32 v0, 0xbfb8aa3b, v10
	v_exp_f32_e32 v0, v0
	s_nop 0
	v_add_f32_e32 v0, 1.0, v0
	v_rcp_f32_e32 v0, v0
	s_nop 0
	v_mul_f32_e32 v0, v10, v0
	v_mul_f32_e32 v0, v26, v0
	v_cvt_pk_bf16_f32 v4, v0, s0
	v_add_u32_e32 v0, 0x21000, v66
	v_lshl_add_u64 v[2:3], v[0:1], 1, s[6:7]
	v_mul_f32_e32 v0, 0xbfb8aa3b, v11
	v_exp_f32_e32 v0, v0
	global_store_short v[2:3], v4, off
	v_add_f32_e32 v0, 1.0, v0
	v_rcp_f32_e32 v0, v0
	s_nop 0
	v_mul_f32_e32 v0, v11, v0
	v_mul_f32_e32 v0, v27, v0
	v_cvt_pk_bf16_f32 v4, v0, s0
	v_add_u32_e32 v0, 0x21b00, v66
	v_lshl_add_u64 v[2:3], v[0:1], 1, s[6:7]
	v_mul_f32_e32 v0, 0xbfb8aa3b, v12
	v_exp_f32_e32 v0, v0
	global_store_short v[2:3], v4, off
	v_add_f32_e32 v0, 1.0, v0
	v_rcp_f32_e32 v0, v0
	s_nop 0
	v_mul_f32_e32 v0, v12, v0
	v_mul_f32_e32 v0, v28, v0
	v_cvt_pk_bf16_f32 v4, v0, s0
	v_add_u32_e32 v0, 0x22600, v66
	v_lshl_add_u64 v[2:3], v[0:1], 1, s[6:7]
	v_mul_f32_e32 v0, 0xbfb8aa3b, v13
	v_exp_f32_e32 v0, v0
	global_store_short v[2:3], v4, off
	v_add_f32_e32 v0, 1.0, v0
	v_rcp_f32_e32 v0, v0
	s_nop 0
	v_mul_f32_e32 v0, v13, v0
	v_mul_f32_e32 v0, v29, v0
	v_cvt_pk_bf16_f32 v4, v0, s0
	v_add_u32_e32 v0, 0x23100, v66
	v_lshl_add_u64 v[2:3], v[0:1], 1, s[6:7]
	v_mul_f32_e32 v0, 0xbfb8aa3b, v14
	v_exp_f32_e32 v0, v0
	global_store_short v[2:3], v4, off
	v_add_f32_e32 v0, 1.0, v0
	v_rcp_f32_e32 v0, v0
	s_nop 0
	v_mul_f32_e32 v0, v14, v0
	v_mul_f32_e32 v0, v30, v0
	v_cvt_pk_bf16_f32 v4, v0, s0
	v_add_u32_e32 v0, 0x26800, v66
	v_lshl_add_u64 v[2:3], v[0:1], 1, s[6:7]
	v_mul_f32_e32 v0, 0xbfb8aa3b, v15
	v_exp_f32_e32 v0, v0
	global_store_short v[2:3], v4, off
	v_add_f32_e32 v0, 1.0, v0
	v_rcp_f32_e32 v0, v0
	s_nop 0
	v_mul_f32_e32 v0, v15, v0
	v_mul_f32_e32 v0, v31, v0
	v_cvt_pk_bf16_f32 v4, v0, s0
	v_add_u32_e32 v0, 0x27300, v66
	v_lshl_add_u64 v[2:3], v[0:1], 1, s[6:7]
	v_mul_f32_e32 v0, 0xbfb8aa3b, v16
	v_exp_f32_e32 v0, v0
	global_store_short v[2:3], v4, off
	v_add_f32_e32 v0, 1.0, v0
	v_rcp_f32_e32 v0, v0
	s_nop 0
	v_mul_f32_e32 v0, v16, v0
	v_mul_f32_e32 v0, v32, v0
	v_cvt_pk_bf16_f32 v4, v0, s0
	v_add_u32_e32 v0, 0x27e00, v66
	v_lshl_add_u64 v[2:3], v[0:1], 1, s[6:7]
	v_mul_f32_e32 v0, 0xbfb8aa3b, v17
	v_exp_f32_e32 v0, v0
	global_store_short v[2:3], v4, off
	v_add_f32_e32 v0, 1.0, v0
	v_rcp_f32_e32 v0, v0
	s_nop 0
	v_mul_f32_e32 v0, v17, v0
	v_mul_f32_e32 v0, v33, v0
	v_cvt_pk_bf16_f32 v4, v0, s0
	v_add_u32_e32 v0, 0x28900, v66
	v_lshl_add_u64 v[2:3], v[0:1], 1, s[6:7]
	global_store_short v[2:3], v4, off
	v_readlane_b32 s16, v245, 0
	s_cmp_eq_u32 s16, 1
	s_cbranch_scc1 .Lgu1_done
	v_readlane_b32 s16, v243, 6
	s_add_i32 s15, s15, s16
	s_add_i32 s14, s14, s53
	s_cmpk_lt_u32 s14, 0x1600
	s_cbranch_scc1 .LBB0_419

; #define TIDX opaque_tid()
; template <int AI, int BI>
; DI void gemm_tile(const u16* __restrict__ A, int lda, const u16* __restrict__ B, int ldb, int nk, bool swap,
;                   f32x16 (&acc)[AI][BI], char* lds) {
;   const int tid = TIDX, lane = tid & 63, wid = tid >> 6;
;   gemm_stage<AI, BI>(A, lda, B, ldb, lds, tid);
;   asm volatile("s_waitcnt vmcnt(0)" ::: "memory");
;   __syncthreads();
; template <int AI, int BI>
; DI void dn_tile(const Params& p, char* wsb, int layer, int sub, bool final_out, int m0, int n0, char* lds) {
;   const u16* HID = (const u16*)(wsb + OFF_HID);
;   const u16* W = (const u16*)(wsb + OFF_W) + (sub ? W_D1 : W_D0);
;   float* xs = (float*)(wsb + OFF_XS);
;   const float* mods = (const float*)(wsb + OFF_MODS) + (size_t)layer * 9 * 9216;
;   const int lane = TIDX & 63, wid = TIDX >> 6, wa = wid >> 1, wb = wid & 1, r = lane & 31, h = lane >> 5;
;   f32x16 acc[AI][BI]; zero_acc<AI, BI>(acc);
;   gemm_tile<AI, BI>(HID + (size_t)m0 * 2816, 2816, W + (size_t)n0 * 2816, 2816, 44, false, acc, lds);
.LBB0_475:
	s_bfe_u32 s10, s34, 0x40006
	s_mul_i32 s10, s10, 0x580000
	v_readlane_b32 s11, v243, 15
	s_add_i32 s37, s11, s10
	s_lshr_b32 s10, s34, 3
	s_and_b32 s10, s10, 0x78
	s_and_b32 s11, s34, 7
	v_mov_b32_e32 v82, v178
	v_mov_b32_e32 v83, v178
	v_mov_b32_e32 v6, v178
	s_or_b32 s36, s10, s11
	s_lshl_b32 s10, s34, 4
	s_and_b32 s35, s10, 0x380
	v_lshrrev_b32_e32 v7, 4, v6
	s_mul_i32 s10, s36, 0xb0000
	v_xor_b32_e32 v0, v7, v6
	s_add_u32 s10, s14, s10
	v_lshlrev_b32_e32 v0, 4, v0
	s_addc_u32 s11, s15, 0
	v_and_b32_e32 v0, 0x70, v0
	v_lshl_add_u64 v[2:3], s[10:11], 0, v[0:1]
	v_ashrrev_i32_e32 v8, 3, v6
	v_mad_i64_i32 v[4:5], s[10:11], v8, s48, v[2:3]
	v_lshlrev_b32_e32 v85, 4, v6
	v_add_u32_e32 v9, 0x100, v6
	v_readfirstlane_b32 s10, v85
	s_mov_b32 m0, s10
	v_ashrrev_i32_e32 v10, 3, v9
	global_load_lds_dwordx4 v[4:5], off
	v_mad_i64_i32 v[4:5], s[10:11], v10, s48, v[2:3]
	v_lshlrev_b32_e32 v86, 4, v9
	v_add_u32_e32 v9, 0x200, v6
	v_readfirstlane_b32 s10, v86
	s_mov_b32 m0, s10
	v_ashrrev_i32_e32 v11, 3, v9
	global_load_lds_dwordx4 v[4:5], off
	v_mad_i64_i32 v[4:5], s[10:11], v11, s48, v[2:3]
	v_lshlrev_b32_e32 v88, 4, v9
	s_mul_i32 s40, s35, 0x1600
	v_readfirstlane_b32 s10, v88
	s_mov_b32 m0, s10
	s_add_u32 s40, s16, s40
	global_load_lds_dwordx4 v[4:5], off
	v_add_u32_e32 v4, 0x300, v6
	v_ashrrev_i32_e32 v9, 3, v4
	v_mad_i64_i32 v[2:3], s[10:11], v9, s48, v[2:3]
	v_lshlrev_b32_e32 v89, 4, v4
	s_addc_u32 s41, s17, 0
	v_readfirstlane_b32 s10, v89
	s_mov_b32 m0, s10
	s_nop 0
	global_load_lds_dwordx4 v[2:3], off
	v_lshl_add_u64 v[2:3], s[40:41], 0, v[0:1]
	v_mad_i64_i32 v[4:5], s[10:11], v8, s48, v[2:3]
	v_add_u32_e32 v0, 0x4000, v85
	s_nop 0
	v_readfirstlane_b32 s10, v0
	s_mov_b32 m0, s10
	v_add_u32_e32 v0, 0x4000, v86
	global_load_lds_dwordx4 v[4:5], off
	v_mad_i64_i32 v[4:5], s[10:11], v10, s48, v[2:3]
	v_readfirstlane_b32 s10, v0
	s_mov_b32 m0, s10
	v_add_u32_e32 v0, 0x4000, v88
	global_load_lds_dwordx4 v[4:5], off
	v_mad_i64_i32 v[4:5], s[10:11], v11, s48, v[2:3]
	v_readfirstlane_b32 s10, v0
	s_mov_b32 m0, s10
	v_mad_i64_i32 v[2:3], s[10:11], v9, s48, v[2:3]
	v_add_u32_e32 v0, 0x4000, v89
	global_load_lds_dwordx4 v[4:5], off
	v_readfirstlane_b32 s10, v0
	s_mov_b32 m0, s10
	v_and_b32_e32 v0, 31, v6
	global_load_lds_dwordx4 v[2:3], off
	v_lshrrev_b32_e32 v4, 1, v6
	s_mov_b32 s10, 0x1ffffc0
	v_and_or_b32 v0, v4, s10, v0
	v_lshrrev_b32_e32 v2, 5, v6
	v_bfe_u32 v5, v6, 1, 3
	v_lshlrev_b32_e32 v91, 7, v0
	v_lshlrev_b32_e32 v0, 7, v6
	v_bfe_u32 v3, v6, 5, 1
	v_and_b32_e32 v92, 0x2f80, v0
	v_bitop3_b32 v0, v2, v5, 1 bitop3:0x6c
	v_lshlrev_b32_e32 v90, 4, v0
	v_bitop3_b32 v0, v3, v5, 2 bitop3:0x36
	v_lshlrev_b32_e32 v87, 4, v0
	v_bitop3_b32 v0, v3, v5, 4 bitop3:0x36
	v_lshlrev_b32_e32 v84, 4, v0
	v_bitop3_b32 v0, v3, v5, 6 bitop3:0x36
	v_mad_i64_i32 v[2:3], s[10:11], v8, s48, 0
	v_bitop3_b32 v4, v7, 7, v6 bitop3:0x48
	v_lshlrev_b32_e32 v12, 4, v4
	s_add_u32 s10, s28, s37
	v_mad_i64_i32 v[4:5], s[40:41], v10, s48, 0
	v_mad_i64_i32 v[6:7], s[40:41], v11, s48, 0
	v_mad_i64_i32 v[8:9], s[40:41], v9, s48, 0
	v_or_b32_e32 v2, v2, v12
	s_addc_u32 s11, s29, 0
	v_or_b32_e32 v4, v4, v12
	v_or_b32_e32 v6, v6, v12
	v_or_b32_e32 v8, v8, v12
	s_bfe_u32 s37, s34, 0x30003
	v_lshl_add_u64 v[66:67], s[10:11], 0, v[2:3]
	v_lshl_add_u64 v[68:69], s[10:11], 0, v[4:5]
	v_lshl_add_u64 v[70:71], s[10:11], 0, v[6:7]
	v_lshl_add_u64 v[72:73], s[10:11], 0, v[8:9]
	v_mad_u64_u32 v[2:3], s[10:11], s37, v193, v[2:3]
	v_lshl_add_u64 v[74:75], s[8:9], 0, v[2:3]
	v_mad_u64_u32 v[2:3], s[10:11], s37, v193, v[4:5]
	v_lshl_add_u64 v[76:77], s[8:9], 0, v[2:3]
	v_mad_u64_u32 v[2:3], s[10:11], s37, v193, v[6:7]
	s_waitcnt vmcnt(0)
	v_lshl_add_u64 v[78:79], s[8:9], 0, v[2:3]
	v_mad_u64_u32 v[2:3], s[10:11], s37, v193, v[8:9]
	v_lshl_add_u64 v[80:81], s[8:9], 0, v[2:3]
	v_mov_b32_e32 v2, 0
	v_lshlrev_b32_e32 v0, 4, v0
	s_mov_b64 s[10:11], 0
	s_mov_b32 s37, 0x8000
	v_mov_b32_e32 v3, v2
	v_mov_b32_e32 v4, v2
	v_mov_b32_e32 v5, v2
	v_mov_b32_e32 v6, v2
	v_mov_b32_e32 v7, v2
	v_mov_b32_e32 v8, v2
	v_mov_b32_e32 v9, v2
	v_mov_b32_e32 v10, v2
	v_mov_b32_e32 v11, v2
	v_mov_b32_e32 v12, v2
	v_mov_b32_e32 v13, v2
	v_mov_b32_e32 v14, v2
	v_mov_b32_e32 v15, v2
	v_mov_b32_e32 v16, v2
	v_mov_b32_e32 v17, v2
	v_mov_b32_e32 v34, v2
	v_mov_b32_e32 v35, v2
	v_mov_b32_e32 v36, v2
	v_mov_b32_e32 v37, v2
	v_mov_b32_e32 v38, v2
	v_mov_b32_e32 v39, v2
	v_mov_b32_e32 v40, v2
	v_mov_b32_e32 v41, v2
	v_mov_b32_e32 v42, v2
	v_mov_b32_e32 v43, v2
	v_mov_b32_e32 v44, v2
	v_mov_b32_e32 v45, v2
	v_mov_b32_e32 v46, v2
	v_mov_b32_e32 v47, v2
	v_mov_b32_e32 v48, v2
	v_mov_b32_e32 v49, v2
	v_mov_b32_e32 v18, v2
	v_mov_b32_e32 v19, v2
	v_mov_b32_e32 v20, v2
	v_mov_b32_e32 v21, v2
	v_mov_b32_e32 v22, v2
	v_mov_b32_e32 v23, v2
	v_mov_b32_e32 v24, v2
	v_mov_b32_e32 v25, v2
	v_mov_b32_e32 v26, v2
	v_mov_b32_e32 v27, v2
	v_mov_b32_e32 v28, v2
	v_mov_b32_e32 v29, v2
	v_mov_b32_e32 v30, v2
	v_mov_b32_e32 v31, v2
	v_mov_b32_e32 v32, v2
	v_mov_b32_e32 v33, v2
	v_mov_b32_e32 v50, v2
	v_mov_b32_e32 v51, v2
	v_mov_b32_e32 v52, v2
	v_mov_b32_e32 v53, v2
	v_mov_b32_e32 v54, v2
	v_mov_b32_e32 v55, v2
	v_mov_b32_e32 v56, v2
	v_mov_b32_e32 v57, v2
	v_mov_b32_e32 v58, v2
	v_mov_b32_e32 v59, v2
	v_mov_b32_e32 v60, v2
	v_mov_b32_e32 v61, v2
	v_mov_b32_e32 v62, v2
	v_mov_b32_e32 v63, v2
	v_mov_b32_e32 v64, v2
	v_mov_b32_e32 v65, v2
	s_waitcnt vmcnt(0) lgkmcnt(0)
	s_barrier

; #define TIDX opaque_tid()
; template <int AI, int BI>
; DI void gemm_tile(const u16* __restrict__ A, int lda, const u16* __restrict__ B, int ldb, int nk, bool swap,
;                   f32x16 (&acc)[AI][BI], char* lds) {
;   const int tid = TIDX, lane = tid & 63, wid = tid >> 6;
;   gemm_stage<AI, BI>(A, lda, B, ldb, lds, tid);
;   asm volatile("s_waitcnt vmcnt(0)" ::: "memory");
;   __syncthreads();
; DI void phase_in(const Params& p, char* wsb, int layer, char* lds) {
;     ...
;   for (int rnd = 0; next_tile(rnd, 144, 54, mt, nt); ++rnd) {
;     const int m0 = mt * 128, n0 = nt * 128;
;     if (layer == 3 && m0 >= TL && !(n0 == 2048 || n0 == 2176 || (n0 >= 2816 && n0 < 3840))) continue;
;     const bool swap = n0 < 3840;
;     f32x16 acc[2][2]; zero_acc<2, 2>(acc);
;     gemm_tile<2, 2>(H + (size_t)m0 * 1024, 1024, W + (size_t)n0 * 1024, 1024, 16, swap, acc, lds);
.LBB0_589:
	s_cmpk_gt_i32 s62, 0x7f
	v_readlane_b32 s6, v242, 9
	s_cselect_b64 s[8:9], -1, 0
	s_cmpk_lt_i32 s62, 0x80
	v_readlane_b32 s7, v242, 10
	s_cselect_b64 s[52:53], -1, 0
	s_and_b64 s[6:7], s[6:7], s[8:9]
	s_and_b32 s10, s61, -2
	s_cmp_lg_u32 s10, 16
	s_cselect_b64 s[10:11], -1, 0
	s_sub_i32 s12, s61, 30
	s_cmp_lt_u32 s12, -8
	s_cselect_b64 s[12:13], -1, 0
	s_and_b64 s[10:11], s[10:11], s[12:13]
	s_and_b64 s[6:7], s[6:7], s[10:11]
	s_and_b64 vcc, exec, s[6:7]
	s_cbranch_vccnz .LBB0_584
	s_lshl_b32 s6, s62, 7
	s_lshl_b32 s50, s61, 7
	s_cmp_gt_i32 s61, 29
	v_mov_b32_e32 v14, v178
	s_cselect_b64 s[10:11], -1, 0
	s_ashr_i32 s7, s6, 31
	s_lshl_b64 s[54:55], s[6:7], 11
	v_lshrrev_b32_e32 v15, 4, v14
	v_xor_b32_e32 v0, v15, v14
	s_add_u32 s56, s29, s54
	v_lshlrev_b32_e32 v0, 4, v0
	v_ashrrev_i32_e32 v4, 3, v14
	s_addc_u32 s57, s34, s55
	v_and_b32_e32 v0, 0x70, v0
	v_ashrrev_i32_e32 v5, 31, v4
	v_lshlrev_b32_e32 v94, 4, v14
	v_lshl_add_u64 v[2:3], s[56:57], 0, v[0:1]
	v_lshlrev_b64 v[4:5], 11, v[4:5]
	v_readfirstlane_b32 s7, v94
	v_lshl_add_u64 v[6:7], v[2:3], 0, v[4:5]
	s_mov_b32 m0, s7
	v_add_u32_e32 v10, 0x100, v14
	global_load_lds_dwordx4 v[6:7], off
	v_ashrrev_i32_e32 v6, 3, v10
	v_ashrrev_i32_e32 v7, 31, v6
	v_lshlrev_b32_e32 v95, 4, v10
	v_lshlrev_b64 v[6:7], 11, v[6:7]
	v_readfirstlane_b32 s7, v95
	v_lshl_add_u64 v[8:9], v[2:3], 0, v[6:7]
	s_mov_b32 m0, s7
	v_add_u32_e32 v12, 0x200, v14
	global_load_lds_dwordx4 v[8:9], off
	v_ashrrev_i32_e32 v8, 3, v12
	v_ashrrev_i32_e32 v9, 31, v8
	v_lshlrev_b32_e32 v96, 4, v12
	v_lshlrev_b64 v[8:9], 11, v[8:9]
	v_readfirstlane_b32 s7, v96
	v_lshl_add_u64 v[10:11], v[2:3], 0, v[8:9]
	s_mov_b32 m0, s7
	v_add_u32_e32 v12, 0x300, v14
	s_ashr_i32 s51, s50, 31
	global_load_lds_dwordx4 v[10:11], off
	v_ashrrev_i32_e32 v10, 3, v12
	s_lshl_b64 s[12:13], s[50:51], 11
	v_ashrrev_i32_e32 v11, 31, v10
	v_lshlrev_b32_e32 v98, 4, v12
	s_add_u32 s58, s35, s12
	v_lshlrev_b64 v[10:11], 11, v[10:11]
	v_readfirstlane_b32 s7, v98
	s_addc_u32 s59, s60, s13
	v_lshl_add_u64 v[2:3], v[2:3], 0, v[10:11]
	s_mov_b32 m0, s7
	s_cmp_lt_i32 s61, 30
	global_load_lds_dwordx4 v[2:3], off
	v_lshl_add_u64 v[2:3], s[58:59], 0, v[0:1]
	v_add_u32_e32 v0, 0x4000, v94
	v_lshl_add_u64 v[12:13], v[2:3], 0, v[4:5]
	v_readfirstlane_b32 s7, v0
	v_add_u32_e32 v0, 0x4000, v95
	s_mov_b32 m0, s7
	v_readfirstlane_b32 s7, v0
	v_add_u32_e32 v0, 0x4000, v96
	global_load_lds_dwordx4 v[12:13], off
	v_lshl_add_u64 v[12:13], v[2:3], 0, v[6:7]
	s_mov_b32 m0, s7
	v_readfirstlane_b32 s7, v0
	v_add_u32_e32 v0, 0x4000, v98
	global_load_lds_dwordx4 v[12:13], off
	v_lshl_add_u64 v[12:13], v[2:3], 0, v[8:9]
	s_mov_b32 m0, s7
	v_readfirstlane_b32 s7, v0
	global_load_lds_dwordx4 v[12:13], off
	v_lshl_add_u64 v[2:3], v[2:3], 0, v[10:11]
	s_mov_b32 m0, s7
	v_and_b32_e32 v0, 31, v14
	global_load_lds_dwordx4 v[2:3], off
	v_lshrrev_b32_e32 v12, 1, v14
	v_and_or_b32 v0, v12, s63, v0
	v_lshrrev_b32_e32 v2, 5, v14
	v_bfe_u32 v13, v14, 1, 3
	v_lshlrev_b32_e32 v102, 7, v0
	v_lshlrev_b32_e32 v0, 7, v14
	v_bfe_u32 v3, v14, 5, 1
	v_and_b32_e32 v100, 0x2f80, v0
	v_bitop3_b32 v0, v2, v13, 1 bitop3:0x6c
	v_lshlrev_b32_e32 v101, 4, v0
	v_bitop3_b32 v0, v3, v13, 2 bitop3:0x36
	v_lshlrev_b32_e32 v99, 4, v0
	v_bitop3_b32 v0, v3, v13, 4 bitop3:0x36
	v_bitop3_b32 v12, v15, 7, v14 bitop3:0x48
	v_lshlrev_b32_e32 v97, 4, v0
	v_bitop3_b32 v0, v3, v13, 6 bitop3:0x36
	v_lshl_add_u64 v[2:3], v[4:5], 0, s[54:55]
	v_lshlrev_b32_e32 v12, 4, v12
	v_or_b32_e32 v2, v2, v12
	v_lshl_add_u64 v[78:79], s[46:47], 0, v[2:3]
	v_lshl_add_u64 v[2:3], v[6:7], 0, s[54:55]
	v_or_b32_e32 v2, v2, v12
	v_lshl_add_u64 v[80:81], s[46:47], 0, v[2:3]
	v_lshl_add_u64 v[2:3], v[8:9], 0, s[54:55]
	v_or_b32_e32 v2, v2, v12
	v_lshl_add_u64 v[82:83], s[46:47], 0, v[2:3]
	v_lshl_add_u64 v[2:3], v[10:11], 0, s[54:55]
	v_or_b32_e32 v2, v2, v12
	v_lshl_add_u64 v[84:85], s[46:47], 0, v[2:3]
	v_lshl_add_u64 v[2:3], v[4:5], 0, s[12:13]
	v_or_b32_e32 v2, v2, v12
	v_lshl_add_u64 v[86:87], s[48:49], 0, v[2:3]
	v_lshl_add_u64 v[2:3], v[6:7], 0, s[12:13]
	v_or_b32_e32 v2, v2, v12
	v_lshl_add_u64 v[88:89], s[48:49], 0, v[2:3]
	v_lshl_add_u64 v[2:3], v[8:9], 0, s[12:13]
	v_or_b32_e32 v2, v2, v12
	v_lshl_add_u64 v[90:91], s[48:49], 0, v[2:3]
	v_lshl_add_u64 v[2:3], v[10:11], 0, s[12:13]
	s_waitcnt vmcnt(0)
	v_or_b32_e32 v2, v2, v12
	v_lshl_add_u64 v[92:93], s[48:49], 0, v[2:3]
	v_mov_b32_e32 v2, 0
	s_cselect_b32 s51, 0x4000, 0
	s_cselect_b32 s7, 0, 0x4000
	v_lshlrev_b32_e32 v0, 4, v0
	s_mov_b64 s[12:13], 0
	s_mov_b32 s54, 0x8000
	v_mov_b32_e32 v3, v2
	v_mov_b32_e32 v4, v2
	v_mov_b32_e32 v5, v2
	v_mov_b32_e32 v6, v2
	v_mov_b32_e32 v7, v2
	v_mov_b32_e32 v8, v2
	v_mov_b32_e32 v9, v2
	v_mov_b32_e32 v10, v2
	v_mov_b32_e32 v11, v2
	v_mov_b32_e32 v12, v2
	v_mov_b32_e32 v13, v2
	v_mov_b32_e32 v14, v2
	v_mov_b32_e32 v15, v2
	v_mov_b32_e32 v16, v2
	v_mov_b32_e32 v17, v2
	v_mov_b32_e32 v34, v2
	v_mov_b32_e32 v35, v2
	v_mov_b32_e32 v36, v2
	v_mov_b32_e32 v37, v2
	v_mov_b32_e32 v38, v2
	v_mov_b32_e32 v39, v2
	v_mov_b32_e32 v40, v2
	v_mov_b32_e32 v41, v2
	v_mov_b32_e32 v42, v2
	v_mov_b32_e32 v43, v2
	v_mov_b32_e32 v44, v2
	v_mov_b32_e32 v45, v2
	v_mov_b32_e32 v46, v2
	v_mov_b32_e32 v47, v2
	v_mov_b32_e32 v48, v2
	v_mov_b32_e32 v49, v2
	v_mov_b32_e32 v18, v2
	v_mov_b32_e32 v19, v2
	v_mov_b32_e32 v20, v2
	v_mov_b32_e32 v21, v2
	v_mov_b32_e32 v22, v2
	v_mov_b32_e32 v23, v2
	v_mov_b32_e32 v24, v2
	v_mov_b32_e32 v25, v2
	v_mov_b32_e32 v26, v2
	v_mov_b32_e32 v27, v2
	v_mov_b32_e32 v28, v2
	v_mov_b32_e32 v29, v2
	v_mov_b32_e32 v30, v2
	v_mov_b32_e32 v31, v2
	v_mov_b32_e32 v32, v2
	v_mov_b32_e32 v33, v2
	v_mov_b32_e32 v50, v2
	v_mov_b32_e32 v51, v2
	v_mov_b32_e32 v52, v2
	v_mov_b32_e32 v53, v2
	v_mov_b32_e32 v54, v2
	v_mov_b32_e32 v55, v2
	v_mov_b32_e32 v56, v2
	v_mov_b32_e32 v57, v2
	v_mov_b32_e32 v58, v2
	v_mov_b32_e32 v59, v2
	v_mov_b32_e32 v60, v2
	v_mov_b32_e32 v61, v2
	v_mov_b32_e32 v62, v2
	v_mov_b32_e32 v63, v2
	v_mov_b32_e32 v64, v2
	v_mov_b32_e32 v65, v2
	s_waitcnt vmcnt(0) lgkmcnt(0)
	s_barrier

; #define MFMA(a, b, c) __builtin_amdgcn_mfma_f32_32x32x16_bf16((a), (b), (c), 0, 0, 0)
; #define TIDX opaque_tid()
; template <int AI, int BI>
; DI void gemm_tile(const u16* __restrict__ A, int lda, const u16* __restrict__ B, int ldb, int nk, bool swap,
;                   f32x16 (&acc)[AI][BI], char* lds) {
;   const int tid = TIDX, lane = tid & 63, wid = tid >> 6;
;   gemm_stage<AI, BI>(A, lda, B, ldb, lds, tid);
;   asm volatile("s_waitcnt vmcnt(0)" ::: "memory");
;   __syncthreads();
;   const int wa = wid >> 1, wb = wid & 1, r = lane & 31, h = lane >> 5, sw = (r >> 1) & 7;
;   const int offA = (swap ? 16384 : 0) + (wa * 32 * AI + r) * 128;
;   const int offB = (swap ? 0 : 16384) + (wb * 32 * BI + r) * 128;
;   for (int kt = 0; kt < nk; ++kt) {
;     const char* cur = lds + (kt & 1) * 32768;
;     if (kt + 1 < nk) gemm_stage<AI, BI>(A + (kt + 1) * 64, lda, B + (kt + 1) * 64, ldb, lds + ((kt + 1) & 1) * 32768, tid);
; #pragma unroll
;     for (int ks = 0; ks < 4; ++ks) {
;       const int co = ((ks * 2 + h) ^ sw) << 4;
;       s16x8 fa[AI], fb[BI];
; #pragma unroll
;       for (int i = 0; i < AI; ++i) fa[i] = *(const s16x8*)(cur + offA + i * 4096 + co);
; #pragma unroll
;       for (int i = 0; i < BI; ++i) fb[i] = *(const s16x8*)(cur + offB + i * 4096 + co);
; #pragma unroll
;       for (int i = 0; i < AI; ++i)
; #pragma unroll
;         for (int j = 0; j < BI; ++j) acc[i][j] = MFMA(fa[i], fb[j], acc[i][j]);
.LBB0_1099:
	s_lshr_b32 s10, s34, 3
	s_and_b32 s10, s10, 0x78
	s_and_b32 s11, s34, 7
	s_or_b32 s10, s10, s11
	v_mov_b32_e32 v82, v178
	v_mov_b32_e32 v83, v178
	v_mov_b32_e32 v12, v178
	s_and_b32 s35, s29, 0x380
	s_lshl_b32 s11, s10, 18
	s_add_u32 s36, s14, s11
	v_lshrrev_b32_e32 v0, 4, v12
	v_xor_b32_e32 v0, v0, v12
	v_add_u32_e32 v8, 0x100, v12
	v_add_u32_e32 v10, 0x200, v12
	v_add_u32_e32 v13, 0x300, v12
	s_addc_u32 s37, s15, 0
	s_lshl_b32 s11, s35, 11
	v_lshlrev_b32_e32 v0, 4, v0
	v_ashrrev_i32_e32 v4, 3, v12
	v_ashrrev_i32_e32 v6, 3, v8
	v_lshlrev_b32_e32 v99, 4, v8
	v_ashrrev_i32_e32 v8, 3, v10
	v_lshlrev_b32_e32 v100, 4, v10
	v_ashrrev_i32_e32 v10, 3, v13
	s_add_u32 s40, s16, s11
	v_and_b32_e32 v0, 0x70, v0
	v_ashrrev_i32_e32 v5, 31, v4
	v_ashrrev_i32_e32 v7, 31, v6
	v_ashrrev_i32_e32 v9, 31, v8
	v_ashrrev_i32_e32 v11, 31, v10
	s_addc_u32 s41, s17, 0
	v_lshl_add_u64 v[2:3], s[36:37], 0, v[0:1]
	v_lshlrev_b64 v[4:5], 11, v[4:5]
	v_lshlrev_b32_e32 v96, 4, v12
	v_lshlrev_b64 v[6:7], 11, v[6:7]
	v_lshlrev_b64 v[8:9], 11, v[8:9]
	v_lshlrev_b64 v[10:11], 11, v[10:11]
	v_lshl_add_u64 v[66:67], v[2:3], 0, v[4:5]
	v_lshl_add_u64 v[68:69], v[2:3], 0, v[6:7]
	v_lshl_add_u64 v[70:71], v[2:3], 0, v[8:9]
	v_lshl_add_u64 v[72:73], v[2:3], 0, v[10:11]
	v_lshl_add_u64 v[2:3], s[40:41], 0, v[0:1]
	v_add_u32_e32 v0, 0x4000, v96
	v_readfirstlane_b32 s47, v96
	v_readfirstlane_b32 s36, v0
	v_add_u32_e32 v0, 0x4000, v99
	s_mov_b32 m0, s47
	v_readfirstlane_b32 s52, v99
	v_lshlrev_b32_e32 v101, 4, v13
	v_readfirstlane_b32 s37, v0
	v_add_u32_e32 v0, 0x4000, v100
	global_load_lds_dwordx4 v[66:67], off
	s_mov_b32 m0, s52
	v_readfirstlane_b32 s55, v100
	v_readfirstlane_b32 s40, v0
	v_add_u32_e32 v0, 0x4000, v101
	global_load_lds_dwordx4 v[68:69], off
	s_mov_b32 m0, s55
	v_readfirstlane_b32 s56, v101
	v_lshl_add_u64 v[74:75], v[2:3], 0, v[4:5]
	v_readfirstlane_b32 s41, v0
	v_and_b32_e32 v0, 31, v12
	v_lshrrev_b32_e32 v4, 1, v12
	global_load_lds_dwordx4 v[70:71], off
	s_mov_b32 m0, s56
	v_and_or_b32 v0, v4, s65, v0
	global_load_lds_dwordx4 v[72:73], off
	s_mov_b32 m0, s36
	v_lshl_add_u64 v[76:77], v[2:3], 0, v[6:7]
	v_lshl_add_u64 v[78:79], v[2:3], 0, v[8:9]
	v_lshl_add_u64 v[80:81], v[2:3], 0, v[10:11]
	v_lshrrev_b32_e32 v2, 5, v12
	v_bfe_u32 v5, v12, 1, 3
	v_lshlrev_b32_e32 v86, 7, v0
	v_lshlrev_b32_e32 v0, 7, v12
	global_load_lds_dwordx4 v[74:75], off
	s_mov_b32 m0, s37
	v_bfe_u32 v3, v12, 5, 1
	v_and_b32_e32 v88, 0x2f80, v0
	v_bitop3_b32 v0, v2, v5, 1 bitop3:0x6c
	global_load_lds_dwordx4 v[76:77], off
	s_mov_b32 m0, s40
	v_lshlrev_b32_e32 v10, 4, v0
	v_bitop3_b32 v0, v3, v5, 2 bitop3:0x36
	v_add_u32_e32 v91, 0x8000, v96
	global_load_lds_dwordx4 v[78:79], off
	s_mov_b32 m0, s41
	v_lshlrev_b32_e32 v85, 4, v0
	v_bitop3_b32 v0, v3, v5, 4 bitop3:0x36
	v_readfirstlane_b32 s46, v91
	v_add_u32_e32 v92, 0x8000, v99
	global_load_lds_dwordx4 v[80:81], off
	v_lshlrev_b32_e32 v87, 4, v0
	v_bitop3_b32 v0, v3, v5, 6 bitop3:0x36
	v_lshl_add_u64 v[2:3], v[66:67], 0, s[68:69]
	s_mov_b32 m0, s46
	v_readfirstlane_b32 s48, v92
	v_add_u32_e32 v93, 0x8000, v100
	s_waitcnt vmcnt(0)
	s_waitcnt vmcnt(0) lgkmcnt(0)
	s_barrier
	global_load_lds_dwordx4 v[2:3], off
	v_lshl_add_u64 v[2:3], v[68:69], 0, s[68:69]
	s_mov_b32 m0, s48
	v_readfirstlane_b32 s49, v93
	v_add_u32_e32 v94, 0x8000, v101
	global_load_lds_dwordx4 v[2:3], off
	v_lshl_add_u64 v[2:3], v[70:71], 0, s[68:69]
	s_mov_b32 m0, s49
	v_readfirstlane_b32 s50, v94
	v_add_u32_e32 v95, 0xc000, v96
	global_load_lds_dwordx4 v[2:3], off
	v_lshl_add_u64 v[2:3], v[72:73], 0, s[68:69]
	s_mov_b32 m0, s50
	v_readfirstlane_b32 s51, v95
	v_add_u32_e32 v97, 0xc000, v99
	global_load_lds_dwordx4 v[2:3], off
	v_lshl_add_u64 v[2:3], v[74:75], 0, s[68:69]
	s_mov_b32 m0, s51
	v_readfirstlane_b32 s53, v97
	v_add_u32_e32 v98, 0xc000, v100
	v_lshlrev_b32_e32 v118, 4, v0
	global_load_lds_dwordx4 v[2:3], off
	v_lshl_add_u64 v[2:3], v[76:77], 0, s[68:69]
	s_mov_b32 m0, s53
	v_readfirstlane_b32 s54, v98
	v_add_u32_e32 v0, 0xc000, v101
	global_load_lds_dwordx4 v[2:3], off
	v_lshl_add_u64 v[2:3], v[78:79], 0, s[68:69]
	s_mov_b32 m0, s54
	v_readfirstlane_b32 s11, v0
	global_load_lds_dwordx4 v[2:3], off
	v_lshl_add_u64 v[2:3], v[80:81], 0, s[68:69]
	s_mov_b32 m0, s11
	v_or_b32_e32 v0, v86, v10
	global_load_lds_dwordx4 v[2:3], off
	v_or_b32_e32 v84, v88, v10
	ds_read_b128 v[2:5], v0
	ds_read_b128 v[6:9], v0 offset:4096
	ds_read_b128 v[10:13], v84 offset:16384
	ds_read_b128 v[14:17], v84 offset:20480
	s_waitcnt lgkmcnt(0)
	v_mfma_f32_32x32x16_bf16 v[50:65], v[2:5], v[10:13], 0
	v_or_b32_e32 v89, v86, v85
	v_or_b32_e32 v90, v88, v85
	ds_read_b128 v[102:105], v89
	ds_read_b128 v[106:109], v89 offset:4096
	ds_read_b128 v[110:113], v90 offset:16384
	ds_read_b128 v[114:117], v90 offset:20480
	v_or_b32_e32 v85, v86, v87
	v_or_b32_e32 v87, v88, v87
	v_or_b32_e32 v86, v86, v118
	v_mfma_f32_32x32x16_bf16 v[18:33], v[2:5], v[14:17], 0
	v_or_b32_e32 v88, v88, v118
	s_mov_b32 m0, s47
	v_mfma_f32_32x32x16_bf16 v[34:49], v[6:9], v[10:13], 0
	v_mfma_f32_32x32x16_bf16 v[2:17], v[6:9], v[14:17], 0
	s_waitcnt lgkmcnt(1)
	v_mfma_f32_32x32x16_bf16 v[50:65], v[102:105], v[110:113], v[50:65]
	s_waitcnt lgkmcnt(0)
	v_mfma_f32_32x32x16_bf16 v[18:33], v[102:105], v[114:117], v[18:33]
	v_mfma_f32_32x32x16_bf16 v[34:49], v[106:109], v[110:113], v[34:49]
	v_mfma_f32_32x32x16_bf16 v[2:17], v[106:109], v[114:117], v[2:17]
	ds_read_b128 v[102:105], v85
	ds_read_b128 v[106:109], v85 offset:4096
	ds_read_b128 v[110:113], v87 offset:16384
	ds_read_b128 v[114:117], v87 offset:20480
	s_waitcnt lgkmcnt(1)
	v_mfma_f32_32x32x16_bf16 v[50:65], v[102:105], v[110:113], v[50:65]
	s_waitcnt lgkmcnt(0)
	v_mfma_f32_32x32x16_bf16 v[18:33], v[102:105], v[114:117], v[18:33]
	v_mfma_f32_32x32x16_bf16 v[34:49], v[106:109], v[110:113], v[34:49]
	v_mfma_f32_32x32x16_bf16 v[2:17], v[106:109], v[114:117], v[2:17]
	ds_read_b128 v[102:105], v86
	ds_read_b128 v[106:109], v86 offset:4096
	ds_read_b128 v[110:113], v88 offset:16384
	ds_read_b128 v[114:117], v88 offset:20480
	s_waitcnt vmcnt(0)
	s_waitcnt lgkmcnt(0)
	s_barrier
; #define MFMA(a, b, c) __builtin_amdgcn_mfma_f32_32x32x16_bf16((a), (b), (c), 0, 0, 0)
; template <int AI, int BI>
; DI void gemm_tile(const u16* __restrict__ A, int lda, const u16* __restrict__ B, int ldb, int nk, bool swap,
;                   f32x16 (&acc)[AI][BI], char* lds) {
;     ...
;   for (int kt = 0; kt < nk; ++kt) {
;     const char* cur = lds + (kt & 1) * 32768;
;     if (kt + 1 < nk) gemm_stage<AI, BI>(A + (kt + 1) * 64, lda, B + (kt + 1) * 64, ldb, lds + ((kt + 1) & 1) * 32768, tid);
; #pragma unroll
;     for (int ks = 0; ks < 4; ++ks) {
;       const int co = ((ks * 2 + h) ^ sw) << 4;
;       s16x8 fa[AI], fb[BI];
; #pragma unroll
;       for (int i = 0; i < AI; ++i) fa[i] = *(const s16x8*)(cur + offA + i * 4096 + co);
; #pragma unroll
;       for (int i = 0; i < BI; ++i) fb[i] = *(const s16x8*)(cur + offB + i * 4096 + co);
; #pragma unroll
;       for (int i = 0; i < AI; ++i)
; #pragma unroll
;         for (int j = 0; j < BI; ++j) acc[i][j] = MFMA(fa[i], fb[j], acc[i][j]);
;     }
;     asm volatile("s_waitcnt vmcnt(0)" ::: "memory");
;     __syncthreads();
;   }
	v_mfma_f32_32x32x16_bf16 v[50:65], v[102:105], v[110:113], v[50:65]
	v_mfma_f32_32x32x16_bf16 v[18:33], v[102:105], v[114:117], v[18:33]
	v_lshl_add_u64 v[102:103], v[66:67], 0, s[4:5]
	global_load_lds_dwordx4 v[102:103], off
	v_lshl_add_u64 v[102:103], v[68:69], 0, s[4:5]
	s_mov_b32 m0, s52
	s_nop 0
	global_load_lds_dwordx4 v[102:103], off
	v_lshl_add_u64 v[102:103], v[70:71], 0, s[4:5]
	s_mov_b32 m0, s55
	v_mfma_f32_32x32x16_bf16 v[34:49], v[106:109], v[110:113], v[34:49]
	global_load_lds_dwordx4 v[102:103], off
	v_lshl_add_u64 v[102:103], v[72:73], 0, s[4:5]
	s_mov_b32 m0, s56
	s_nop 0
	global_load_lds_dwordx4 v[102:103], off
	v_lshl_add_u64 v[102:103], v[74:75], 0, s[4:5]
	s_mov_b32 m0, s36
	v_mfma_f32_32x32x16_bf16 v[2:17], v[106:109], v[114:117], v[2:17]
	global_load_lds_dwordx4 v[102:103], off
	v_lshl_add_u64 v[102:103], v[76:77], 0, s[4:5]
	s_mov_b32 m0, s37
	s_nop 0
	global_load_lds_dwordx4 v[102:103], off
	v_lshl_add_u64 v[102:103], v[78:79], 0, s[4:5]
	s_mov_b32 m0, s40
	s_nop 0
	global_load_lds_dwordx4 v[102:103], off
	v_lshl_add_u64 v[102:103], v[80:81], 0, s[4:5]
	s_mov_b32 m0, s41
	s_nop 0
	global_load_lds_dwordx4 v[102:103], off
	ds_read_b128 v[102:105], v0 offset:32768
	ds_read_b128 v[106:109], v0 offset:36864
	ds_read_b128 v[110:113], v84 offset:49152
	ds_read_b128 v[114:117], v84 offset:53248
	s_waitcnt lgkmcnt(0)
	v_mfma_f32_32x32x16_bf16 v[50:65], v[102:105], v[110:113], v[50:65]
	s_mov_b32 m0, s46
	v_mfma_f32_32x32x16_bf16 v[18:33], v[102:105], v[114:117], v[18:33]
	v_mfma_f32_32x32x16_bf16 v[34:49], v[106:109], v[110:113], v[34:49]
	v_mfma_f32_32x32x16_bf16 v[2:17], v[106:109], v[114:117], v[2:17]
	ds_read_b128 v[102:105], v89 offset:32768
	ds_read_b128 v[106:109], v89 offset:36864
	ds_read_b128 v[110:113], v90 offset:49152
	ds_read_b128 v[114:117], v90 offset:53248
	s_waitcnt lgkmcnt(1)
	v_mfma_f32_32x32x16_bf16 v[50:65], v[102:105], v[110:113], v[50:65]
	s_waitcnt lgkmcnt(0)
	v_mfma_f32_32x32x16_bf16 v[18:33], v[102:105], v[114:117], v[18:33]
	v_mfma_f32_32x32x16_bf16 v[34:49], v[106:109], v[110:113], v[34:49]
	v_mfma_f32_32x32x16_bf16 v[2:17], v[106:109], v[114:117], v[2:17]
	ds_read_b128 v[102:105], v85 offset:32768
	ds_read_b128 v[106:109], v85 offset:36864
	ds_read_b128 v[110:113], v87 offset:49152
	ds_read_b128 v[114:117], v87 offset:53248
	s_waitcnt lgkmcnt(1)
	v_mfma_f32_32x32x16_bf16 v[50:65], v[102:105], v[110:113], v[50:65]
	s_waitcnt lgkmcnt(0)
	v_mfma_f32_32x32x16_bf16 v[18:33], v[102:105], v[114:117], v[18:33]
	v_mfma_f32_32x32x16_bf16 v[34:49], v[106:109], v[110:113], v[34:49]
	v_mfma_f32_32x32x16_bf16 v[2:17], v[106:109], v[114:117], v[2:17]
	ds_read_b128 v[102:105], v86 offset:32768
	ds_read_b128 v[106:109], v86 offset:36864
	ds_read_b128 v[110:113], v88 offset:49152
	ds_read_b128 v[114:117], v88 offset:53248
	s_waitcnt vmcnt(0)
	s_waitcnt lgkmcnt(0)
	s_barrier
	v_mfma_f32_32x32x16_bf16 v[50:65], v[102:105], v[110:113], v[50:65]
	v_mfma_f32_32x32x16_bf16 v[18:33], v[102:105], v[114:117], v[18:33]
	v_lshl_add_u64 v[102:103], v[66:67], 0, s[70:71]
	global_load_lds_dwordx4 v[102:103], off
	v_lshl_add_u64 v[102:103], v[68:69], 0, s[70:71]
	s_mov_b32 m0, s48
	s_nop 0
	global_load_lds_dwordx4 v[102:103], off
	v_lshl_add_u64 v[102:103], v[70:71], 0, s[70:71]
	s_mov_b32 m0, s49
	v_mfma_f32_32x32x16_bf16 v[34:49], v[106:109], v[110:113], v[34:49]
	global_load_lds_dwordx4 v[102:103], off
	v_lshl_add_u64 v[102:103], v[72:73], 0, s[70:71]
	s_mov_b32 m0, s50
	s_nop 0
	global_load_lds_dwordx4 v[102:103], off
	v_lshl_add_u64 v[102:103], v[74:75], 0, s[70:71]
	s_mov_b32 m0, s51
	v_mfma_f32_32x32x16_bf16 v[2:17], v[106:109], v[114:117], v[2:17]
	global_load_lds_dwordx4 v[102:103], off
	v_lshl_add_u64 v[102:103], v[76:77], 0, s[70:71]
	s_mov_b32 m0, s53
	s_nop 0
	global_load_lds_dwordx4 v[102:103], off
	v_lshl_add_u64 v[102:103], v[78:79], 0, s[70:71]
	s_mov_b32 m0, s54
	s_nop 0
	global_load_lds_dwordx4 v[102:103], off
	v_lshl_add_u64 v[102:103], v[80:81], 0, s[70:71]
	s_mov_b32 m0, s11
	s_nop 0
	global_load_lds_dwordx4 v[102:103], off
	ds_read_b128 v[102:105], v0
	ds_read_b128 v[106:109], v0 offset:4096
	ds_read_b128 v[110:113], v84 offset:16384
	ds_read_b128 v[114:117], v84 offset:20480
	s_waitcnt lgkmcnt(0)
	v_mfma_f32_32x32x16_bf16 v[50:65], v[102:105], v[110:113], v[50:65]
	s_mov_b32 m0, s47
	v_mfma_f32_32x32x16_bf16 v[18:33], v[102:105], v[114:117], v[18:33]
	v_mfma_f32_32x32x16_bf16 v[34:49], v[106:109], v[110:113], v[34:49]
	v_mfma_f32_32x32x16_bf16 v[2:17], v[106:109], v[114:117], v[2:17]
	ds_read_b128 v[102:105], v89
	ds_read_b128 v[106:109], v89 offset:4096
	ds_read_b128 v[110:113], v90 offset:16384
	ds_read_b128 v[114:117], v90 offset:20480
	s_waitcnt lgkmcnt(1)
	v_mfma_f32_32x32x16_bf16 v[50:65], v[102:105], v[110:113], v[50:65]
	s_waitcnt lgkmcnt(0)
	v_mfma_f32_32x32x16_bf16 v[18:33], v[102:105], v[114:117], v[18:33]
	v_mfma_f32_32x32x16_bf16 v[34:49], v[106:109], v[110:113], v[34:49]
	v_mfma_f32_32x32x16_bf16 v[2:17], v[106:109], v[114:117], v[2:17]
	ds_read_b128 v[102:105], v85
	ds_read_b128 v[106:109], v85 offset:4096
	ds_read_b128 v[110:113], v87 offset:16384
	ds_read_b128 v[114:117], v87 offset:20480
	s_waitcnt lgkmcnt(1)
	v_mfma_f32_32x32x16_bf16 v[50:65], v[102:105], v[110:113], v[50:65]
	s_waitcnt lgkmcnt(0)
	v_mfma_f32_32x32x16_bf16 v[18:33], v[102:105], v[114:117], v[18:33]
	v_mfma_f32_32x32x16_bf16 v[34:49], v[106:109], v[110:113], v[34:49]
	v_mfma_f32_32x32x16_bf16 v[2:17], v[106:109], v[114:117], v[2:17]
	ds_read_b128 v[102:105], v86
	ds_read_b128 v[106:109], v86 offset:4096
	ds_read_b128 v[110:113], v88 offset:16384
	ds_read_b128 v[114:117], v88 offset:20480
	s_waitcnt vmcnt(0)
	s_waitcnt lgkmcnt(0)
	s_barrier
; #define MFMA(a, b, c) __builtin_amdgcn_mfma_f32_32x32x16_bf16((a), (b), (c), 0, 0, 0)
; template <int AI, int BI>
; DI void gemm_tile(const u16* __restrict__ A, int lda, const u16* __restrict__ B, int ldb, int nk, bool swap,
;                   f32x16 (&acc)[AI][BI], char* lds) {
;     ...
;   for (int kt = 0; kt < nk; ++kt) {
;     const char* cur = lds + (kt & 1) * 32768;
;     if (kt + 1 < nk) gemm_stage<AI, BI>(A + (kt + 1) * 64, lda, B + (kt + 1) * 64, ldb, lds + ((kt + 1) & 1) * 32768, tid);
; #pragma unroll
;     for (int ks = 0; ks < 4; ++ks) {
;       const int co = ((ks * 2 + h) ^ sw) << 4;
;       s16x8 fa[AI], fb[BI];
; #pragma unroll
;       for (int i = 0; i < AI; ++i) fa[i] = *(const s16x8*)(cur + offA + i * 4096 + co);
; #pragma unroll
;       for (int i = 0; i < BI; ++i) fb[i] = *(const s16x8*)(cur + offB + i * 4096 + co);
; #pragma unroll
;       for (int i = 0; i < AI; ++i)
; #pragma unroll
;         for (int j = 0; j < BI; ++j) acc[i][j] = MFMA(fa[i], fb[j], acc[i][j]);
;     }
;     asm volatile("s_waitcnt vmcnt(0)" ::: "memory");
;     __syncthreads();
;   }
	v_mfma_f32_32x32x16_bf16 v[50:65], v[102:105], v[110:113], v[50:65]
	v_mfma_f32_32x32x16_bf16 v[18:33], v[102:105], v[114:117], v[18:33]
	v_lshl_add_u64 v[102:103], v[66:67], 0, s[66:67]
	global_load_lds_dwordx4 v[102:103], off
	v_lshl_add_u64 v[102:103], v[68:69], 0, s[66:67]
	s_mov_b32 m0, s52
	s_nop 0
	global_load_lds_dwordx4 v[102:103], off
	v_lshl_add_u64 v[102:103], v[70:71], 0, s[66:67]
	s_mov_b32 m0, s55
	v_mfma_f32_32x32x16_bf16 v[34:49], v[106:109], v[110:113], v[34:49]
	global_load_lds_dwordx4 v[102:103], off
	v_lshl_add_u64 v[102:103], v[72:73], 0, s[66:67]
	s_mov_b32 m0, s56
	s_nop 0
	global_load_lds_dwordx4 v[102:103], off
	v_lshl_add_u64 v[102:103], v[74:75], 0, s[66:67]
	s_mov_b32 m0, s36
	v_mfma_f32_32x32x16_bf16 v[2:17], v[106:109], v[114:117], v[2:17]
	global_load_lds_dwordx4 v[102:103], off
	v_lshl_add_u64 v[102:103], v[76:77], 0, s[66:67]
	s_mov_b32 m0, s37
	s_nop 0
	global_load_lds_dwordx4 v[102:103], off
	v_lshl_add_u64 v[102:103], v[78:79], 0, s[66:67]
	s_mov_b32 m0, s40
	s_nop 0
	global_load_lds_dwordx4 v[102:103], off
	v_lshl_add_u64 v[102:103], v[80:81], 0, s[66:67]
	s_mov_b32 m0, s41
	s_nop 0
	global_load_lds_dwordx4 v[102:103], off
	ds_read_b128 v[102:105], v0 offset:32768
	ds_read_b128 v[106:109], v0 offset:36864
	ds_read_b128 v[110:113], v84 offset:49152
	ds_read_b128 v[114:117], v84 offset:53248
	s_waitcnt lgkmcnt(0)
	v_mfma_f32_32x32x16_bf16 v[50:65], v[102:105], v[110:113], v[50:65]
	s_mov_b32 m0, s46
	v_mfma_f32_32x32x16_bf16 v[18:33], v[102:105], v[114:117], v[18:33]
	v_mfma_f32_32x32x16_bf16 v[34:49], v[106:109], v[110:113], v[34:49]
	v_mfma_f32_32x32x16_bf16 v[2:17], v[106:109], v[114:117], v[2:17]
	ds_read_b128 v[102:105], v89 offset:32768
	ds_read_b128 v[106:109], v89 offset:36864
	ds_read_b128 v[110:113], v90 offset:49152
	ds_read_b128 v[114:117], v90 offset:53248
	s_waitcnt lgkmcnt(1)
	v_mfma_f32_32x32x16_bf16 v[50:65], v[102:105], v[110:113], v[50:65]
	s_waitcnt lgkmcnt(0)
	v_mfma_f32_32x32x16_bf16 v[18:33], v[102:105], v[114:117], v[18:33]
	v_mfma_f32_32x32x16_bf16 v[34:49], v[106:109], v[110:113], v[34:49]
	v_mfma_f32_32x32x16_bf16 v[2:17], v[106:109], v[114:117], v[2:17]
	ds_read_b128 v[102:105], v85 offset:32768
	ds_read_b128 v[106:109], v85 offset:36864
	ds_read_b128 v[110:113], v87 offset:49152
	ds_read_b128 v[114:117], v87 offset:53248
	s_waitcnt lgkmcnt(1)
	v_mfma_f32_32x32x16_bf16 v[50:65], v[102:105], v[110:113], v[50:65]
	s_waitcnt lgkmcnt(0)
	v_mfma_f32_32x32x16_bf16 v[18:33], v[102:105], v[114:117], v[18:33]
	v_mfma_f32_32x32x16_bf16 v[34:49], v[106:109], v[110:113], v[34:49]
	v_mfma_f32_32x32x16_bf16 v[2:17], v[106:109], v[114:117], v[2:17]
	ds_read_b128 v[102:105], v86 offset:32768
	ds_read_b128 v[106:109], v86 offset:36864
	ds_read_b128 v[110:113], v88 offset:49152
	ds_read_b128 v[114:117], v88 offset:53248
	s_waitcnt vmcnt(0)
	s_waitcnt lgkmcnt(0)
	s_barrier
	v_mfma_f32_32x32x16_bf16 v[50:65], v[102:105], v[110:113], v[50:65]
	v_mfma_f32_32x32x16_bf16 v[18:33], v[102:105], v[114:117], v[18:33]
	v_lshl_add_u64 v[102:103], v[66:67], 0, s[72:73]
	global_load_lds_dwordx4 v[102:103], off
	v_lshl_add_u64 v[102:103], v[68:69], 0, s[72:73]
	s_mov_b32 m0, s48
	s_nop 0
	global_load_lds_dwordx4 v[102:103], off
	v_lshl_add_u64 v[102:103], v[70:71], 0, s[72:73]
	s_mov_b32 m0, s49
	v_mfma_f32_32x32x16_bf16 v[34:49], v[106:109], v[110:113], v[34:49]
	global_load_lds_dwordx4 v[102:103], off
	v_lshl_add_u64 v[102:103], v[72:73], 0, s[72:73]
	s_mov_b32 m0, s50
	s_nop 0
	global_load_lds_dwordx4 v[102:103], off
	v_lshl_add_u64 v[102:103], v[74:75], 0, s[72:73]
	s_mov_b32 m0, s51
	v_mfma_f32_32x32x16_bf16 v[2:17], v[106:109], v[114:117], v[2:17]
	global_load_lds_dwordx4 v[102:103], off
	v_lshl_add_u64 v[102:103], v[76:77], 0, s[72:73]
	s_mov_b32 m0, s53
	s_nop 0
	global_load_lds_dwordx4 v[102:103], off
	v_lshl_add_u64 v[102:103], v[78:79], 0, s[72:73]
	s_mov_b32 m0, s54
	s_nop 0
	global_load_lds_dwordx4 v[102:103], off
	v_lshl_add_u64 v[102:103], v[80:81], 0, s[72:73]
	s_mov_b32 m0, s11
	s_nop 0
	global_load_lds_dwordx4 v[102:103], off
	ds_read_b128 v[102:105], v0
	ds_read_b128 v[106:109], v0 offset:4096
	ds_read_b128 v[110:113], v84 offset:16384
	ds_read_b128 v[114:117], v84 offset:20480
	s_waitcnt lgkmcnt(0)
	v_mfma_f32_32x32x16_bf16 v[50:65], v[102:105], v[110:113], v[50:65]
	s_mov_b32 m0, s47
	v_readfirstlane_b32 s47, v99
	v_mfma_f32_32x32x16_bf16 v[18:33], v[102:105], v[114:117], v[18:33]
	v_mfma_f32_32x32x16_bf16 v[34:49], v[106:109], v[110:113], v[34:49]
	v_mfma_f32_32x32x16_bf16 v[2:17], v[106:109], v[114:117], v[2:17]
	ds_read_b128 v[102:105], v89
	ds_read_b128 v[106:109], v89 offset:4096
	ds_read_b128 v[110:113], v90 offset:16384
	ds_read_b128 v[114:117], v90 offset:20480
	s_waitcnt lgkmcnt(1)
	v_mfma_f32_32x32x16_bf16 v[50:65], v[102:105], v[110:113], v[50:65]
	s_waitcnt lgkmcnt(0)
	v_mfma_f32_32x32x16_bf16 v[18:33], v[102:105], v[114:117], v[18:33]
	v_mfma_f32_32x32x16_bf16 v[34:49], v[106:109], v[110:113], v[34:49]
	v_mfma_f32_32x32x16_bf16 v[2:17], v[106:109], v[114:117], v[2:17]
	ds_read_b128 v[102:105], v85
	ds_read_b128 v[106:109], v85 offset:4096
	ds_read_b128 v[110:113], v87 offset:16384
	ds_read_b128 v[114:117], v87 offset:20480
	s_waitcnt lgkmcnt(1)
	v_mfma_f32_32x32x16_bf16 v[50:65], v[102:105], v[110:113], v[50:65]
	s_waitcnt lgkmcnt(0)
	v_mfma_f32_32x32x16_bf16 v[18:33], v[102:105], v[114:117], v[18:33]
	v_mfma_f32_32x32x16_bf16 v[34:49], v[106:109], v[110:113], v[34:49]
	v_mfma_f32_32x32x16_bf16 v[2:17], v[106:109], v[114:117], v[2:17]
	ds_read_b128 v[102:105], v86
	ds_read_b128 v[106:109], v86 offset:4096
	ds_read_b128 v[110:113], v88 offset:16384
	ds_read_b128 v[114:117], v88 offset:20480
	s_waitcnt vmcnt(0)
	s_waitcnt lgkmcnt(0)
	s_barrier
; #define MFMA(a, b, c) __builtin_amdgcn_mfma_f32_32x32x16_bf16((a), (b), (c), 0, 0, 0)
; template <int AI, int BI>
; DI void gemm_tile(const u16* __restrict__ A, int lda, const u16* __restrict__ B, int ldb, int nk, bool swap,
;                   f32x16 (&acc)[AI][BI], char* lds) {
;     ...
;   for (int kt = 0; kt < nk; ++kt) {
;     const char* cur = lds + (kt & 1) * 32768;
;     if (kt + 1 < nk) gemm_stage<AI, BI>(A + (kt + 1) * 64, lda, B + (kt + 1) * 64, ldb, lds + ((kt + 1) & 1) * 32768, tid);
; #pragma unroll
;     for (int ks = 0; ks < 4; ++ks) {
;       const int co = ((ks * 2 + h) ^ sw) << 4;
;       s16x8 fa[AI], fb[BI];
; #pragma unroll
;       for (int i = 0; i < AI; ++i) fa[i] = *(const s16x8*)(cur + offA + i * 4096 + co);
; #pragma unroll
;       for (int i = 0; i < BI; ++i) fb[i] = *(const s16x8*)(cur + offB + i * 4096 + co);
; #pragma unroll
;       for (int i = 0; i < AI; ++i)
; #pragma unroll
;         for (int j = 0; j < BI; ++j) acc[i][j] = MFMA(fa[i], fb[j], acc[i][j]);
;     }
;     asm volatile("s_waitcnt vmcnt(0)" ::: "memory");
;     __syncthreads();
;   }
	v_mfma_f32_32x32x16_bf16 v[50:65], v[102:105], v[110:113], v[50:65]
	v_mfma_f32_32x32x16_bf16 v[18:33], v[102:105], v[114:117], v[18:33]
	v_lshl_add_u64 v[102:103], v[66:67], 0, s[74:75]
	global_load_lds_dwordx4 v[102:103], off
	v_lshl_add_u64 v[102:103], v[68:69], 0, s[74:75]
	s_mov_b32 m0, s52
	v_readfirstlane_b32 s52, v93
	global_load_lds_dwordx4 v[102:103], off
	v_lshl_add_u64 v[102:103], v[70:71], 0, s[74:75]
	s_mov_b32 m0, s55
	v_mfma_f32_32x32x16_bf16 v[34:49], v[106:109], v[110:113], v[34:49]
	global_load_lds_dwordx4 v[102:103], off
	v_lshl_add_u64 v[102:103], v[72:73], 0, s[74:75]
	s_mov_b32 m0, s56
	v_readfirstlane_b32 s55, v97
	global_load_lds_dwordx4 v[102:103], off
	v_lshl_add_u64 v[102:103], v[74:75], 0, s[74:75]
	s_mov_b32 m0, s36
	v_mfma_f32_32x32x16_bf16 v[2:17], v[106:109], v[114:117], v[2:17]
	global_load_lds_dwordx4 v[102:103], off
	v_lshl_add_u64 v[102:103], v[76:77], 0, s[74:75]
	s_mov_b32 m0, s37
	v_readfirstlane_b32 s56, v98
	global_load_lds_dwordx4 v[102:103], off
	v_lshl_add_u64 v[102:103], v[78:79], 0, s[74:75]
	s_mov_b32 m0, s40
	s_nop 0
	global_load_lds_dwordx4 v[102:103], off
	v_lshl_add_u64 v[102:103], v[80:81], 0, s[74:75]
	s_mov_b32 m0, s41
	s_nop 0
	global_load_lds_dwordx4 v[102:103], off
	ds_read_b128 v[102:105], v0 offset:32768
	ds_read_b128 v[106:109], v0 offset:36864
	ds_read_b128 v[110:113], v84 offset:49152
	ds_read_b128 v[114:117], v84 offset:53248
	s_waitcnt lgkmcnt(0)
	v_mfma_f32_32x32x16_bf16 v[50:65], v[102:105], v[110:113], v[50:65]
	s_mov_b32 m0, s46
	v_readfirstlane_b32 s46, v96
	v_mfma_f32_32x32x16_bf16 v[18:33], v[102:105], v[114:117], v[18:33]
	v_mfma_f32_32x32x16_bf16 v[34:49], v[106:109], v[110:113], v[34:49]
	v_mfma_f32_32x32x16_bf16 v[2:17], v[106:109], v[114:117], v[2:17]
	ds_read_b128 v[102:105], v89 offset:32768
	ds_read_b128 v[106:109], v89 offset:36864
	ds_read_b128 v[110:113], v90 offset:49152
	ds_read_b128 v[114:117], v90 offset:53248
	s_waitcnt lgkmcnt(1)
	v_mfma_f32_32x32x16_bf16 v[50:65], v[102:105], v[110:113], v[50:65]
	s_waitcnt lgkmcnt(0)
	v_mfma_f32_32x32x16_bf16 v[18:33], v[102:105], v[114:117], v[18:33]
	v_mfma_f32_32x32x16_bf16 v[34:49], v[106:109], v[110:113], v[34:49]
	v_mfma_f32_32x32x16_bf16 v[2:17], v[106:109], v[114:117], v[2:17]
	ds_read_b128 v[102:105], v85 offset:32768
	ds_read_b128 v[106:109], v85 offset:36864
	ds_read_b128 v[110:113], v87 offset:49152
	ds_read_b128 v[114:117], v87 offset:53248
	s_waitcnt lgkmcnt(1)
	v_mfma_f32_32x32x16_bf16 v[50:65], v[102:105], v[110:113], v[50:65]
	s_waitcnt lgkmcnt(0)
	v_mfma_f32_32x32x16_bf16 v[18:33], v[102:105], v[114:117], v[18:33]
	v_mfma_f32_32x32x16_bf16 v[34:49], v[106:109], v[110:113], v[34:49]
	v_mfma_f32_32x32x16_bf16 v[2:17], v[106:109], v[114:117], v[2:17]
	ds_read_b128 v[102:105], v86 offset:32768
	ds_read_b128 v[106:109], v86 offset:36864
	ds_read_b128 v[110:113], v88 offset:49152
	ds_read_b128 v[114:117], v88 offset:53248
	s_waitcnt vmcnt(0)
	s_waitcnt lgkmcnt(0)
	s_barrier
	v_mfma_f32_32x32x16_bf16 v[50:65], v[102:105], v[110:113], v[50:65]
	v_mfma_f32_32x32x16_bf16 v[18:33], v[102:105], v[114:117], v[18:33]
	v_lshl_add_u64 v[102:103], v[66:67], 0, s[76:77]
	global_load_lds_dwordx4 v[102:103], off
	v_lshl_add_u64 v[102:103], v[68:69], 0, s[76:77]
	s_mov_b32 m0, s48
	v_readfirstlane_b32 s48, v100
	global_load_lds_dwordx4 v[102:103], off
	v_lshl_add_u64 v[102:103], v[70:71], 0, s[76:77]
	s_mov_b32 m0, s49
	v_mfma_f32_32x32x16_bf16 v[34:49], v[106:109], v[110:113], v[34:49]
	global_load_lds_dwordx4 v[102:103], off
	v_lshl_add_u64 v[102:103], v[72:73], 0, s[76:77]
	s_mov_b32 m0, s50
	v_readfirstlane_b32 s49, v101
	global_load_lds_dwordx4 v[102:103], off
	v_lshl_add_u64 v[102:103], v[74:75], 0, s[76:77]
	s_mov_b32 m0, s51
	v_mfma_f32_32x32x16_bf16 v[2:17], v[106:109], v[114:117], v[2:17]
	global_load_lds_dwordx4 v[102:103], off
	v_lshl_add_u64 v[102:103], v[76:77], 0, s[76:77]
	s_mov_b32 m0, s53
	v_lshl_add_u64 v[100:101], v[74:75], 0, s[80:81]
	global_load_lds_dwordx4 v[102:103], off
	v_lshl_add_u64 v[102:103], v[78:79], 0, s[76:77]
	s_mov_b32 m0, s54
	v_readfirstlane_b32 s50, v91
	global_load_lds_dwordx4 v[102:103], off
	v_lshl_add_u64 v[102:103], v[80:81], 0, s[76:77]
	s_mov_b32 m0, s11
	v_readfirstlane_b32 s51, v92
	global_load_lds_dwordx4 v[102:103], off
	ds_read_b128 v[102:105], v0
	ds_read_b128 v[106:109], v0 offset:4096
	ds_read_b128 v[110:113], v84 offset:16384
	ds_read_b128 v[114:117], v84 offset:20480
	s_waitcnt lgkmcnt(0)
	v_mfma_f32_32x32x16_bf16 v[50:65], v[102:105], v[110:113], v[50:65]
	s_mov_b32 m0, s46
	v_readfirstlane_b32 s53, v94
	v_lshl_add_u64 v[92:93], v[72:73], 0, s[82:83]
	v_readfirstlane_b32 s54, v95
	v_and_b32_e32 v91, 31, v82
	v_mfma_f32_32x32x16_bf16 v[18:33], v[102:105], v[114:117], v[18:33]
	v_mfma_f32_32x32x16_bf16 v[34:49], v[106:109], v[110:113], v[34:49]
	v_mfma_f32_32x32x16_bf16 v[2:17], v[106:109], v[114:117], v[2:17]
	ds_read_b128 v[102:105], v89
	ds_read_b128 v[106:109], v89 offset:4096
	ds_read_b128 v[110:113], v90 offset:16384
	ds_read_b128 v[114:117], v90 offset:20480
	s_waitcnt lgkmcnt(1)
	v_mfma_f32_32x32x16_bf16 v[50:65], v[102:105], v[110:113], v[50:65]
	s_waitcnt lgkmcnt(0)
	v_mfma_f32_32x32x16_bf16 v[18:33], v[102:105], v[114:117], v[18:33]
	v_mfma_f32_32x32x16_bf16 v[34:49], v[106:109], v[110:113], v[34:49]
	v_mfma_f32_32x32x16_bf16 v[2:17], v[106:109], v[114:117], v[2:17]
	ds_read_b128 v[102:105], v85
	ds_read_b128 v[106:109], v85 offset:4096
	ds_read_b128 v[110:113], v87 offset:16384
	ds_read_b128 v[114:117], v87 offset:20480
	s_waitcnt lgkmcnt(1)
	v_mfma_f32_32x32x16_bf16 v[50:65], v[102:105], v[110:113], v[50:65]
	s_waitcnt lgkmcnt(0)
	v_mfma_f32_32x32x16_bf16 v[18:33], v[102:105], v[114:117], v[18:33]
	v_mfma_f32_32x32x16_bf16 v[34:49], v[106:109], v[110:113], v[34:49]
	v_mfma_f32_32x32x16_bf16 v[2:17], v[106:109], v[114:117], v[2:17]
	ds_read_b128 v[102:105], v86
	ds_read_b128 v[106:109], v86 offset:4096
	ds_read_b128 v[110:113], v88 offset:16384
	ds_read_b128 v[114:117], v88 offset:20480
	s_waitcnt vmcnt(0)
	s_waitcnt lgkmcnt(0)
	s_barrier
; #define MFMA(a, b, c) __builtin_amdgcn_mfma_f32_32x32x16_bf16((a), (b), (c), 0, 0, 0)
; template <int AI, int BI>
; DI void gemm_tile(const u16* __restrict__ A, int lda, const u16* __restrict__ B, int ldb, int nk, bool swap,
;                   f32x16 (&acc)[AI][BI], char* lds) {
;     ...
;   for (int kt = 0; kt < nk; ++kt) {
;     const char* cur = lds + (kt & 1) * 32768;
;     if (kt + 1 < nk) gemm_stage<AI, BI>(A + (kt + 1) * 64, lda, B + (kt + 1) * 64, ldb, lds + ((kt + 1) & 1) * 32768, tid);
; #pragma unroll
;     for (int ks = 0; ks < 4; ++ks) {
;       const int co = ((ks * 2 + h) ^ sw) << 4;
;       s16x8 fa[AI], fb[BI];
; #pragma unroll
;       for (int i = 0; i < AI; ++i) fa[i] = *(const s16x8*)(cur + offA + i * 4096 + co);
; #pragma unroll
;       for (int i = 0; i < BI; ++i) fb[i] = *(const s16x8*)(cur + offB + i * 4096 + co);
; #pragma unroll
;       for (int i = 0; i < AI; ++i)
; #pragma unroll
;         for (int j = 0; j < BI; ++j) acc[i][j] = MFMA(fa[i], fb[j], acc[i][j]);
;     }
;     asm volatile("s_waitcnt vmcnt(0)" ::: "memory");
;     __syncthreads();
;   }
	v_mfma_f32_32x32x16_bf16 v[50:65], v[102:105], v[110:113], v[50:65]
	v_mfma_f32_32x32x16_bf16 v[18:33], v[102:105], v[114:117], v[18:33]
	v_lshl_add_u64 v[102:103], v[66:67], 0, s[80:81]
	global_load_lds_dwordx4 v[102:103], off
	v_lshl_add_u64 v[102:103], v[68:69], 0, s[80:81]
	s_mov_b32 m0, s47
	s_nop 0
	global_load_lds_dwordx4 v[102:103], off
	v_lshl_add_u64 v[102:103], v[70:71], 0, s[80:81]
	s_mov_b32 m0, s48
	v_mfma_f32_32x32x16_bf16 v[34:49], v[106:109], v[110:113], v[34:49]
	global_load_lds_dwordx4 v[102:103], off
	v_lshl_add_u64 v[102:103], v[72:73], 0, s[80:81]
	s_mov_b32 m0, s49
	s_nop 0
	global_load_lds_dwordx4 v[102:103], off
	s_mov_b32 m0, s36
	v_mfma_f32_32x32x16_bf16 v[2:17], v[106:109], v[114:117], v[2:17]
	global_load_lds_dwordx4 v[100:101], off
	v_lshl_add_u64 v[100:101], v[76:77], 0, s[80:81]
	s_mov_b32 m0, s37
	s_nop 0
	global_load_lds_dwordx4 v[100:101], off
	v_lshl_add_u64 v[100:101], v[78:79], 0, s[80:81]
	s_mov_b32 m0, s40
	s_nop 0
	global_load_lds_dwordx4 v[100:101], off
	v_lshl_add_u64 v[100:101], v[80:81], 0, s[80:81]
	s_mov_b32 m0, s41
	s_nop 0
	global_load_lds_dwordx4 v[100:101], off
	ds_read_b128 v[100:103], v0 offset:32768
	ds_read_b128 v[104:107], v0 offset:36864
	ds_read_b128 v[108:111], v84 offset:49152
	ds_read_b128 v[112:115], v84 offset:53248
	s_waitcnt lgkmcnt(0)
	v_mfma_f32_32x32x16_bf16 v[50:65], v[100:103], v[108:111], v[50:65]
	s_mov_b32 m0, s50
	v_mfma_f32_32x32x16_bf16 v[18:33], v[100:103], v[112:115], v[18:33]
	v_mfma_f32_32x32x16_bf16 v[34:49], v[104:107], v[108:111], v[34:49]
	v_mfma_f32_32x32x16_bf16 v[2:17], v[104:107], v[112:115], v[2:17]
	ds_read_b128 v[100:103], v89 offset:32768
	ds_read_b128 v[104:107], v89 offset:36864
	ds_read_b128 v[108:111], v90 offset:49152
	ds_read_b128 v[112:115], v90 offset:53248
	s_waitcnt lgkmcnt(1)
	v_mfma_f32_32x32x16_bf16 v[50:65], v[100:103], v[108:111], v[50:65]
	s_waitcnt lgkmcnt(0)
	v_mfma_f32_32x32x16_bf16 v[18:33], v[100:103], v[112:115], v[18:33]
	v_mfma_f32_32x32x16_bf16 v[34:49], v[104:107], v[108:111], v[34:49]
	v_mfma_f32_32x32x16_bf16 v[2:17], v[104:107], v[112:115], v[2:17]
	ds_read_b128 v[100:103], v85 offset:32768
	ds_read_b128 v[104:107], v85 offset:36864
	ds_read_b128 v[108:111], v87 offset:49152
	ds_read_b128 v[112:115], v87 offset:53248
	s_waitcnt lgkmcnt(1)
	v_mfma_f32_32x32x16_bf16 v[50:65], v[100:103], v[108:111], v[50:65]
	s_waitcnt lgkmcnt(0)
	v_mfma_f32_32x32x16_bf16 v[18:33], v[100:103], v[112:115], v[18:33]
	v_mfma_f32_32x32x16_bf16 v[34:49], v[104:107], v[108:111], v[34:49]
	v_mfma_f32_32x32x16_bf16 v[2:17], v[104:107], v[112:115], v[2:17]
	ds_read_b128 v[100:103], v86 offset:32768
	ds_read_b128 v[104:107], v86 offset:36864
	ds_read_b128 v[108:111], v88 offset:49152
	ds_read_b128 v[112:115], v88 offset:53248
	s_waitcnt vmcnt(0)
	s_waitcnt lgkmcnt(0)
	s_barrier
	v_mfma_f32_32x32x16_bf16 v[50:65], v[100:103], v[108:111], v[50:65]
	v_mfma_f32_32x32x16_bf16 v[18:33], v[100:103], v[112:115], v[18:33]
	v_lshl_add_u64 v[100:101], v[66:67], 0, s[82:83]
	global_load_lds_dwordx4 v[100:101], off
	v_lshl_add_u64 v[100:101], v[68:69], 0, s[82:83]
	s_mov_b32 m0, s51
	s_nop 0
	global_load_lds_dwordx4 v[100:101], off
	v_lshl_add_u64 v[100:101], v[70:71], 0, s[82:83]
	s_mov_b32 m0, s52
	v_mfma_f32_32x32x16_bf16 v[34:49], v[104:107], v[108:111], v[34:49]
	global_load_lds_dwordx4 v[100:101], off
	s_mov_b32 m0, s53
	s_nop 0
	global_load_lds_dwordx4 v[92:93], off
	v_lshl_add_u64 v[92:93], v[74:75], 0, s[82:83]
	s_mov_b32 m0, s54
	v_mfma_f32_32x32x16_bf16 v[2:17], v[104:107], v[112:115], v[2:17]
	global_load_lds_dwordx4 v[92:93], off
	v_lshl_add_u64 v[92:93], v[76:77], 0, s[82:83]
	s_mov_b32 m0, s55
	s_nop 0
	global_load_lds_dwordx4 v[92:93], off
	v_lshl_add_u64 v[92:93], v[78:79], 0, s[82:83]
	s_mov_b32 m0, s56
	s_nop 0
	global_load_lds_dwordx4 v[92:93], off
	v_lshl_add_u64 v[92:93], v[80:81], 0, s[82:83]
	s_mov_b32 m0, s11
	s_nop 0
	global_load_lds_dwordx4 v[92:93], off
	ds_read_b128 v[92:95], v0
	ds_read_b128 v[96:99], v0 offset:4096
	ds_read_b128 v[100:103], v84 offset:16384
	ds_read_b128 v[104:107], v84 offset:20480
	s_waitcnt lgkmcnt(0)
	v_mfma_f32_32x32x16_bf16 v[50:65], v[92:95], v[100:103], v[50:65]
	s_mov_b32 m0, s46
	v_mfma_f32_32x32x16_bf16 v[18:33], v[92:95], v[104:107], v[18:33]
	v_mfma_f32_32x32x16_bf16 v[34:49], v[96:99], v[100:103], v[34:49]
	v_mfma_f32_32x32x16_bf16 v[2:17], v[96:99], v[104:107], v[2:17]
	ds_read_b128 v[92:95], v89
	ds_read_b128 v[96:99], v89 offset:4096
	ds_read_b128 v[100:103], v90 offset:16384
	ds_read_b128 v[104:107], v90 offset:20480
	s_waitcnt lgkmcnt(1)
	v_mfma_f32_32x32x16_bf16 v[50:65], v[92:95], v[100:103], v[50:65]
	s_waitcnt lgkmcnt(0)
	v_mfma_f32_32x32x16_bf16 v[18:33], v[92:95], v[104:107], v[18:33]
	v_mfma_f32_32x32x16_bf16 v[34:49], v[96:99], v[100:103], v[34:49]
	v_mfma_f32_32x32x16_bf16 v[2:17], v[96:99], v[104:107], v[2:17]
	ds_read_b128 v[92:95], v85
	ds_read_b128 v[96:99], v85 offset:4096
	ds_read_b128 v[100:103], v87 offset:16384
	ds_read_b128 v[104:107], v87 offset:20480
	s_waitcnt lgkmcnt(1)
	v_mfma_f32_32x32x16_bf16 v[50:65], v[92:95], v[100:103], v[50:65]
	s_waitcnt lgkmcnt(0)
	v_mfma_f32_32x32x16_bf16 v[18:33], v[92:95], v[104:107], v[18:33]
	v_mfma_f32_32x32x16_bf16 v[34:49], v[96:99], v[100:103], v[34:49]
	v_mfma_f32_32x32x16_bf16 v[2:17], v[96:99], v[104:107], v[2:17]
	ds_read_b128 v[92:95], v86
	ds_read_b128 v[96:99], v86 offset:4096
	ds_read_b128 v[100:103], v88 offset:16384
	ds_read_b128 v[104:107], v88 offset:20480
	s_waitcnt vmcnt(0)
	s_waitcnt lgkmcnt(0)
	s_barrier
; #define MFMA(a, b, c) __builtin_amdgcn_mfma_f32_32x32x16_bf16((a), (b), (c), 0, 0, 0)
; template <int AI, int BI>
; DI void gemm_tile(const u16* __restrict__ A, int lda, const u16* __restrict__ B, int ldb, int nk, bool swap,
;                   f32x16 (&acc)[AI][BI], char* lds) {
;     ...
;   for (int kt = 0; kt < nk; ++kt) {
;     const char* cur = lds + (kt & 1) * 32768;
;     if (kt + 1 < nk) gemm_stage<AI, BI>(A + (kt + 1) * 64, lda, B + (kt + 1) * 64, ldb, lds + ((kt + 1) & 1) * 32768, tid);
; #pragma unroll
;     for (int ks = 0; ks < 4; ++ks) {
;       const int co = ((ks * 2 + h) ^ sw) << 4;
;       s16x8 fa[AI], fb[BI];
; #pragma unroll
;       for (int i = 0; i < AI; ++i) fa[i] = *(const s16x8*)(cur + offA + i * 4096 + co);
; #pragma unroll
;       for (int i = 0; i < BI; ++i) fb[i] = *(const s16x8*)(cur + offB + i * 4096 + co);
; #pragma unroll
;       for (int i = 0; i < AI; ++i)
; #pragma unroll
;         for (int j = 0; j < BI; ++j) acc[i][j] = MFMA(fa[i], fb[j], acc[i][j]);
;     }
;     asm volatile("s_waitcnt vmcnt(0)" ::: "memory");
;     __syncthreads();
;   }
	v_mfma_f32_32x32x16_bf16 v[50:65], v[92:95], v[100:103], v[50:65]
	v_mfma_f32_32x32x16_bf16 v[18:33], v[92:95], v[104:107], v[18:33]
	v_lshl_add_u64 v[92:93], v[66:67], 0, s[84:85]
	global_load_lds_dwordx4 v[92:93], off
	v_lshl_add_u64 v[92:93], v[68:69], 0, s[84:85]
	s_mov_b32 m0, s47
	s_nop 0
	global_load_lds_dwordx4 v[92:93], off
	v_lshl_add_u64 v[92:93], v[70:71], 0, s[84:85]
	s_mov_b32 m0, s48
	v_mfma_f32_32x32x16_bf16 v[34:49], v[96:99], v[100:103], v[34:49]
	global_load_lds_dwordx4 v[92:93], off
	v_lshl_add_u64 v[92:93], v[72:73], 0, s[84:85]
	s_mov_b32 m0, s49
	s_nop 0
	global_load_lds_dwordx4 v[92:93], off
	v_lshl_add_u64 v[92:93], v[74:75], 0, s[84:85]
	s_mov_b32 m0, s36
	v_mfma_f32_32x32x16_bf16 v[2:17], v[96:99], v[104:107], v[2:17]
	global_load_lds_dwordx4 v[92:93], off
	v_lshl_add_u64 v[92:93], v[76:77], 0, s[84:85]
	s_mov_b32 m0, s37
	s_nop 0
	global_load_lds_dwordx4 v[92:93], off
	v_lshl_add_u64 v[92:93], v[78:79], 0, s[84:85]
	s_mov_b32 m0, s40
	s_nop 0
	global_load_lds_dwordx4 v[92:93], off
	v_lshl_add_u64 v[92:93], v[80:81], 0, s[84:85]
	s_mov_b32 m0, s41
	s_nop 0
	global_load_lds_dwordx4 v[92:93], off
	ds_read_b128 v[92:95], v0 offset:32768
	ds_read_b128 v[96:99], v0 offset:36864
	ds_read_b128 v[100:103], v84 offset:49152
	ds_read_b128 v[104:107], v84 offset:53248
	s_waitcnt lgkmcnt(0)
	v_mfma_f32_32x32x16_bf16 v[50:65], v[92:95], v[100:103], v[50:65]
	s_mov_b32 m0, s50
	v_mfma_f32_32x32x16_bf16 v[18:33], v[92:95], v[104:107], v[18:33]
	v_mfma_f32_32x32x16_bf16 v[34:49], v[96:99], v[100:103], v[34:49]
	v_mfma_f32_32x32x16_bf16 v[2:17], v[96:99], v[104:107], v[2:17]
	ds_read_b128 v[92:95], v89 offset:32768
	ds_read_b128 v[96:99], v89 offset:36864
	ds_read_b128 v[100:103], v90 offset:49152
	ds_read_b128 v[104:107], v90 offset:53248
	s_waitcnt lgkmcnt(1)
	v_mfma_f32_32x32x16_bf16 v[50:65], v[92:95], v[100:103], v[50:65]
	s_waitcnt lgkmcnt(0)
	v_mfma_f32_32x32x16_bf16 v[18:33], v[92:95], v[104:107], v[18:33]
	v_mfma_f32_32x32x16_bf16 v[34:49], v[96:99], v[100:103], v[34:49]
	v_mfma_f32_32x32x16_bf16 v[2:17], v[96:99], v[104:107], v[2:17]
	ds_read_b128 v[92:95], v85 offset:32768
	ds_read_b128 v[96:99], v85 offset:36864
	ds_read_b128 v[100:103], v87 offset:49152
	ds_read_b128 v[104:107], v87 offset:53248
	s_waitcnt lgkmcnt(1)
	v_mfma_f32_32x32x16_bf16 v[50:65], v[92:95], v[100:103], v[50:65]
	s_waitcnt lgkmcnt(0)
	v_mfma_f32_32x32x16_bf16 v[18:33], v[92:95], v[104:107], v[18:33]
	v_mfma_f32_32x32x16_bf16 v[34:49], v[96:99], v[100:103], v[34:49]
	v_mfma_f32_32x32x16_bf16 v[2:17], v[96:99], v[104:107], v[2:17]
	ds_read_b128 v[92:95], v86 offset:32768
	ds_read_b128 v[96:99], v86 offset:36864
	ds_read_b128 v[100:103], v88 offset:49152
	ds_read_b128 v[104:107], v88 offset:53248
	s_waitcnt vmcnt(0)
	s_waitcnt lgkmcnt(0)
	s_barrier
	v_mfma_f32_32x32x16_bf16 v[50:65], v[92:95], v[100:103], v[50:65]
	v_mfma_f32_32x32x16_bf16 v[18:33], v[92:95], v[104:107], v[18:33]
	v_lshl_add_u64 v[92:93], v[66:67], 0, s[88:89]
	global_load_lds_dwordx4 v[92:93], off
	v_lshl_add_u64 v[92:93], v[68:69], 0, s[88:89]
	s_mov_b32 m0, s51
	s_nop 0
	global_load_lds_dwordx4 v[92:93], off
	v_lshl_add_u64 v[92:93], v[70:71], 0, s[88:89]
	s_mov_b32 m0, s52
	v_mfma_f32_32x32x16_bf16 v[34:49], v[96:99], v[100:103], v[34:49]
	global_load_lds_dwordx4 v[92:93], off
	v_lshl_add_u64 v[92:93], v[72:73], 0, s[88:89]
	s_mov_b32 m0, s53
	s_nop 0
	global_load_lds_dwordx4 v[92:93], off
	v_lshl_add_u64 v[92:93], v[74:75], 0, s[88:89]
	s_mov_b32 m0, s54
	v_mfma_f32_32x32x16_bf16 v[2:17], v[96:99], v[104:107], v[2:17]
	global_load_lds_dwordx4 v[92:93], off
	v_lshl_add_u64 v[92:93], v[76:77], 0, s[88:89]
	s_mov_b32 m0, s55
	s_nop 0
	global_load_lds_dwordx4 v[92:93], off
	v_lshl_add_u64 v[92:93], v[78:79], 0, s[88:89]
	s_mov_b32 m0, s56
	s_nop 0
	global_load_lds_dwordx4 v[92:93], off
	v_lshl_add_u64 v[92:93], v[80:81], 0, s[88:89]
	s_mov_b32 m0, s11
	s_nop 0
	global_load_lds_dwordx4 v[92:93], off
	ds_read_b128 v[92:95], v0
	ds_read_b128 v[96:99], v0 offset:4096
	ds_read_b128 v[100:103], v84 offset:16384
	ds_read_b128 v[104:107], v84 offset:20480
	s_waitcnt lgkmcnt(0)
	v_mfma_f32_32x32x16_bf16 v[50:65], v[92:95], v[100:103], v[50:65]
	s_mov_b32 m0, s46
	v_mfma_f32_32x32x16_bf16 v[18:33], v[92:95], v[104:107], v[18:33]
	v_mfma_f32_32x32x16_bf16 v[34:49], v[96:99], v[100:103], v[34:49]
	v_mfma_f32_32x32x16_bf16 v[2:17], v[96:99], v[104:107], v[2:17]
	ds_read_b128 v[92:95], v89
	ds_read_b128 v[96:99], v89 offset:4096
	ds_read_b128 v[100:103], v90 offset:16384
	ds_read_b128 v[104:107], v90 offset:20480
	s_waitcnt lgkmcnt(1)
	v_mfma_f32_32x32x16_bf16 v[50:65], v[92:95], v[100:103], v[50:65]
	s_waitcnt lgkmcnt(0)
	v_mfma_f32_32x32x16_bf16 v[18:33], v[92:95], v[104:107], v[18:33]
	v_mfma_f32_32x32x16_bf16 v[34:49], v[96:99], v[100:103], v[34:49]
	v_mfma_f32_32x32x16_bf16 v[2:17], v[96:99], v[104:107], v[2:17]
	ds_read_b128 v[92:95], v85
	ds_read_b128 v[96:99], v85 offset:4096
	ds_read_b128 v[100:103], v87 offset:16384
	ds_read_b128 v[104:107], v87 offset:20480
	s_waitcnt lgkmcnt(1)
	v_mfma_f32_32x32x16_bf16 v[50:65], v[92:95], v[100:103], v[50:65]
	s_waitcnt lgkmcnt(0)
	v_mfma_f32_32x32x16_bf16 v[18:33], v[92:95], v[104:107], v[18:33]
	v_mfma_f32_32x32x16_bf16 v[34:49], v[96:99], v[100:103], v[34:49]
	v_mfma_f32_32x32x16_bf16 v[2:17], v[96:99], v[104:107], v[2:17]
	ds_read_b128 v[92:95], v86
	ds_read_b128 v[96:99], v86 offset:4096
	ds_read_b128 v[100:103], v88 offset:16384
	ds_read_b128 v[104:107], v88 offset:20480
	s_waitcnt vmcnt(0)
	s_waitcnt lgkmcnt(0)
	s_barrier
; #define MFMA(a, b, c) __builtin_amdgcn_mfma_f32_32x32x16_bf16((a), (b), (c), 0, 0, 0)
; template <int AI, int BI>
; DI void gemm_tile(const u16* __restrict__ A, int lda, const u16* __restrict__ B, int ldb, int nk, bool swap,
;                   f32x16 (&acc)[AI][BI], char* lds) {
;     ...
;   for (int kt = 0; kt < nk; ++kt) {
;     const char* cur = lds + (kt & 1) * 32768;
;     if (kt + 1 < nk) gemm_stage<AI, BI>(A + (kt + 1) * 64, lda, B + (kt + 1) * 64, ldb, lds + ((kt + 1) & 1) * 32768, tid);
; #pragma unroll
;     for (int ks = 0; ks < 4; ++ks) {
;       const int co = ((ks * 2 + h) ^ sw) << 4;
;       s16x8 fa[AI], fb[BI];
; #pragma unroll
;       for (int i = 0; i < AI; ++i) fa[i] = *(const s16x8*)(cur + offA + i * 4096 + co);
; #pragma unroll
;       for (int i = 0; i < BI; ++i) fb[i] = *(const s16x8*)(cur + offB + i * 4096 + co);
; #pragma unroll
;       for (int i = 0; i < AI; ++i)
; #pragma unroll
;         for (int j = 0; j < BI; ++j) acc[i][j] = MFMA(fa[i], fb[j], acc[i][j]);
;     }
;     asm volatile("s_waitcnt vmcnt(0)" ::: "memory");
;     __syncthreads();
;   }
	v_mfma_f32_32x32x16_bf16 v[50:65], v[92:95], v[100:103], v[50:65]
	v_mfma_f32_32x32x16_bf16 v[18:33], v[92:95], v[104:107], v[18:33]
	v_lshl_add_u64 v[92:93], v[66:67], 0, vcc
	global_load_lds_dwordx4 v[92:93], off
	v_lshl_add_u64 v[92:93], v[68:69], 0, vcc
	s_mov_b32 m0, s47
	s_nop 0
	global_load_lds_dwordx4 v[92:93], off
	v_lshl_add_u64 v[92:93], v[70:71], 0, vcc
	s_mov_b32 m0, s48
	v_mfma_f32_32x32x16_bf16 v[34:49], v[96:99], v[100:103], v[34:49]
	global_load_lds_dwordx4 v[92:93], off
	v_lshl_add_u64 v[92:93], v[72:73], 0, vcc
	s_mov_b32 m0, s49
	s_nop 0
	global_load_lds_dwordx4 v[92:93], off
	v_lshl_add_u64 v[92:93], v[74:75], 0, vcc
	s_mov_b32 m0, s36
	v_mfma_f32_32x32x16_bf16 v[2:17], v[96:99], v[104:107], v[2:17]
	global_load_lds_dwordx4 v[92:93], off
	v_lshl_add_u64 v[92:93], v[76:77], 0, vcc
	s_mov_b32 m0, s37
	s_nop 0
	global_load_lds_dwordx4 v[92:93], off
	v_lshl_add_u64 v[92:93], v[78:79], 0, vcc
	s_mov_b32 m0, s40
	s_nop 0
	global_load_lds_dwordx4 v[92:93], off
	v_lshl_add_u64 v[92:93], v[80:81], 0, vcc
	s_mov_b32 m0, s41
	s_nop 0
	global_load_lds_dwordx4 v[92:93], off
	ds_read_b128 v[92:95], v0 offset:32768
	ds_read_b128 v[96:99], v0 offset:36864
	ds_read_b128 v[100:103], v84 offset:49152
	ds_read_b128 v[104:107], v84 offset:53248
	s_waitcnt lgkmcnt(0)
	v_mfma_f32_32x32x16_bf16 v[50:65], v[92:95], v[100:103], v[50:65]
	s_mov_b32 m0, s50
	v_mfma_f32_32x32x16_bf16 v[18:33], v[92:95], v[104:107], v[18:33]
	v_mfma_f32_32x32x16_bf16 v[34:49], v[96:99], v[100:103], v[34:49]
	v_mfma_f32_32x32x16_bf16 v[2:17], v[96:99], v[104:107], v[2:17]
	ds_read_b128 v[92:95], v89 offset:32768
	ds_read_b128 v[96:99], v89 offset:36864
	ds_read_b128 v[100:103], v90 offset:49152
	ds_read_b128 v[104:107], v90 offset:53248
	s_waitcnt lgkmcnt(1)
	v_mfma_f32_32x32x16_bf16 v[50:65], v[92:95], v[100:103], v[50:65]
	s_waitcnt lgkmcnt(0)
	v_mfma_f32_32x32x16_bf16 v[18:33], v[92:95], v[104:107], v[18:33]
	v_mfma_f32_32x32x16_bf16 v[34:49], v[96:99], v[100:103], v[34:49]
	v_mfma_f32_32x32x16_bf16 v[2:17], v[96:99], v[104:107], v[2:17]
	ds_read_b128 v[92:95], v85 offset:32768
	ds_read_b128 v[96:99], v85 offset:36864
	ds_read_b128 v[100:103], v87 offset:49152
	ds_read_b128 v[104:107], v87 offset:53248
	s_waitcnt lgkmcnt(1)
	v_mfma_f32_32x32x16_bf16 v[50:65], v[92:95], v[100:103], v[50:65]
	s_waitcnt lgkmcnt(0)
	v_mfma_f32_32x32x16_bf16 v[18:33], v[92:95], v[104:107], v[18:33]
	v_mfma_f32_32x32x16_bf16 v[34:49], v[96:99], v[100:103], v[34:49]
	v_mfma_f32_32x32x16_bf16 v[2:17], v[96:99], v[104:107], v[2:17]
	ds_read_b128 v[92:95], v86 offset:32768
	ds_read_b128 v[96:99], v86 offset:36864
	ds_read_b128 v[100:103], v88 offset:49152
	ds_read_b128 v[104:107], v88 offset:53248
	s_waitcnt vmcnt(0)
	s_waitcnt lgkmcnt(0)
	s_barrier
	v_mfma_f32_32x32x16_bf16 v[50:65], v[92:95], v[100:103], v[50:65]
	v_mfma_f32_32x32x16_bf16 v[18:33], v[92:95], v[104:107], v[18:33]
	v_lshl_add_u64 v[92:93], v[66:67], 0, s[78:79]
	global_load_lds_dwordx4 v[92:93], off
	v_lshl_add_u64 v[92:93], v[68:69], 0, s[78:79]
	s_mov_b32 m0, s51
	s_nop 0
	global_load_lds_dwordx4 v[92:93], off
	v_lshl_add_u64 v[92:93], v[70:71], 0, s[78:79]
	s_mov_b32 m0, s52
	v_mfma_f32_32x32x16_bf16 v[34:49], v[96:99], v[100:103], v[34:49]
	global_load_lds_dwordx4 v[92:93], off
	v_lshl_add_u64 v[92:93], v[72:73], 0, s[78:79]
	s_mov_b32 m0, s53
	s_nop 0
	global_load_lds_dwordx4 v[92:93], off
	v_lshl_add_u64 v[92:93], v[74:75], 0, s[78:79]
	s_mov_b32 m0, s54
	v_mfma_f32_32x32x16_bf16 v[2:17], v[96:99], v[104:107], v[2:17]
	global_load_lds_dwordx4 v[92:93], off
	v_lshl_add_u64 v[92:93], v[76:77], 0, s[78:79]
	s_mov_b32 m0, s55
	s_nop 0
	global_load_lds_dwordx4 v[92:93], off
	v_lshl_add_u64 v[92:93], v[78:79], 0, s[78:79]
	s_mov_b32 m0, s56
	s_nop 0
	global_load_lds_dwordx4 v[92:93], off
	v_lshl_add_u64 v[92:93], v[80:81], 0, s[78:79]
	s_mov_b32 m0, s11
	s_nop 0
	global_load_lds_dwordx4 v[92:93], off
	ds_read_b128 v[92:95], v0
	ds_read_b128 v[96:99], v0 offset:4096
	ds_read_b128 v[100:103], v84 offset:16384
	ds_read_b128 v[104:107], v84 offset:20480
	s_waitcnt lgkmcnt(0)
	v_mfma_f32_32x32x16_bf16 v[50:65], v[92:95], v[100:103], v[50:65]
	s_mov_b32 m0, s46
	v_mfma_f32_32x32x16_bf16 v[18:33], v[92:95], v[104:107], v[18:33]
	v_mfma_f32_32x32x16_bf16 v[34:49], v[96:99], v[100:103], v[34:49]
	v_mfma_f32_32x32x16_bf16 v[2:17], v[96:99], v[104:107], v[2:17]
	ds_read_b128 v[92:95], v89
	ds_read_b128 v[96:99], v89 offset:4096
	ds_read_b128 v[100:103], v90 offset:16384
	ds_read_b128 v[104:107], v90 offset:20480
	s_waitcnt lgkmcnt(1)
	v_mfma_f32_32x32x16_bf16 v[50:65], v[92:95], v[100:103], v[50:65]
	s_waitcnt lgkmcnt(0)
	v_mfma_f32_32x32x16_bf16 v[18:33], v[92:95], v[104:107], v[18:33]
	v_mfma_f32_32x32x16_bf16 v[34:49], v[96:99], v[100:103], v[34:49]
	v_mfma_f32_32x32x16_bf16 v[2:17], v[96:99], v[104:107], v[2:17]
	ds_read_b128 v[92:95], v85
	ds_read_b128 v[96:99], v85 offset:4096
	ds_read_b128 v[100:103], v87 offset:16384
	ds_read_b128 v[104:107], v87 offset:20480
	s_waitcnt lgkmcnt(1)
	v_mfma_f32_32x32x16_bf16 v[50:65], v[92:95], v[100:103], v[50:65]
	s_waitcnt lgkmcnt(0)
	v_mfma_f32_32x32x16_bf16 v[18:33], v[92:95], v[104:107], v[18:33]
	v_mfma_f32_32x32x16_bf16 v[34:49], v[96:99], v[100:103], v[34:49]
	v_mfma_f32_32x32x16_bf16 v[2:17], v[96:99], v[104:107], v[2:17]
	ds_read_b128 v[92:95], v86
	ds_read_b128 v[96:99], v86 offset:4096
	ds_read_b128 v[100:103], v88 offset:16384
	ds_read_b128 v[104:107], v88 offset:20480
	s_waitcnt vmcnt(0)
	s_waitcnt lgkmcnt(0)
	s_barrier
; #define MFMA(a, b, c) __builtin_amdgcn_mfma_f32_32x32x16_bf16((a), (b), (c), 0, 0, 0)
; template <int AI, int BI>
; DI void gemm_tile(const u16* __restrict__ A, int lda, const u16* __restrict__ B, int ldb, int nk, bool swap,
;                   f32x16 (&acc)[AI][BI], char* lds) {
;     ...
;   for (int kt = 0; kt < nk; ++kt) {
;     const char* cur = lds + (kt & 1) * 32768;
;     if (kt + 1 < nk) gemm_stage<AI, BI>(A + (kt + 1) * 64, lda, B + (kt + 1) * 64, ldb, lds + ((kt + 1) & 1) * 32768, tid);
; #pragma unroll
;     for (int ks = 0; ks < 4; ++ks) {
;       const int co = ((ks * 2 + h) ^ sw) << 4;
;       s16x8 fa[AI], fb[BI];
; #pragma unroll
;       for (int i = 0; i < AI; ++i) fa[i] = *(const s16x8*)(cur + offA + i * 4096 + co);
; #pragma unroll
;       for (int i = 0; i < BI; ++i) fb[i] = *(const s16x8*)(cur + offB + i * 4096 + co);
; #pragma unroll
;       for (int i = 0; i < AI; ++i)
; #pragma unroll
;         for (int j = 0; j < BI; ++j) acc[i][j] = MFMA(fa[i], fb[j], acc[i][j]);
;     }
;     asm volatile("s_waitcnt vmcnt(0)" ::: "memory");
;     __syncthreads();
;   }
	v_mfma_f32_32x32x16_bf16 v[50:65], v[92:95], v[100:103], v[50:65]
	v_mfma_f32_32x32x16_bf16 v[18:33], v[92:95], v[104:107], v[18:33]
	v_lshl_add_u64 v[92:93], v[66:67], 0, s[2:3]
	global_load_lds_dwordx4 v[92:93], off
	v_lshl_add_u64 v[92:93], v[68:69], 0, s[2:3]
	s_mov_b32 m0, s47
	v_lshl_add_u64 v[66:67], v[66:67], 0, s[30:31]
	global_load_lds_dwordx4 v[92:93], off
	v_lshl_add_u64 v[92:93], v[70:71], 0, s[2:3]
	s_mov_b32 m0, s48
	v_mfma_f32_32x32x16_bf16 v[34:49], v[96:99], v[100:103], v[34:49]
	global_load_lds_dwordx4 v[92:93], off
	v_lshl_add_u64 v[92:93], v[72:73], 0, s[2:3]
	s_mov_b32 m0, s49
	s_nop 0
	global_load_lds_dwordx4 v[92:93], off
	v_lshl_add_u64 v[92:93], v[74:75], 0, s[2:3]
	s_mov_b32 m0, s36
	v_mfma_f32_32x32x16_bf16 v[2:17], v[96:99], v[104:107], v[2:17]
	global_load_lds_dwordx4 v[92:93], off
	v_lshl_add_u64 v[92:93], v[76:77], 0, s[2:3]
	s_mov_b32 m0, s37
	s_lshl_b32 s36, s10, 7
	global_load_lds_dwordx4 v[92:93], off
	v_lshl_add_u64 v[92:93], v[78:79], 0, s[2:3]
	s_mov_b32 m0, s40
	s_lshr_b32 s10, s34, 7
	global_load_lds_dwordx4 v[92:93], off
	v_lshl_add_u64 v[92:93], v[80:81], 0, s[2:3]
	s_mov_b32 m0, s41
	s_mul_i32 s10, s10, 0x9000
	global_load_lds_dwordx4 v[92:93], off
	ds_read_b128 v[92:95], v0 offset:32768
	ds_read_b128 v[96:99], v0 offset:36864
	ds_read_b128 v[100:103], v84 offset:49152
	ds_read_b128 v[104:107], v84 offset:53248
	s_waitcnt lgkmcnt(0)
	v_mfma_f32_32x32x16_bf16 v[50:65], v[92:95], v[100:103], v[50:65]
	s_mov_b32 m0, s50
	s_add_u32 s10, s18, s10
	v_mfma_f32_32x32x16_bf16 v[18:33], v[92:95], v[104:107], v[18:33]
	v_mfma_f32_32x32x16_bf16 v[34:49], v[96:99], v[100:103], v[34:49]
	v_mfma_f32_32x32x16_bf16 v[2:17], v[96:99], v[104:107], v[2:17]
	ds_read_b128 v[92:95], v89 offset:32768
	ds_read_b128 v[96:99], v89 offset:36864
	ds_read_b128 v[100:103], v90 offset:49152
	ds_read_b128 v[104:107], v90 offset:53248
	s_waitcnt lgkmcnt(1)
	v_mfma_f32_32x32x16_bf16 v[50:65], v[92:95], v[100:103], v[50:65]
	s_waitcnt lgkmcnt(0)
	v_mfma_f32_32x32x16_bf16 v[18:33], v[92:95], v[104:107], v[18:33]
	v_mfma_f32_32x32x16_bf16 v[34:49], v[96:99], v[100:103], v[34:49]
	v_mfma_f32_32x32x16_bf16 v[2:17], v[96:99], v[104:107], v[2:17]
	ds_read_b128 v[92:95], v85 offset:32768
	ds_read_b128 v[96:99], v85 offset:36864
	ds_read_b128 v[100:103], v87 offset:49152
	ds_read_b128 v[104:107], v87 offset:53248
	s_waitcnt lgkmcnt(1)
	v_mfma_f32_32x32x16_bf16 v[50:65], v[92:95], v[100:103], v[50:65]
	s_waitcnt lgkmcnt(0)
	v_mfma_f32_32x32x16_bf16 v[18:33], v[92:95], v[104:107], v[18:33]
	v_mfma_f32_32x32x16_bf16 v[34:49], v[96:99], v[100:103], v[34:49]
	v_mfma_f32_32x32x16_bf16 v[2:17], v[96:99], v[104:107], v[2:17]
	ds_read_b128 v[92:95], v86 offset:32768
	ds_read_b128 v[96:99], v86 offset:36864
	ds_read_b128 v[100:103], v88 offset:49152
	ds_read_b128 v[104:107], v88 offset:53248
	s_waitcnt vmcnt(0)
	s_waitcnt lgkmcnt(0)
	s_barrier
	global_load_lds_dwordx4 v[66:67], off
	v_lshl_add_u64 v[66:67], v[68:69], 0, s[30:31]
	s_mov_b32 m0, s51
	v_mfma_f32_32x32x16_bf16 v[50:65], v[92:95], v[100:103], v[50:65]
	global_load_lds_dwordx4 v[66:67], off
	v_lshl_add_u64 v[66:67], v[70:71], 0, s[30:31]
	s_mov_b32 m0, s52
	s_nop 0
	global_load_lds_dwordx4 v[66:67], off
	v_lshl_add_u64 v[66:67], v[72:73], 0, s[30:31]
	s_mov_b32 m0, s53
	v_mfma_f32_32x32x16_bf16 v[18:33], v[92:95], v[104:107], v[18:33]
	global_load_lds_dwordx4 v[66:67], off
	v_lshl_add_u64 v[66:67], v[74:75], 0, s[30:31]
	s_mov_b32 m0, s54
	s_nop 0
	global_load_lds_dwordx4 v[66:67], off
	v_lshl_add_u64 v[66:67], v[76:77], 0, s[30:31]
	s_mov_b32 m0, s55
	v_mfma_f32_32x32x16_bf16 v[34:49], v[96:99], v[100:103], v[34:49]
	global_load_lds_dwordx4 v[66:67], off
	v_lshl_add_u64 v[66:67], v[78:79], 0, s[30:31]
	s_mov_b32 m0, s56
	s_nop 0
	global_load_lds_dwordx4 v[66:67], off
	v_lshl_add_u64 v[66:67], v[80:81], 0, s[30:31]
	s_mov_b32 m0, s11
	v_mfma_f32_32x32x16_bf16 v[2:17], v[96:99], v[104:107], v[2:17]
	global_load_lds_dwordx4 v[66:67], off
	ds_read_b128 v[66:69], v0
	ds_read_b128 v[70:73], v0 offset:4096
	ds_read_b128 v[74:77], v84 offset:16384
	ds_read_b128 v[78:81], v84 offset:20480
	s_addc_u32 s11, s28, 0
	s_add_u32 s10, s10, 0x9000
	s_addc_u32 s11, s11, 0
	s_waitcnt lgkmcnt(0)
	v_mfma_f32_32x32x16_bf16 v[50:65], v[66:69], v[74:77], v[50:65]
	v_mfma_f32_32x32x16_bf16 v[18:33], v[66:69], v[78:81], v[18:33]
	v_mfma_f32_32x32x16_bf16 v[34:49], v[70:73], v[74:77], v[34:49]
	v_mfma_f32_32x32x16_bf16 v[2:17], v[70:73], v[78:81], v[2:17]
	ds_read_b128 v[66:69], v89
	ds_read_b128 v[70:73], v89 offset:4096
	ds_read_b128 v[74:77], v90 offset:16384
	ds_read_b128 v[78:81], v90 offset:20480
	s_waitcnt lgkmcnt(1)
	v_mfma_f32_32x32x16_bf16 v[50:65], v[66:69], v[74:77], v[50:65]
	s_waitcnt lgkmcnt(0)
	v_mfma_f32_32x32x16_bf16 v[18:33], v[66:69], v[78:81], v[18:33]
	v_mfma_f32_32x32x16_bf16 v[34:49], v[70:73], v[74:77], v[34:49]
	v_mfma_f32_32x32x16_bf16 v[2:17], v[70:73], v[78:81], v[2:17]
	ds_read_b128 v[66:69], v85
	ds_read_b128 v[70:73], v85 offset:4096
	ds_read_b128 v[74:77], v87 offset:16384
	ds_read_b128 v[78:81], v87 offset:20480
	s_waitcnt lgkmcnt(1)
	v_mfma_f32_32x32x16_bf16 v[50:65], v[66:69], v[74:77], v[50:65]
	s_waitcnt lgkmcnt(0)
	v_mfma_f32_32x32x16_bf16 v[18:33], v[66:69], v[78:81], v[18:33]
	v_mfma_f32_32x32x16_bf16 v[34:49], v[70:73], v[74:77], v[34:49]
	v_mfma_f32_32x32x16_bf16 v[2:17], v[70:73], v[78:81], v[2:17]
	ds_read_b128 v[66:69], v86
	ds_read_b128 v[70:73], v86 offset:4096
	ds_read_b128 v[74:77], v88 offset:16384
	ds_read_b128 v[78:81], v88 offset:20480
	s_waitcnt vmcnt(0)
	s_waitcnt lgkmcnt(0)
	s_barrier
; #define MFMA(a, b, c) __builtin_amdgcn_mfma_f32_32x32x16_bf16((a), (b), (c), 0, 0, 0)
; #define GAS __attribute__((address_space(1)))
; DI int opaque0() { int z = 0; asm volatile("" : "+v"(z)); return z; }
; template <int AI, int BI>
; DI void gemm_tile(const u16* __restrict__ A, int lda, const u16* __restrict__ B, int ldb, int nk, bool swap,
;                   f32x16 (&acc)[AI][BI], char* lds) {
;     ...
;       for (int i = 0; i < AI; ++i)
; #pragma unroll
;         for (int j = 0; j < BI; ++j) acc[i][j] = MFMA(fa[i], fb[j], acc[i][j]);
;     }
;     asm volatile("s_waitcnt vmcnt(0)" ::: "memory");
;     __syncthreads();
;   }
; template <int AI, int BI>
; DI void m2_tile(char* wsb, int layer, int m0, int n0, char* lds) {
;     ...
;   const int m0e = m0 + opaque0();
;   const int mr = m0 < TL ? (m0 >> 11) : 8;
;   const float* gate = mods + (size_t)mr * 9216 + 5 * 1024;
;   GAS float* xsu = uptr(xs);
; #pragma unroll
;   for (int bi = 0; bi < BI; ++bi) {
;     const int n = n0 + wb * 32 * BI + bi * 32 + r;
;     const float gv = gate[n];
;     const unsigned ib = (unsigned)((m0e + wa * 32 * AI + 4 * h) * 1024 + n);
; #pragma unroll
;     for (int ai = 0; ai < AI; ++ai)
; #pragma unroll
;       for (int reg = 0; reg < 16; ++reg) {
;         const unsigned idx = ib + (unsigned)((ai * 32 + (reg & 3) + 8 * (reg >> 2)) * 1024);
;         xsu[idx] += gv * acc[ai][bi][reg];
;         if ((reg & 7) == 7) __builtin_amdgcn_sched_barrier(0);
;       }
	v_mfma_f32_32x32x16_bf16 v[50:65], v[66:69], v[74:77], v[50:65]
	v_mfma_f32_32x32x16_bf16 v[18:33], v[66:69], v[78:81], v[18:33]
	v_mfma_f32_32x32x16_bf16 v[34:49], v[70:73], v[74:77], v[34:49]
	v_mfma_f32_32x32x16_bf16 v[2:17], v[70:73], v[78:81], v[2:17]
	ds_read_b128 v[66:69], v0 offset:32768
	ds_read_b128 v[70:73], v0 offset:36864
	ds_read_b128 v[74:77], v84 offset:49152
	ds_read_b128 v[78:81], v84 offset:53248
	v_mov_b32_e32 v0, v1
	s_waitcnt lgkmcnt(1)
	v_mfma_f32_32x32x16_bf16 v[50:65], v[66:69], v[74:77], v[50:65]
	s_waitcnt lgkmcnt(0)
	v_mfma_f32_32x32x16_bf16 v[18:33], v[66:69], v[78:81], v[18:33]
	v_mfma_f32_32x32x16_bf16 v[34:49], v[70:73], v[74:77], v[34:49]
	v_mfma_f32_32x32x16_bf16 v[2:17], v[70:73], v[78:81], v[2:17]
	ds_read_b128 v[66:69], v89 offset:32768
	ds_read_b128 v[70:73], v89 offset:36864
	ds_read_b128 v[74:77], v90 offset:49152
	ds_read_b128 v[78:81], v90 offset:53248
	s_waitcnt lgkmcnt(1)
	v_mfma_f32_32x32x16_bf16 v[50:65], v[66:69], v[74:77], v[50:65]
	s_waitcnt lgkmcnt(0)
	v_mfma_f32_32x32x16_bf16 v[18:33], v[66:69], v[78:81], v[18:33]
	v_mfma_f32_32x32x16_bf16 v[34:49], v[70:73], v[74:77], v[34:49]
	v_mfma_f32_32x32x16_bf16 v[2:17], v[70:73], v[78:81], v[2:17]
	ds_read_b128 v[66:69], v85 offset:32768
	ds_read_b128 v[70:73], v85 offset:36864
	ds_read_b128 v[74:77], v87 offset:49152
	ds_read_b128 v[78:81], v87 offset:53248
	s_waitcnt lgkmcnt(1)
	v_mfma_f32_32x32x16_bf16 v[50:65], v[66:69], v[74:77], v[50:65]
	s_waitcnt lgkmcnt(0)
	v_mfma_f32_32x32x16_bf16 v[18:33], v[66:69], v[78:81], v[18:33]
	v_mfma_f32_32x32x16_bf16 v[34:49], v[70:73], v[74:77], v[34:49]
	v_mfma_f32_32x32x16_bf16 v[2:17], v[70:73], v[78:81], v[2:17]
	ds_read_b128 v[66:69], v86 offset:32768
	ds_read_b128 v[70:73], v86 offset:36864
	ds_read_b128 v[74:77], v88 offset:49152
	ds_read_b128 v[78:81], v88 offset:53248
	s_waitcnt vmcnt(0)
	s_waitcnt lgkmcnt(0)
	s_barrier
	v_mfma_f32_32x32x16_bf16 v[50:65], v[66:69], v[74:77], v[50:65]
	v_mfma_f32_32x32x16_bf16 v[18:33], v[66:69], v[78:81], v[18:33]
	v_mfma_f32_32x32x16_bf16 v[34:49], v[70:73], v[74:77], v[34:49]
	v_mfma_f32_32x32x16_bf16 v[2:17], v[70:73], v[78:81], v[2:17]
	v_and_b32_e32 v143, 31, v178
	v_and_b32_e32 v140, 64, v178
	v_or_b32_e32 v140, v140, v143
	v_bfe_u32 v143, v178, 5, 1
	v_bfe_u32 v139, v178, 7, 1
	v_lshlrev_b32_e32 v139, 6, v139
	v_lshl_add_u32 v139, v143, 2, v139
	v_lshl_add_u32 v139, v139, 10, v140
	v_lshlrev_b32_e32 v139, 2, v139
	v_add_u32_e32 v140, s35, v140
	v_lshlrev_b32_e32 v140, 2, v140
	global_load_dword v141, v140, s[10:11]
	global_load_dword v142, v140, s[10:11] offset:128
	s_lshl_b32 s56, s36, 10
	s_add_u32 s56, s56, s35
	s_lshl_b32 s56, s56, 2
	s_add_u32 s54, s8, s56
	s_addc_u32 s55, s9, 0
	s_mov_b64 s[52:53], s[54:55]
	global_load_dword v66, v139, s[52:53]
	global_load_dword v67, v139, s[52:53] offset:128
	s_add_u32 s52, s52, 4096
	s_addc_u32 s53, s53, 0
	global_load_dword v68, v139, s[52:53]
	global_load_dword v69, v139, s[52:53] offset:128
	s_add_u32 s52, s52, 4096
	s_addc_u32 s53, s53, 0
	global_load_dword v70, v139, s[52:53]
	global_load_dword v71, v139, s[52:53] offset:128
	s_add_u32 s52, s52, 4096
	s_addc_u32 s53, s53, 0
	global_load_dword v72, v139, s[52:53]
	global_load_dword v73, v139, s[52:53] offset:128
	s_add_u32 s52, s52, 20480
	s_addc_u32 s53, s53, 0
	global_load_dword v74, v139, s[52:53]
	global_load_dword v75, v139, s[52:53] offset:128
	s_add_u32 s52, s52, 4096
	s_addc_u32 s53, s53, 0
	global_load_dword v76, v139, s[52:53]
	global_load_dword v77, v139, s[52:53] offset:128
	s_add_u32 s52, s52, 4096
	s_addc_u32 s53, s53, 0
	global_load_dword v78, v139, s[52:53]
	global_load_dword v79, v139, s[52:53] offset:128
	s_add_u32 s52, s52, 4096
	s_addc_u32 s53, s53, 0
	global_load_dword v80, v139, s[52:53]
	global_load_dword v81, v139, s[52:53] offset:128
	s_add_u32 s52, s52, 20480
	s_addc_u32 s53, s53, 0
	global_load_dword v82, v139, s[52:53]
	global_load_dword v83, v139, s[52:53] offset:128
	s_add_u32 s52, s52, 4096
	s_addc_u32 s53, s53, 0
	global_load_dword v84, v139, s[52:53]
	global_load_dword v85, v139, s[52:53] offset:128
	s_add_u32 s52, s52, 4096
	s_addc_u32 s53, s53, 0
	global_load_dword v86, v139, s[52:53]
	global_load_dword v87, v139, s[52:53] offset:128
	s_add_u32 s52, s52, 4096
	s_addc_u32 s53, s53, 0
	global_load_dword v88, v139, s[52:53]
	global_load_dword v89, v139, s[52:53] offset:128
	s_add_u32 s52, s52, 20480
	s_addc_u32 s53, s53, 0
	global_load_dword v90, v139, s[52:53]
	global_load_dword v91, v139, s[52:53] offset:128
	s_add_u32 s52, s52, 4096
	s_addc_u32 s53, s53, 0
	global_load_dword v92, v139, s[52:53]
	global_load_dword v93, v139, s[52:53] offset:128
	s_add_u32 s52, s52, 4096
	s_addc_u32 s53, s53, 0
	global_load_dword v94, v139, s[52:53]
	global_load_dword v95, v139, s[52:53] offset:128
	s_add_u32 s52, s52, 4096
	s_addc_u32 s53, s53, 0
	global_load_dword v96, v139, s[52:53]
	global_load_dword v97, v139, s[52:53] offset:128
	s_add_u32 s52, s52, 20480
	s_addc_u32 s53, s53, 0
	global_load_dword v98, v139, s[52:53]
	global_load_dword v99, v139, s[52:53] offset:128
	s_add_u32 s52, s52, 4096
	s_addc_u32 s53, s53, 0
	global_load_dword v100, v139, s[52:53]
	global_load_dword v101, v139, s[52:53] offset:128
	s_add_u32 s52, s52, 4096
	s_addc_u32 s53, s53, 0
	global_load_dword v102, v139, s[52:53]
	global_load_dword v103, v139, s[52:53] offset:128
	s_add_u32 s52, s52, 4096
	s_addc_u32 s53, s53, 0
	global_load_dword v104, v139, s[52:53]
	global_load_dword v105, v139, s[52:53] offset:128
	s_add_u32 s52, s52, 20480
	s_addc_u32 s53, s53, 0
	global_load_dword v106, v139, s[52:53]
	global_load_dword v107, v139, s[52:53] offset:128
	s_add_u32 s52, s52, 4096
; template <int AI, int BI>
; DI void m2_tile(char* wsb, int layer, int m0, int n0, char* lds) {
;     ...
; #pragma unroll
;   for (int bi = 0; bi < BI; ++bi) {
;     const int n = n0 + wb * 32 * BI + bi * 32 + r;
;     const float gv = gate[n];
;     const unsigned ib = (unsigned)((m0e + wa * 32 * AI + 4 * h) * 1024 + n);
; #pragma unroll
;     for (int ai = 0; ai < AI; ++ai)
; #pragma unroll
;       for (int reg = 0; reg < 16; ++reg) {
;         const unsigned idx = ib + (unsigned)((ai * 32 + (reg & 3) + 8 * (reg >> 2)) * 1024);
;         xsu[idx] += gv * acc[ai][bi][reg];
;         if ((reg & 7) == 7) __builtin_amdgcn_sched_barrier(0);
;       }
	s_addc_u32 s53, s53, 0
	global_load_dword v108, v139, s[52:53]
	global_load_dword v109, v139, s[52:53] offset:128
	s_add_u32 s52, s52, 4096
	s_addc_u32 s53, s53, 0
	global_load_dword v110, v139, s[52:53]
	global_load_dword v111, v139, s[52:53] offset:128
	s_add_u32 s52, s52, 4096
	s_addc_u32 s53, s53, 0
	global_load_dword v112, v139, s[52:53]
	global_load_dword v113, v139, s[52:53] offset:128
	s_add_u32 s52, s52, 20480
	s_addc_u32 s53, s53, 0
	global_load_dword v114, v139, s[52:53]
	global_load_dword v115, v139, s[52:53] offset:128
	s_add_u32 s52, s52, 4096
	s_addc_u32 s53, s53, 0
	global_load_dword v116, v139, s[52:53]
	global_load_dword v117, v139, s[52:53] offset:128
	s_add_u32 s52, s52, 4096
	s_addc_u32 s53, s53, 0
	global_load_dword v118, v139, s[52:53]
	global_load_dword v119, v139, s[52:53] offset:128
	s_add_u32 s52, s52, 4096
	s_addc_u32 s53, s53, 0
	global_load_dword v120, v139, s[52:53]
	global_load_dword v121, v139, s[52:53] offset:128
	s_add_u32 s52, s52, 20480
	s_addc_u32 s53, s53, 0
	global_load_dword v122, v139, s[52:53]
	global_load_dword v123, v139, s[52:53] offset:128
	s_add_u32 s52, s52, 4096
	s_addc_u32 s53, s53, 0
	global_load_dword v124, v139, s[52:53]
	global_load_dword v134, v139, s[52:53] offset:128
	s_add_u32 s52, s52, 4096
	s_addc_u32 s53, s53, 0
	global_load_dword v135, v139, s[52:53]
	global_load_dword v136, v139, s[52:53] offset:128
	s_add_u32 s52, s52, 4096
	s_addc_u32 s53, s53, 0
	global_load_dword v137, v139, s[52:53]
	global_load_dword v138, v139, s[52:53] offset:128
	s_waitcnt vmcnt(48)
	v_fmac_f32_e32 v66, v50, v141
	v_fmac_f32_e32 v67, v18, v142
	v_fmac_f32_e32 v68, v51, v141
	v_fmac_f32_e32 v69, v19, v142
	v_fmac_f32_e32 v70, v52, v141
	v_fmac_f32_e32 v71, v20, v142
	v_fmac_f32_e32 v72, v53, v141
	v_fmac_f32_e32 v73, v21, v142
	v_fmac_f32_e32 v74, v54, v141
	v_fmac_f32_e32 v75, v22, v142
	v_fmac_f32_e32 v76, v55, v141
	v_fmac_f32_e32 v77, v23, v142
	v_fmac_f32_e32 v78, v56, v141
	v_fmac_f32_e32 v79, v24, v142
	v_fmac_f32_e32 v80, v57, v141
	v_fmac_f32_e32 v81, v25, v142
	s_waitcnt vmcnt(32)
	v_fmac_f32_e32 v82, v58, v141
	v_fmac_f32_e32 v83, v26, v142
	v_fmac_f32_e32 v84, v59, v141
	v_fmac_f32_e32 v85, v27, v142
	v_fmac_f32_e32 v86, v60, v141
	v_fmac_f32_e32 v87, v28, v142
	v_fmac_f32_e32 v88, v61, v141
	v_fmac_f32_e32 v89, v29, v142
	v_fmac_f32_e32 v90, v62, v141
	v_fmac_f32_e32 v91, v30, v142
	v_fmac_f32_e32 v92, v63, v141
	v_fmac_f32_e32 v93, v31, v142
	v_fmac_f32_e32 v94, v64, v141
	v_fmac_f32_e32 v95, v32, v142
	v_fmac_f32_e32 v96, v65, v141
	v_fmac_f32_e32 v97, v33, v142
	s_waitcnt vmcnt(16)
	v_fmac_f32_e32 v98, v34, v141
	v_fmac_f32_e32 v99, v2, v142
	v_fmac_f32_e32 v100, v35, v141
	v_fmac_f32_e32 v101, v3, v142
	v_fmac_f32_e32 v102, v36, v141
	v_fmac_f32_e32 v103, v4, v142
	v_fmac_f32_e32 v104, v37, v141
	v_fmac_f32_e32 v105, v5, v142
	v_fmac_f32_e32 v106, v38, v141
	v_fmac_f32_e32 v107, v6, v142
	v_fmac_f32_e32 v108, v39, v141
	v_fmac_f32_e32 v109, v7, v142
	v_fmac_f32_e32 v110, v40, v141
	v_fmac_f32_e32 v111, v8, v142
	v_fmac_f32_e32 v112, v41, v141
	v_fmac_f32_e32 v113, v9, v142
	s_waitcnt vmcnt(0)
; template <int AI, int BI>
; DI void m2_tile(char* wsb, int layer, int m0, int n0, char* lds) {
;     ...
; #pragma unroll
;   for (int bi = 0; bi < BI; ++bi) {
;     const int n = n0 + wb * 32 * BI + bi * 32 + r;
;     const float gv = gate[n];
;     const unsigned ib = (unsigned)((m0e + wa * 32 * AI + 4 * h) * 1024 + n);
; #pragma unroll
;     for (int ai = 0; ai < AI; ++ai)
; #pragma unroll
;       for (int reg = 0; reg < 16; ++reg) {
;         const unsigned idx = ib + (unsigned)((ai * 32 + (reg & 3) + 8 * (reg >> 2)) * 1024);
;         xsu[idx] += gv * acc[ai][bi][reg];
;         if ((reg & 7) == 7) __builtin_amdgcn_sched_barrier(0);
;       }
;   }
; }
; DI void phase_m2(const Params& p, char* wsb, int layer, int mrows, char* lds) {
;   int mt, nt;
;   for (int rnd = 0; next_tile(rnd, 128, 8, mt, nt); ++rnd) m2_tile<2, 2>(wsb, layer, mt * 128, nt * 128, lds);
;   if (mrows > TL)
;     for (int rnd = 0; next_tile(rnd, 32, 16, mt, nt); ++rnd) m2_tile<1, 1>(wsb, layer, TL + mt * 64, nt * 64, lds);
	v_fmac_f32_e32 v114, v42, v141
	v_fmac_f32_e32 v115, v10, v142
	v_fmac_f32_e32 v116, v43, v141
	v_fmac_f32_e32 v117, v11, v142
	v_fmac_f32_e32 v118, v44, v141
	v_fmac_f32_e32 v119, v12, v142
	v_fmac_f32_e32 v120, v45, v141
	v_fmac_f32_e32 v121, v13, v142
	v_fmac_f32_e32 v122, v46, v141
	v_fmac_f32_e32 v123, v14, v142
	v_fmac_f32_e32 v124, v47, v141
	v_fmac_f32_e32 v134, v15, v142
	v_fmac_f32_e32 v135, v48, v141
	v_fmac_f32_e32 v136, v16, v142
	v_fmac_f32_e32 v137, v49, v141
	v_fmac_f32_e32 v138, v17, v142
	s_mov_b64 s[52:53], s[54:55]
	global_store_dword v139, v66, s[52:53]
	global_store_dword v139, v67, s[52:53] offset:128
	s_add_u32 s52, s52, 4096
	s_addc_u32 s53, s53, 0
	global_store_dword v139, v68, s[52:53]
	global_store_dword v139, v69, s[52:53] offset:128
	s_add_u32 s52, s52, 4096
	s_addc_u32 s53, s53, 0
	global_store_dword v139, v70, s[52:53]
	global_store_dword v139, v71, s[52:53] offset:128
	s_add_u32 s52, s52, 4096
	s_addc_u32 s53, s53, 0
	global_store_dword v139, v72, s[52:53]
	global_store_dword v139, v73, s[52:53] offset:128
	s_add_u32 s52, s52, 20480
	s_addc_u32 s53, s53, 0
	global_store_dword v139, v74, s[52:53]
	global_store_dword v139, v75, s[52:53] offset:128
	s_add_u32 s52, s52, 4096
	s_addc_u32 s53, s53, 0
	global_store_dword v139, v76, s[52:53]
	global_store_dword v139, v77, s[52:53] offset:128
	s_add_u32 s52, s52, 4096
	s_addc_u32 s53, s53, 0
	global_store_dword v139, v78, s[52:53]
	global_store_dword v139, v79, s[52:53] offset:128
	s_add_u32 s52, s52, 4096
	s_addc_u32 s53, s53, 0
	global_store_dword v139, v80, s[52:53]
	global_store_dword v139, v81, s[52:53] offset:128
	s_add_u32 s52, s52, 20480
	s_addc_u32 s53, s53, 0
	global_store_dword v139, v82, s[52:53]
	global_store_dword v139, v83, s[52:53] offset:128
	s_add_u32 s52, s52, 4096
	s_addc_u32 s53, s53, 0
	global_store_dword v139, v84, s[52:53]
	global_store_dword v139, v85, s[52:53] offset:128
	s_add_u32 s52, s52, 4096
	s_addc_u32 s53, s53, 0
	global_store_dword v139, v86, s[52:53]
	global_store_dword v139, v87, s[52:53] offset:128
	s_add_u32 s52, s52, 4096
	s_addc_u32 s53, s53, 0
	global_store_dword v139, v88, s[52:53]
	global_store_dword v139, v89, s[52:53] offset:128
	s_add_u32 s52, s52, 20480
	s_addc_u32 s53, s53, 0
	global_store_dword v139, v90, s[52:53]
	global_store_dword v139, v91, s[52:53] offset:128
	s_add_u32 s52, s52, 4096
	s_addc_u32 s53, s53, 0
	global_store_dword v139, v92, s[52:53]
	global_store_dword v139, v93, s[52:53] offset:128
	s_add_u32 s52, s52, 4096
	s_addc_u32 s53, s53, 0
	global_store_dword v139, v94, s[52:53]
	global_store_dword v139, v95, s[52:53] offset:128
	s_add_u32 s52, s52, 4096
	s_addc_u32 s53, s53, 0
	global_store_dword v139, v96, s[52:53]
	global_store_dword v139, v97, s[52:53] offset:128
	s_add_u32 s52, s52, 20480
	s_addc_u32 s53, s53, 0
	global_store_dword v139, v98, s[52:53]
	global_store_dword v139, v99, s[52:53] offset:128
	s_add_u32 s52, s52, 4096
	s_addc_u32 s53, s53, 0
	global_store_dword v139, v100, s[52:53]
	global_store_dword v139, v101, s[52:53] offset:128
	s_add_u32 s52, s52, 4096
	s_addc_u32 s53, s53, 0
	global_store_dword v139, v102, s[52:53]
	global_store_dword v139, v103, s[52:53] offset:128
	s_add_u32 s52, s52, 4096
	s_addc_u32 s53, s53, 0
	global_store_dword v139, v104, s[52:53]
	global_store_dword v139, v105, s[52:53] offset:128
	s_add_u32 s52, s52, 20480
	s_addc_u32 s53, s53, 0
	global_store_dword v139, v106, s[52:53]
	global_store_dword v139, v107, s[52:53] offset:128
	s_add_u32 s52, s52, 4096
	s_addc_u32 s53, s53, 0
	global_store_dword v139, v108, s[52:53]
	global_store_dword v139, v109, s[52:53] offset:128
	s_add_u32 s52, s52, 4096
	s_addc_u32 s53, s53, 0
	global_store_dword v139, v110, s[52:53]
	global_store_dword v139, v111, s[52:53] offset:128
	s_add_u32 s52, s52, 4096
	s_addc_u32 s53, s53, 0
	global_store_dword v139, v112, s[52:53]
	global_store_dword v139, v113, s[52:53] offset:128
	s_add_u32 s52, s52, 20480
	s_addc_u32 s53, s53, 0
	global_store_dword v139, v114, s[52:53]
	global_store_dword v139, v115, s[52:53] offset:128
	s_add_u32 s52, s52, 4096
	s_addc_u32 s53, s53, 0
	global_store_dword v139, v116, s[52:53]
	global_store_dword v139, v117, s[52:53] offset:128
	s_add_u32 s52, s52, 4096
	s_addc_u32 s53, s53, 0
	global_store_dword v139, v118, s[52:53]
	global_store_dword v139, v119, s[52:53] offset:128
	s_add_u32 s52, s52, 4096
	s_addc_u32 s53, s53, 0
	global_store_dword v139, v120, s[52:53]
	global_store_dword v139, v121, s[52:53] offset:128
	s_add_u32 s52, s52, 20480
	s_addc_u32 s53, s53, 0
	global_store_dword v139, v122, s[52:53]
	global_store_dword v139, v123, s[52:53] offset:128
	s_add_u32 s52, s52, 4096
	s_addc_u32 s53, s53, 0
	global_store_dword v139, v124, s[52:53]
	global_store_dword v139, v134, s[52:53] offset:128
	s_add_u32 s52, s52, 4096
	s_addc_u32 s53, s53, 0
	global_store_dword v139, v135, s[52:53]
	global_store_dword v139, v136, s[52:53] offset:128
	s_add_u32 s52, s52, 4096
	s_addc_u32 s53, s53, 0
	global_store_dword v139, v137, s[52:53]
	global_store_dword v139, v138, s[52:53] offset:128
	s_add_i32 s34, s34, s57
	s_add_i32 s29, s29, s64
	s_cmpk_lt_u32 s34, 0x400
	s_cbranch_scc1 .LBB0_1099
	v_readlane_b32 s28, v243, 45
	v_readlane_b32 s34, v243, 47
	v_readlane_b32 s29, v243, 46
	v_readlane_b32 s35, v243, 48

; #define TIDX opaque_tid()
; template <int AI, int BI>
; DI void gemm_stage(const u16* __restrict__ A, int lda, const u16* __restrict__ B, int ldb, char* buf, int tid) {
; #pragma unroll
;   for (int i = 0; i < 2 * AI; ++i) {
;     const int S = tid + NTHR * i, row = S >> 3, c = (S & 7) ^ ((row >> 1) & 7);
;     __builtin_amdgcn_global_load_lds((const unsigned*)(A + (size_t)row * lda + c * 8), (__attribute__((address_space(3))) unsigned*)(buf + S * 16), 16, 0, 0);
;   }
; #pragma unroll
;   for (int i = 0; i < 2 * BI; ++i) {
;     const int S = tid + NTHR * i, row = S >> 3, c = (S & 7) ^ ((row >> 1) & 7);
;     __builtin_amdgcn_global_load_lds((const unsigned*)(B + (size_t)row * ldb + c * 8), (__attribute__((address_space(3))) unsigned*)(buf + 16384 + S * 16), 16, 0, 0);
;   }
; }
; template <int AI, int BI>
; DI void gemm_tile(const u16* __restrict__ A, int lda, const u16* __restrict__ B, int ldb, int nk, bool swap,
;                   f32x16 (&acc)[AI][BI], char* lds) {
;   const int tid = TIDX, lane = tid & 63, wid = tid >> 6;
;   gemm_stage<AI, BI>(A, lda, B, ldb, lds, tid);
;   asm volatile("s_waitcnt vmcnt(0)" ::: "memory");
;   __syncthreads();
.LBB0_1263:
	s_bfe_u32 s6, s40, 0x40006
	s_mul_i32 s6, s6, 0x580000
	v_readlane_b32 s7, v243, 15
	s_add_i32 s13, s7, s6
	s_lshr_b32 s6, s40, 3
	s_and_b32 s6, s6, 0x78
	s_and_b32 s7, s40, 7
	v_mov_b32_e32 v82, v178
	v_mov_b32_e32 v83, v178
	v_mov_b32_e32 v6, v178
	s_or_b32 s12, s6, s7
	s_lshl_b32 s6, s40, 4
	s_and_b32 s14, s6, 0x380
	v_lshrrev_b32_e32 v7, 4, v6
	s_mul_i32 s6, s12, 0xb0000
	v_xor_b32_e32 v0, v7, v6
	s_add_u32 s6, s16, s6
	v_lshlrev_b32_e32 v0, 4, v0
	s_addc_u32 s7, s17, 0
	s_mul_i32 s15, s14, 0x1600
	v_and_b32_e32 v0, 0x70, v0
	s_add_u32 s46, s18, s15
	v_lshl_add_u64 v[2:3], s[6:7], 0, v[0:1]
	v_ashrrev_i32_e32 v8, 3, v6
	s_movk_i32 s15, 0x1600
	v_mad_i64_i32 v[4:5], s[6:7], v8, s15, v[2:3]
	v_lshlrev_b32_e32 v85, 4, v6
	v_add_u32_e32 v9, 0x100, v6
	v_readfirstlane_b32 s6, v85
	s_mov_b32 m0, s6
	v_ashrrev_i32_e32 v10, 3, v9
	global_load_lds_dwordx4 v[4:5], off
	v_mad_i64_i32 v[4:5], s[6:7], v10, s15, v[2:3]
	v_lshlrev_b32_e32 v86, 4, v9
	v_add_u32_e32 v9, 0x200, v6
	v_readfirstlane_b32 s6, v86
	s_mov_b32 m0, s6
	v_ashrrev_i32_e32 v11, 3, v9
	global_load_lds_dwordx4 v[4:5], off
	v_mad_i64_i32 v[4:5], s[6:7], v11, s15, v[2:3]
	v_lshlrev_b32_e32 v87, 4, v9
	s_addc_u32 s47, s28, 0
	v_readfirstlane_b32 s6, v87
	s_mov_b32 m0, s6
	s_nop 0
	global_load_lds_dwordx4 v[4:5], off
	v_add_u32_e32 v4, 0x300, v6
	v_ashrrev_i32_e32 v9, 3, v4
	v_mad_i64_i32 v[2:3], s[6:7], v9, s15, v[2:3]
	v_lshlrev_b32_e32 v89, 4, v4
	s_nop 0
	v_readfirstlane_b32 s6, v89
	s_mov_b32 m0, s6
	s_nop 0
	global_load_lds_dwordx4 v[2:3], off
	v_lshl_add_u64 v[2:3], s[46:47], 0, v[0:1]
	v_mad_i64_i32 v[4:5], s[6:7], v8, s15, v[2:3]
	v_add_u32_e32 v0, 0x4000, v85
	s_nop 0
	v_readfirstlane_b32 s6, v0
	s_mov_b32 m0, s6
	v_add_u32_e32 v0, 0x4000, v86
	global_load_lds_dwordx4 v[4:5], off
	v_mad_i64_i32 v[4:5], s[6:7], v10, s15, v[2:3]
	v_readfirstlane_b32 s6, v0
	s_mov_b32 m0, s6
	v_add_u32_e32 v0, 0x4000, v87
	global_load_lds_dwordx4 v[4:5], off
	v_mad_i64_i32 v[4:5], s[6:7], v11, s15, v[2:3]
	v_readfirstlane_b32 s6, v0
	s_mov_b32 m0, s6
	v_mad_i64_i32 v[2:3], s[6:7], v9, s15, v[2:3]
	v_add_u32_e32 v0, 0x4000, v89
	global_load_lds_dwordx4 v[4:5], off
	v_readfirstlane_b32 s6, v0
	s_mov_b32 m0, s6
	v_and_b32_e32 v0, 31, v6
	global_load_lds_dwordx4 v[2:3], off
	v_lshrrev_b32_e32 v4, 1, v6
	s_mov_b32 s6, 0x1ffffc0
	v_and_or_b32 v0, v4, s6, v0
	v_lshrrev_b32_e32 v2, 5, v6
	v_bfe_u32 v5, v6, 1, 3
	v_lshlrev_b32_e32 v91, 7, v0
	v_lshlrev_b32_e32 v0, 7, v6
	v_bfe_u32 v3, v6, 5, 1
	v_and_b32_e32 v92, 0x2f80, v0
	v_bitop3_b32 v0, v2, v5, 1 bitop3:0x6c
	v_lshlrev_b32_e32 v90, 4, v0
	v_bitop3_b32 v0, v3, v5, 2 bitop3:0x36
	v_lshlrev_b32_e32 v88, 4, v0
	v_bitop3_b32 v0, v3, v5, 4 bitop3:0x36
	v_lshlrev_b32_e32 v84, 4, v0
	v_bitop3_b32 v0, v3, v5, 6 bitop3:0x36
	v_mad_i64_i32 v[2:3], s[6:7], v8, s15, 0
	v_bitop3_b32 v4, v7, 7, v6 bitop3:0x48
	v_lshlrev_b32_e32 v12, 4, v4
	s_add_u32 s6, s36, s13
	v_mad_i64_i32 v[4:5], s[46:47], v10, s15, 0
	v_mad_i64_i32 v[6:7], s[46:47], v11, s15, 0
	v_mad_i64_i32 v[8:9], s[46:47], v9, s15, 0
	v_or_b32_e32 v2, v2, v12
	s_addc_u32 s7, s37, 0
	v_or_b32_e32 v4, v4, v12
	v_or_b32_e32 v6, v6, v12
	v_or_b32_e32 v8, v8, v12
	s_bfe_u32 s13, s40, 0x30003
	v_lshl_add_u64 v[66:67], s[6:7], 0, v[2:3]
	v_lshl_add_u64 v[68:69], s[6:7], 0, v[4:5]
	v_lshl_add_u64 v[70:71], s[6:7], 0, v[6:7]
	v_lshl_add_u64 v[72:73], s[6:7], 0, v[8:9]
	v_mad_u64_u32 v[2:3], s[6:7], s13, v193, v[2:3]
	v_lshl_add_u64 v[74:75], s[10:11], 0, v[2:3]
	v_mad_u64_u32 v[2:3], s[6:7], s13, v193, v[4:5]
	v_lshl_add_u64 v[76:77], s[10:11], 0, v[2:3]
	v_mad_u64_u32 v[2:3], s[6:7], s13, v193, v[6:7]
	s_waitcnt vmcnt(0)
	v_lshl_add_u64 v[78:79], s[10:11], 0, v[2:3]
	v_mad_u64_u32 v[2:3], s[6:7], s13, v193, v[8:9]
	v_lshl_add_u64 v[80:81], s[10:11], 0, v[2:3]
	v_mov_b32_e32 v2, 0
	v_lshlrev_b32_e32 v0, 4, v0
	s_mov_b64 s[6:7], 0
	s_mov_b32 s13, 0x8000
	v_mov_b32_e32 v3, v2
	v_mov_b32_e32 v4, v2
	v_mov_b32_e32 v5, v2
	v_mov_b32_e32 v6, v2
	v_mov_b32_e32 v7, v2
	v_mov_b32_e32 v8, v2
	v_mov_b32_e32 v9, v2
	v_mov_b32_e32 v10, v2
	v_mov_b32_e32 v11, v2
	v_mov_b32_e32 v12, v2
	v_mov_b32_e32 v13, v2
	v_mov_b32_e32 v14, v2
	v_mov_b32_e32 v15, v2
	v_mov_b32_e32 v16, v2
	v_mov_b32_e32 v17, v2
	v_mov_b32_e32 v34, v2
	v_mov_b32_e32 v35, v2
	v_mov_b32_e32 v36, v2
	v_mov_b32_e32 v37, v2
	v_mov_b32_e32 v38, v2
	v_mov_b32_e32 v39, v2
	v_mov_b32_e32 v40, v2
	v_mov_b32_e32 v41, v2
	v_mov_b32_e32 v42, v2
	v_mov_b32_e32 v43, v2
	v_mov_b32_e32 v44, v2
	v_mov_b32_e32 v45, v2
	v_mov_b32_e32 v46, v2
	v_mov_b32_e32 v47, v2
	v_mov_b32_e32 v48, v2
	v_mov_b32_e32 v49, v2
	v_mov_b32_e32 v18, v2
	v_mov_b32_e32 v19, v2
	v_mov_b32_e32 v20, v2
	v_mov_b32_e32 v21, v2
	v_mov_b32_e32 v22, v2
	v_mov_b32_e32 v23, v2
	v_mov_b32_e32 v24, v2
	v_mov_b32_e32 v25, v2
	v_mov_b32_e32 v26, v2
	v_mov_b32_e32 v27, v2
	v_mov_b32_e32 v28, v2
	v_mov_b32_e32 v29, v2
	v_mov_b32_e32 v30, v2
	v_mov_b32_e32 v31, v2
	v_mov_b32_e32 v32, v2
	v_mov_b32_e32 v33, v2
	v_mov_b32_e32 v50, v2
	v_mov_b32_e32 v51, v2
	v_mov_b32_e32 v52, v2
	v_mov_b32_e32 v53, v2
	v_mov_b32_e32 v54, v2
	v_mov_b32_e32 v55, v2
	v_mov_b32_e32 v56, v2
	v_mov_b32_e32 v57, v2
	v_mov_b32_e32 v58, v2
	v_mov_b32_e32 v59, v2
	v_mov_b32_e32 v60, v2
	v_mov_b32_e32 v61, v2
	v_mov_b32_e32 v62, v2
	v_mov_b32_e32 v63, v2
	v_mov_b32_e32 v64, v2
	v_mov_b32_e32 v65, v2
	s_waitcnt vmcnt(0) lgkmcnt(0)
	s_barrier
